# first K-iteration of every GEMM tile peeled with C=0 on the first MFMA of each accumulator: the 128 v_mov accumulator zeroing per tile is gone; on top of scalar-base loads
# speedup vs baseline: 1.0187x; 1.0071x over previous
; #define PG8_STAGE(bufoff, gbase, voff) do { _Pragma("unroll") for (int _i = 0; _i < 2; ++_i) \
;         __builtin_amdgcn_global_load_lds((const unsigned*)((const char*)(gbase) + (voff)[_i]), (PG8_LAS unsigned*)(lds + (bufoff) + ldsw + _i * 8192), 16, 0, 0); } while (0)
; #define PG8_LDA(dst, b, h) do { _Pragma("unroll") for (int m = 0; m < 4; ++m) _Pragma("unroll") for (int k = 0; k < 2; ++k) dst[m][k] = *(const PG8_LAS bf16x8*)(lds + PG8_SA(b, h) + aoff + m * 2048 + k * 1024); } while (0)
; #define PG8_LDB(dst, b, h) do { _Pragma("unroll") for (int n = 0; n < 2; ++n) _Pragma("unroll") for (int k = 0; k < 2; ++k) dst[n][k] = *(const PG8_LAS bf16x8*)(lds + PG8_SB(b, h) + boff + n * 2048 + k * 1024); } while (0)
; #define PG8_MMA(ai, bj, At, Bt) do { __builtin_amdgcn_s_setprio(1); _Pragma("unroll") for (int m = 0; m < 4; ++m) _Pragma("unroll") for (int n = 0; n < 2; ++n) _Pragma("unroll") for (int k = 0; k < 2; ++k) \
;         acc[ai][bj][m][n] = __builtin_amdgcn_mfma_f32_16x16x32_bf16(Bt[n][k], At[m][k], acc[ai][bj][m][n], 0, 0, 0); __builtin_amdgcn_s_setprio(0); } while (0)
; #define PG8_WAIT_V(n) asm volatile("s_waitcnt vmcnt(" #n ")" ::: "memory")
; #define PG8_WAIT_L(n) asm volatile("s_waitcnt lgkmcnt(" #n ")" ::: "memory")
; #define PG8_BAR __builtin_amdgcn_s_barrier()
; #define PG8_SCHED __builtin_amdgcn_sched_barrier(0)
; template <class Epi, class Sched, bool ALIGN_EPI = false, bool SP2 = false>
; __device__ __forceinline__ void gemm_phase(PG8_LAS unsigned char* lds, const Gemm g, const Sched& S, const Epi& E, int tid_in) {
;     ...
;     f32x4 acc[2][2][4][2];
; #pragma unroll
;     for (int a = 0; a < 2; ++a)
; #pragma unroll
;         for (int b = 0; b < 2; ++b)
; #pragma unroll
;             for (int m = 0; m < 4; ++m)
; #pragma unroll
;                 for (int n = 0; n < 2; ++n) acc[a][b][m][n] = (f32x4){0.f, 0.f, 0.f, 0.f};
;     ...
;             PG8_LDB(B0, 0, 0); PG8_LDB(B1, 0, 1); PG8_SCHED; PG8_LDA(At, 0, 0); PG8_STAGE(PG8_SA(1, 1), a1 + hstep, voffA);
;             PG8_WAIT_V(8); PG8_WAIT_L(0); PG8_BAR; PG8_MMA(0, 0, At, B0); PG8_MMA(0, 1, At, B1); PG8_BAR; PG8_SCHED;
;             PG8_LDA(At, 0, 1); PG8_STAGE(PG8_SB(0, 0), b2, voffB); PG8_STAGE(PG8_SB(0, 1), b2 + hstepB, voffB); PG8_STAGE(PG8_SA(0, 0), a2, voffA);
.LBB0_79:
	s_ashr_i32 s41, s40, 31
	s_lshl_b64 s[26:27], s[40:41], 20
	s_add_u32 s42, s28, s26
	s_addc_u32 s43, s29, s27
	s_and_b64 s[26:27], s[6:7], exec
	s_cselect_b32 s41, s43, s49
	s_cselect_b32 s70, s42, s48
	s_ashr_i32 s39, s38, 31
	s_lshl_b64 s[26:27], s[38:39], 20
	s_add_u32 s44, s36, s26
	s_addc_u32 s45, s37, s27
	s_and_b64 s[26:27], s[6:7], exec
	s_cselect_b32 s39, s45, s51
	s_cselect_b32 s71, s44, s50
	s_add_u32 s48, s48, 0x80080
	s_addc_u32 s49, s49, 0
	s_add_u32 s74, s50, 0x100
	s_addc_u32 s75, s51, 0
	s_mov_b32 s76, -2
	s_cmp_eq_u32 s98, 1
	s_cbranch_scc0 .Lkb_skip_0
	s_mov_b32 s98, 0
	s_barrier
.Lkb_skip_0:
	ds_read_b128 v[156:159], v150
	ds_read_b128 v[160:163], v150 offset:1024
	ds_read_b128 v[164:167], v150 offset:2048
	ds_read_b128 v[168:171], v150 offset:3072
	ds_read_b128 v[172:175], v151
	ds_read_b128 v[176:179], v151 offset:1024
	ds_read_b128 v[180:183], v151 offset:2048
	ds_read_b128 v[184:187], v151 offset:3072
	s_add_u32 s26, s48, 0xfff80080
	s_addc_u32 s27, s49, -1
	s_cmp_eq_u32 s76, 28
	s_cselect_b32 s53, s41, s27
	s_cselect_b32 s52, s70, s26
	s_cselect_b32 s51, s39, s75
	s_cselect_b32 s50, s71, s74
	s_add_i32 m0, s47, 0xc000
	ds_read_b128 v[188:191], v152
	ds_read_b128 v[192:195], v152 offset:1024
	ds_read_b128 v[196:199], v152 offset:2048
	ds_read_b128 v[200:203], v152 offset:3072
	ds_read_b128 v[212:215], v152 offset:4096
	ds_read_b128 v[216:219], v152 offset:5120
	ds_read_b128 v[220:223], v152 offset:6144
	ds_read_b128 v[224:227], v152 offset:7168
	global_load_lds_dwordx4 v138, s[48:49]
	s_add_i32 m0, s47, 0xe000
	s_nop 0
	global_load_lds_dwordx4 v140, s[48:49]
	s_waitcnt vmcnt(8)
	s_waitcnt lgkmcnt(0)
	s_barrier
	s_setprio 1
	s_waitcnt lgkmcnt(0)
	v_mfma_f32_16x16x32_bf16 v[124:127], v[156:159], v[188:191], 0
	v_mfma_f32_16x16x32_bf16 v[120:123], v[164:167], v[188:191], 0
	v_mfma_f32_16x16x32_bf16 v[108:111], v[156:159], v[196:199], 0
	v_mfma_f32_16x16x32_bf16 v[104:107], v[164:167], v[196:199], 0
	v_mfma_f32_16x16x32_bf16 v[92:95], v[156:159], v[212:215], 0
	v_mfma_f32_16x16x32_bf16 v[88:91], v[164:167], v[212:215], 0
	v_mfma_f32_16x16x32_bf16 v[76:79], v[156:159], v[220:223], 0
	v_mfma_f32_16x16x32_bf16 v[72:75], v[164:167], v[220:223], 0
	v_mfma_f32_16x16x32_bf16 v[124:127], v[160:163], v[192:195], v[124:127]
	v_mfma_f32_16x16x32_bf16 v[120:123], v[168:171], v[192:195], v[120:123]
	v_mfma_f32_16x16x32_bf16 v[108:111], v[160:163], v[200:203], v[108:111]
	v_mfma_f32_16x16x32_bf16 v[104:107], v[168:171], v[200:203], v[104:107]
	v_mfma_f32_16x16x32_bf16 v[92:95], v[160:163], v[216:219], v[92:95]
	v_mfma_f32_16x16x32_bf16 v[88:91], v[168:171], v[216:219], v[88:91]
	v_mfma_f32_16x16x32_bf16 v[76:79], v[160:163], v[224:227], v[76:79]
	v_mfma_f32_16x16x32_bf16 v[72:75], v[168:171], v[224:227], v[72:75]
	s_setprio 0
	s_setprio 1
	v_mfma_f32_16x16x32_bf16 v[116:119], v[172:175], v[188:191], 0
	v_mfma_f32_16x16x32_bf16 v[112:115], v[180:183], v[188:191], 0
	v_mfma_f32_16x16x32_bf16 v[100:103], v[172:175], v[196:199], 0
	v_mfma_f32_16x16x32_bf16 v[96:99], v[180:183], v[196:199], 0
	v_mfma_f32_16x16x32_bf16 v[84:87], v[172:175], v[212:215], 0
	v_mfma_f32_16x16x32_bf16 v[80:83], v[180:183], v[212:215], 0
	v_mfma_f32_16x16x32_bf16 v[68:71], v[172:175], v[220:223], 0
	v_mfma_f32_16x16x32_bf16 v[64:67], v[180:183], v[220:223], 0
	v_mfma_f32_16x16x32_bf16 v[116:119], v[176:179], v[192:195], v[116:119]
	v_mfma_f32_16x16x32_bf16 v[112:115], v[184:187], v[192:195], v[112:115]
	v_mfma_f32_16x16x32_bf16 v[100:103], v[176:179], v[200:203], v[100:103]
	v_mfma_f32_16x16x32_bf16 v[96:99], v[184:187], v[200:203], v[96:99]
	v_mfma_f32_16x16x32_bf16 v[84:87], v[176:179], v[216:219], v[84:87]
	v_mfma_f32_16x16x32_bf16 v[80:83], v[184:187], v[216:219], v[80:83]
	v_mfma_f32_16x16x32_bf16 v[68:71], v[176:179], v[224:227], v[68:71]
	v_mfma_f32_16x16x32_bf16 v[64:67], v[184:187], v[224:227], v[64:67]
	s_setprio 0
	s_barrier
	s_add_i32 s26, s67, s54
	s_mov_b32 m0, s26
	ds_read_b128 v[188:191], v152 offset:16384
	ds_read_b128 v[192:195], v152 offset:17408
	ds_read_b128 v[196:199], v152 offset:18432
	ds_read_b128 v[200:203], v152 offset:19456
	ds_read_b128 v[212:215], v152 offset:20480
	ds_read_b128 v[216:219], v152 offset:21504
	ds_read_b128 v[220:223], v152 offset:22528
	ds_read_b128 v[224:227], v152 offset:23552
	global_load_lds_dwordx4 v132, s[50:51]
	s_add_i32 m0, s26, 0x2000
	s_add_u32 s26, s50, 0x20000
	s_addc_u32 s27, s51, 0
	s_add_i32 s33, s68, s54
	global_load_lds_dwordx4 v128, s[50:51]
	s_mov_b32 m0, s33
	s_nop 0
	global_load_lds_dwordx4 v132, s[26:27]
	s_add_i32 m0, s33, 0x2000
	s_nop 0
	global_load_lds_dwordx4 v128, s[26:27]
	s_mov_b32 m0, s47
	s_nop 0
	global_load_lds_dwordx4 v134, s[52:53]
	s_mov_b32 m0, s56
	s_nop 0
	global_load_lds_dwordx4 v130, s[52:53]
	s_waitcnt vmcnt(8)
	s_waitcnt lgkmcnt(0)
	s_barrier
; #define PG8_STAGE(bufoff, gbase, voff) do { _Pragma("unroll") for (int _i = 0; _i < 2; ++_i) \
;         __builtin_amdgcn_global_load_lds((const unsigned*)((const char*)(gbase) + (voff)[_i]), (PG8_LAS unsigned*)(lds + (bufoff) + ldsw + _i * 8192), 16, 0, 0); } while (0)
; #define PG8_LDA(dst, b, h) do { _Pragma("unroll") for (int m = 0; m < 4; ++m) _Pragma("unroll") for (int k = 0; k < 2; ++k) dst[m][k] = *(const PG8_LAS bf16x8*)(lds + PG8_SA(b, h) + aoff + m * 2048 + k * 1024); } while (0)
; #define PG8_LDB(dst, b, h) do { _Pragma("unroll") for (int n = 0; n < 2; ++n) _Pragma("unroll") for (int k = 0; k < 2; ++k) dst[n][k] = *(const PG8_LAS bf16x8*)(lds + PG8_SB(b, h) + boff + n * 2048 + k * 1024); } while (0)
; #define PG8_MMA(ai, bj, At, Bt) do { __builtin_amdgcn_s_setprio(1); _Pragma("unroll") for (int m = 0; m < 4; ++m) _Pragma("unroll") for (int n = 0; n < 2; ++n) _Pragma("unroll") for (int k = 0; k < 2; ++k) \
;         acc[ai][bj][m][n] = __builtin_amdgcn_mfma_f32_16x16x32_bf16(Bt[n][k], At[m][k], acc[ai][bj][m][n], 0, 0, 0); __builtin_amdgcn_s_setprio(0); } while (0)
; #define PG8_WAIT_V(n) asm volatile("s_waitcnt vmcnt(" #n ")" ::: "memory")
; #define PG8_WAIT_L(n) asm volatile("s_waitcnt lgkmcnt(" #n ")" ::: "memory")
; #define PG8_BAR __builtin_amdgcn_s_barrier()
; #define PG8_SCHED __builtin_amdgcn_sched_barrier(0)
; template <class Epi, class Sched, bool ALIGN_EPI = false, bool SP2 = false>
; __device__ __forceinline__ void gemm_phase(PG8_LAS unsigned char* lds, const Gemm g, const Sched& S, const Epi& E, int tid_in) {
;     ...
;             PG8_WAIT_V(8); PG8_WAIT_L(0); PG8_BAR; PG8_MMA(1, 0, At, B0); PG8_MMA(1, 1, At, B1); PG8_BAR; PG8_SCHED;
;             PG8_LDB(B0, 1, 0); PG8_LDB(B1, 1, 1); PG8_SCHED; PG8_LDA(At, 1, 0); PG8_STAGE(PG8_SA(0, 1), a2 + hstep, voffA);
;             PG8_WAIT_V(8); PG8_WAIT_L(0); PG8_BAR; PG8_MMA(0, 0, At, B0); PG8_MMA(0, 1, At, B1); PG8_BAR; PG8_SCHED;
	s_setprio 1
	s_waitcnt lgkmcnt(0)
	v_mfma_f32_16x16x32_bf16 v[60:63], v[156:159], v[188:191], 0
	v_mfma_f32_16x16x32_bf16 v[56:59], v[164:167], v[188:191], 0
	v_mfma_f32_16x16x32_bf16 v[44:47], v[156:159], v[196:199], 0
	v_mfma_f32_16x16x32_bf16 v[40:43], v[164:167], v[196:199], 0
	v_mfma_f32_16x16x32_bf16 v[28:31], v[156:159], v[212:215], 0
	v_mfma_f32_16x16x32_bf16 v[24:27], v[164:167], v[212:215], 0
	v_mfma_f32_16x16x32_bf16 v[12:15], v[156:159], v[220:223], 0
	v_mfma_f32_16x16x32_bf16 v[8:11], v[164:167], v[220:223], 0
	v_mfma_f32_16x16x32_bf16 v[60:63], v[160:163], v[192:195], v[60:63]
	v_mfma_f32_16x16x32_bf16 v[56:59], v[168:171], v[192:195], v[56:59]
	v_mfma_f32_16x16x32_bf16 v[44:47], v[160:163], v[200:203], v[44:47]
	v_mfma_f32_16x16x32_bf16 v[40:43], v[168:171], v[200:203], v[40:43]
	v_mfma_f32_16x16x32_bf16 v[28:31], v[160:163], v[216:219], v[28:31]
	v_mfma_f32_16x16x32_bf16 v[24:27], v[168:171], v[216:219], v[24:27]
	v_mfma_f32_16x16x32_bf16 v[12:15], v[160:163], v[224:227], v[12:15]
	v_mfma_f32_16x16x32_bf16 v[8:11], v[168:171], v[224:227], v[8:11]
	s_setprio 0
	s_setprio 1
	v_mfma_f32_16x16x32_bf16 v[52:55], v[172:175], v[188:191], 0
	v_mfma_f32_16x16x32_bf16 v[48:51], v[180:183], v[188:191], 0
	v_mfma_f32_16x16x32_bf16 v[36:39], v[172:175], v[196:199], 0
	v_mfma_f32_16x16x32_bf16 v[32:35], v[180:183], v[196:199], 0
	v_mfma_f32_16x16x32_bf16 v[20:23], v[172:175], v[212:215], 0
	v_mfma_f32_16x16x32_bf16 v[16:19], v[180:183], v[212:215], 0
	v_mfma_f32_16x16x32_bf16 v[4:7], v[172:175], v[220:223], 0
	v_mfma_f32_16x16x32_bf16 v[0:3], v[180:183], v[220:223], 0
	v_mfma_f32_16x16x32_bf16 v[52:55], v[176:179], v[192:195], v[52:55]
	v_mfma_f32_16x16x32_bf16 v[48:51], v[184:187], v[192:195], v[48:51]
	v_mfma_f32_16x16x32_bf16 v[36:39], v[176:179], v[200:203], v[36:39]
	v_mfma_f32_16x16x32_bf16 v[32:35], v[184:187], v[200:203], v[32:35]
	v_mfma_f32_16x16x32_bf16 v[20:23], v[176:179], v[216:219], v[20:23]
	v_mfma_f32_16x16x32_bf16 v[16:19], v[184:187], v[216:219], v[16:19]
	v_mfma_f32_16x16x32_bf16 v[4:7], v[176:179], v[224:227], v[4:7]
	v_mfma_f32_16x16x32_bf16 v[0:3], v[184:187], v[224:227], v[0:3]
	s_setprio 0
	s_barrier
	s_add_i32 s33, 0, 0x18000
	v_add_u32_e32 v155, s33, v146
	s_add_i32 s77, 0, 0x1c000
	ds_read_b128 v[156:159], v155
	ds_read_b128 v[160:163], v155 offset:1024
	ds_read_b128 v[164:167], v155 offset:2048
	ds_read_b128 v[168:171], v155 offset:3072
	v_add_u32_e32 v155, s77, v146
	ds_read_b128 v[172:175], v155
	ds_read_b128 v[176:179], v155 offset:1024
	ds_read_b128 v[180:183], v155 offset:2048
	ds_read_b128 v[184:187], v155 offset:3072
	s_add_u32 s26, s52, 0x80000
	s_addc_u32 s27, s53, 0
	s_mov_b32 m0, s57
	ds_read_b128 v[188:191], v152 offset:32768
	ds_read_b128 v[192:195], v152 offset:33792
	ds_read_b128 v[196:199], v152 offset:34816
	ds_read_b128 v[200:203], v152 offset:35840
	ds_read_b128 v[212:215], v152 offset:36864
	ds_read_b128 v[216:219], v152 offset:37888
	ds_read_b128 v[220:223], v152 offset:38912
	ds_read_b128 v[224:227], v152 offset:39936
	global_load_lds_dwordx4 v134, s[26:27]
	s_mov_b32 m0, s58
	s_nop 0
	global_load_lds_dwordx4 v130, s[26:27]
	s_waitcnt vmcnt(8)
	s_waitcnt lgkmcnt(0)
	s_barrier
	s_setprio 1
	s_waitcnt lgkmcnt(0)
	v_mfma_f32_16x16x32_bf16 v[124:127], v[156:159], v[188:191], v[124:127]
	v_mfma_f32_16x16x32_bf16 v[120:123], v[164:167], v[188:191], v[120:123]
	v_mfma_f32_16x16x32_bf16 v[108:111], v[156:159], v[196:199], v[108:111]
	v_mfma_f32_16x16x32_bf16 v[104:107], v[164:167], v[196:199], v[104:107]
	v_mfma_f32_16x16x32_bf16 v[92:95], v[156:159], v[212:215], v[92:95]
	v_mfma_f32_16x16x32_bf16 v[88:91], v[164:167], v[212:215], v[88:91]
	v_mfma_f32_16x16x32_bf16 v[76:79], v[156:159], v[220:223], v[76:79]
	v_mfma_f32_16x16x32_bf16 v[72:75], v[164:167], v[220:223], v[72:75]
	v_mfma_f32_16x16x32_bf16 v[124:127], v[160:163], v[192:195], v[124:127]
	v_mfma_f32_16x16x32_bf16 v[120:123], v[168:171], v[192:195], v[120:123]
	v_mfma_f32_16x16x32_bf16 v[108:111], v[160:163], v[200:203], v[108:111]
	v_mfma_f32_16x16x32_bf16 v[104:107], v[168:171], v[200:203], v[104:107]
	v_mfma_f32_16x16x32_bf16 v[92:95], v[160:163], v[216:219], v[92:95]
	v_mfma_f32_16x16x32_bf16 v[88:91], v[168:171], v[216:219], v[88:91]
	v_mfma_f32_16x16x32_bf16 v[76:79], v[160:163], v[224:227], v[76:79]
	v_mfma_f32_16x16x32_bf16 v[72:75], v[168:171], v[224:227], v[72:75]
	s_setprio 0
	s_setprio 1
	v_mfma_f32_16x16x32_bf16 v[116:119], v[172:175], v[188:191], v[116:119]
	v_mfma_f32_16x16x32_bf16 v[112:115], v[180:183], v[188:191], v[112:115]
	v_mfma_f32_16x16x32_bf16 v[100:103], v[172:175], v[196:199], v[100:103]
	v_mfma_f32_16x16x32_bf16 v[96:99], v[180:183], v[196:199], v[96:99]
	v_mfma_f32_16x16x32_bf16 v[84:87], v[172:175], v[212:215], v[84:87]
	v_mfma_f32_16x16x32_bf16 v[80:83], v[180:183], v[212:215], v[80:83]
	v_mfma_f32_16x16x32_bf16 v[68:71], v[172:175], v[220:223], v[68:71]
	v_mfma_f32_16x16x32_bf16 v[64:67], v[180:183], v[220:223], v[64:67]
	v_mfma_f32_16x16x32_bf16 v[116:119], v[176:179], v[192:195], v[116:119]
	v_mfma_f32_16x16x32_bf16 v[112:115], v[184:187], v[192:195], v[112:115]
	v_mfma_f32_16x16x32_bf16 v[100:103], v[176:179], v[200:203], v[100:103]
	v_mfma_f32_16x16x32_bf16 v[96:99], v[184:187], v[200:203], v[96:99]
	v_mfma_f32_16x16x32_bf16 v[84:87], v[176:179], v[216:219], v[84:87]
	v_mfma_f32_16x16x32_bf16 v[80:83], v[184:187], v[216:219], v[80:83]
	v_mfma_f32_16x16x32_bf16 v[68:71], v[176:179], v[224:227], v[68:71]
	v_mfma_f32_16x16x32_bf16 v[64:67], v[184:187], v[224:227], v[64:67]
	s_setprio 0
	s_barrier
; #define PG8_STAGE(bufoff, gbase, voff) do { _Pragma("unroll") for (int _i = 0; _i < 2; ++_i) \
;         __builtin_amdgcn_global_load_lds((const unsigned*)((const char*)(gbase) + (voff)[_i]), (PG8_LAS unsigned*)(lds + (bufoff) + ldsw + _i * 8192), 16, 0, 0); } while (0)
; #define PG8_LDA(dst, b, h) do { _Pragma("unroll") for (int m = 0; m < 4; ++m) _Pragma("unroll") for (int k = 0; k < 2; ++k) dst[m][k] = *(const PG8_LAS bf16x8*)(lds + PG8_SA(b, h) + aoff + m * 2048 + k * 1024); } while (0)
; #define PG8_MMA(ai, bj, At, Bt) do { __builtin_amdgcn_s_setprio(1); _Pragma("unroll") for (int m = 0; m < 4; ++m) _Pragma("unroll") for (int n = 0; n < 2; ++n) _Pragma("unroll") for (int k = 0; k < 2; ++k) \
;         acc[ai][bj][m][n] = __builtin_amdgcn_mfma_f32_16x16x32_bf16(Bt[n][k], At[m][k], acc[ai][bj][m][n], 0, 0, 0); __builtin_amdgcn_s_setprio(0); } while (0)
; #define PG8_WAIT_V(n) asm volatile("s_waitcnt vmcnt(" #n ")" ::: "memory")
; #define PG8_WAIT_L(n) asm volatile("s_waitcnt lgkmcnt(" #n ")" ::: "memory")
; #define PG8_BAR __builtin_amdgcn_s_barrier()
; #define PG8_SCHED __builtin_amdgcn_sched_barrier(0)
; template <class Epi, class Sched, bool ALIGN_EPI = false, bool SP2 = false>
; __device__ __forceinline__ void gemm_phase(PG8_LAS unsigned char* lds, const Gemm g, const Sched& S, const Epi& E, int tid_in) {
;     ...
;         for (int t = 0; t < nt; t += 2) {
;             const bool last = (t == nt - 2);
;     ...
;             PG8_LDA(At, 1, 1); PG8_STAGE(PG8_SB(1, 0), b3, voffB); PG8_STAGE(PG8_SB(1, 1), b3 + hstepB, voffB); PG8_STAGE(PG8_SA(1, 0), a3, voffA);
;             PG8_WAIT_V(8); PG8_WAIT_L(0); PG8_BAR; PG8_MMA(1, 0, At, B0); PG8_MMA(1, 1, At, B1); PG8_BAR; PG8_SCHED;
	s_add_i32 s26, s33, s54
	s_add_i32 m0, s26, 0xffffff80
	ds_read_b128 v[188:191], v152 offset:49152
	ds_read_b128 v[192:195], v152 offset:50176
	ds_read_b128 v[196:199], v152 offset:51200
	ds_read_b128 v[200:203], v152 offset:52224
	ds_read_b128 v[212:215], v152 offset:53248
	ds_read_b128 v[216:219], v152 offset:54272
	ds_read_b128 v[220:223], v152 offset:55296
	ds_read_b128 v[224:227], v152 offset:56320
	global_load_lds_dwordx4 v132, s[50:51] offset:128
	s_add_i32 m0, s26, 0x1f80
	s_add_u32 s26, s50, 0x20080
	s_addc_u32 s27, s51, 0
	s_add_i32 s33, s77, s54
	global_load_lds_dwordx4 v128, s[50:51] offset:128
	s_mov_b32 m0, s33
	s_nop 0
	global_load_lds_dwordx4 v132, s[26:27]
	s_add_i32 m0, s33, 0x2000
	s_nop 0
	global_load_lds_dwordx4 v128, s[26:27]
	s_add_i32 m0, s61, 0xffffff80
	s_nop 0
	global_load_lds_dwordx4 v134, s[52:53] offset:128
	s_add_i32 m0, s62, 0xffffff80
	s_nop 0
	global_load_lds_dwordx4 v130, s[52:53] offset:128
	s_waitcnt vmcnt(8)
	s_waitcnt lgkmcnt(0)
	s_barrier
	s_setprio 1
	s_waitcnt lgkmcnt(0)
	v_mfma_f32_16x16x32_bf16 v[60:63], v[156:159], v[188:191], v[60:63]
	v_mfma_f32_16x16x32_bf16 v[56:59], v[164:167], v[188:191], v[56:59]
	v_mfma_f32_16x16x32_bf16 v[44:47], v[156:159], v[196:199], v[44:47]
	v_mfma_f32_16x16x32_bf16 v[40:43], v[164:167], v[196:199], v[40:43]
	v_mfma_f32_16x16x32_bf16 v[28:31], v[156:159], v[212:215], v[28:31]
	v_mfma_f32_16x16x32_bf16 v[24:27], v[164:167], v[212:215], v[24:27]
	v_mfma_f32_16x16x32_bf16 v[12:15], v[156:159], v[220:223], v[12:15]
	v_mfma_f32_16x16x32_bf16 v[8:11], v[164:167], v[220:223], v[8:11]
	v_mfma_f32_16x16x32_bf16 v[60:63], v[160:163], v[192:195], v[60:63]
	v_mfma_f32_16x16x32_bf16 v[56:59], v[168:171], v[192:195], v[56:59]
	v_mfma_f32_16x16x32_bf16 v[44:47], v[160:163], v[200:203], v[44:47]
	v_mfma_f32_16x16x32_bf16 v[40:43], v[168:171], v[200:203], v[40:43]
	v_mfma_f32_16x16x32_bf16 v[28:31], v[160:163], v[216:219], v[28:31]
	v_mfma_f32_16x16x32_bf16 v[24:27], v[168:171], v[216:219], v[24:27]
	v_mfma_f32_16x16x32_bf16 v[12:15], v[160:163], v[224:227], v[12:15]
	v_mfma_f32_16x16x32_bf16 v[8:11], v[168:171], v[224:227], v[8:11]
	s_setprio 0
	s_setprio 1
	v_mfma_f32_16x16x32_bf16 v[52:55], v[172:175], v[188:191], v[52:55]
	v_mfma_f32_16x16x32_bf16 v[48:51], v[180:183], v[188:191], v[48:51]
	v_mfma_f32_16x16x32_bf16 v[36:39], v[172:175], v[196:199], v[36:39]
	v_mfma_f32_16x16x32_bf16 v[32:35], v[180:183], v[196:199], v[32:35]
	v_mfma_f32_16x16x32_bf16 v[20:23], v[172:175], v[212:215], v[20:23]
	v_mfma_f32_16x16x32_bf16 v[16:19], v[180:183], v[212:215], v[16:19]
	v_mfma_f32_16x16x32_bf16 v[4:7], v[172:175], v[220:223], v[4:7]
	v_mfma_f32_16x16x32_bf16 v[0:3], v[180:183], v[220:223], v[0:3]
	v_mfma_f32_16x16x32_bf16 v[52:55], v[176:179], v[192:195], v[52:55]
	v_mfma_f32_16x16x32_bf16 v[48:51], v[184:187], v[192:195], v[48:51]
	v_mfma_f32_16x16x32_bf16 v[36:39], v[176:179], v[200:203], v[36:39]
	v_mfma_f32_16x16x32_bf16 v[32:35], v[184:187], v[200:203], v[32:35]
	v_mfma_f32_16x16x32_bf16 v[20:23], v[176:179], v[216:219], v[20:23]
	v_mfma_f32_16x16x32_bf16 v[16:19], v[184:187], v[216:219], v[16:19]
	v_mfma_f32_16x16x32_bf16 v[4:7], v[176:179], v[224:227], v[4:7]
	v_mfma_f32_16x16x32_bf16 v[0:3], v[184:187], v[224:227], v[0:3]
	s_setprio 0
	s_barrier
	s_add_i32 s76, s76, 2
	s_add_u32 s48, s48, 0x100
	s_addc_u32 s49, s49, 0
	s_add_u32 s74, s74, 0x100
	s_addc_u32 s75, s75, 0
	s_cmp_gt_u32 s76, 29

; #define PG8_STAGE(bufoff, gbase, voff) do { _Pragma("unroll") for (int _i = 0; _i < 2; ++_i) \
;         __builtin_amdgcn_global_load_lds((const unsigned*)((const char*)(gbase) + (voff)[_i]), (PG8_LAS unsigned*)(lds + (bufoff) + ldsw + _i * 8192), 16, 0, 0); } while (0)
; #define PG8_LDA(dst, b, h) do { _Pragma("unroll") for (int m = 0; m < 4; ++m) _Pragma("unroll") for (int k = 0; k < 2; ++k) dst[m][k] = *(const PG8_LAS bf16x8*)(lds + PG8_SA(b, h) + aoff + m * 2048 + k * 1024); } while (0)
; #define PG8_LDB(dst, b, h) do { _Pragma("unroll") for (int n = 0; n < 2; ++n) _Pragma("unroll") for (int k = 0; k < 2; ++k) dst[n][k] = *(const PG8_LAS bf16x8*)(lds + PG8_SB(b, h) + boff + n * 2048 + k * 1024); } while (0)
; #define PG8_MMA(ai, bj, At, Bt) do { __builtin_amdgcn_s_setprio(1); _Pragma("unroll") for (int m = 0; m < 4; ++m) _Pragma("unroll") for (int n = 0; n < 2; ++n) _Pragma("unroll") for (int k = 0; k < 2; ++k) \
;         acc[ai][bj][m][n] = __builtin_amdgcn_mfma_f32_16x16x32_bf16(Bt[n][k], At[m][k], acc[ai][bj][m][n], 0, 0, 0); __builtin_amdgcn_s_setprio(0); } while (0)
; #define PG8_WAIT_V(n) asm volatile("s_waitcnt vmcnt(" #n ")" ::: "memory")
; #define PG8_WAIT_L(n) asm volatile("s_waitcnt lgkmcnt(" #n ")" ::: "memory")
; #define PG8_BAR __builtin_amdgcn_s_barrier()
; #define PG8_SCHED __builtin_amdgcn_sched_barrier(0)
; template <class Epi, class Sched, bool ALIGN_EPI = false, bool SP2 = false>
; __device__ __forceinline__ void gemm_phase(PG8_LAS unsigned char* lds, const Gemm g, const Sched& S, const Epi& E, int tid_in) {
;     ...
;     f32x4 acc[2][2][4][2];
; #pragma unroll
;     for (int a = 0; a < 2; ++a)
; #pragma unroll
;         for (int b = 0; b < 2; ++b)
; #pragma unroll
;             for (int m = 0; m < 4; ++m)
; #pragma unroll
;                 for (int n = 0; n < 2; ++n) acc[a][b][m][n] = (f32x4){0.f, 0.f, 0.f, 0.f};
;     ...
;             PG8_LDB(B0, 0, 0); PG8_LDB(B1, 0, 1); PG8_SCHED; PG8_LDA(At, 0, 0); PG8_STAGE(PG8_SA(1, 1), a1 + hstep, voffA);
;             PG8_WAIT_V(8); PG8_WAIT_L(0); PG8_BAR; PG8_MMA(0, 0, At, B0); PG8_MMA(0, 1, At, B1); PG8_BAR; PG8_SCHED;
;             PG8_LDA(At, 0, 1); PG8_STAGE(PG8_SB(0, 0), b2, voffB); PG8_STAGE(PG8_SB(0, 1), b2 + hstepB, voffB); PG8_STAGE(PG8_SA(0, 0), a2, voffA);
.LBB0_291:
	s_ashr_i32 s49, s48, 31
	s_lshl_b64 s[26:27], s[48:49], 20
	s_add_u32 s50, s28, s26
	s_addc_u32 s51, s29, s27
	s_and_b64 s[26:27], s[10:11], exec
	s_cselect_b32 s49, s51, s59
	s_cselect_b32 s55, s50, s58
	s_ashr_i32 s47, s46, 31
	s_lshl_b64 s[26:27], s[46:47], 20
	s_add_u32 s52, s64, s26
	s_addc_u32 s53, s65, s27
	s_and_b64 s[26:27], s[10:11], exec
	s_cselect_b32 s47, s53, s61
	s_cselect_b32 s75, s52, s60
	s_add_u32 s58, s58, 0x80080
	s_addc_u32 s59, s59, 0
	s_add_u32 s76, s60, 0x100
	s_addc_u32 s77, s61, 0
	s_mov_b32 s79, -2
	s_waitcnt lgkmcnt(0)
	s_cmp_eq_u32 s98, 1
	s_cbranch_scc0 .Lkb_skip_1
	s_mov_b32 s98, 0
	s_barrier
.Lkb_skip_1:
	ds_read_b128 v[146:149], v153
	ds_read_b128 v[158:161], v153 offset:1024
	ds_read_b128 v[162:165], v153 offset:2048
	ds_read_b128 v[166:169], v153 offset:3072
	ds_read_b128 v[170:173], v154
	ds_read_b128 v[174:177], v154 offset:1024
	ds_read_b128 v[178:181], v154 offset:2048
	ds_read_b128 v[182:185], v154 offset:3072
	s_add_u32 s26, s58, 0xfff80080
	s_addc_u32 s27, s59, -1
	s_cmp_eq_u32 s79, 28
	s_cselect_b32 s63, s49, s27
	s_cselect_b32 s62, s55, s26
	s_cselect_b32 s61, s47, s77
	s_cselect_b32 s60, s75, s76
	s_add_i32 m0, s57, 0xc000
	ds_read_b128 v[186:189], v155
	ds_read_b128 v[190:193], v155 offset:1024
	ds_read_b128 v[194:197], v155 offset:2048
	ds_read_b128 v[198:201], v155 offset:3072
	ds_read_b128 v[202:205], v155 offset:4096
	ds_read_b128 v[206:209], v155 offset:5120
	ds_read_b128 v[212:215], v155 offset:6144
	ds_read_b128 v[216:219], v155 offset:7168
	global_load_lds_dwordx4 v138, s[58:59]
	s_add_i32 m0, s57, 0xe000
	s_nop 0
	global_load_lds_dwordx4 v140, s[58:59]
	s_waitcnt vmcnt(8)
	s_waitcnt lgkmcnt(0)
	s_barrier
	s_setprio 1
	s_waitcnt lgkmcnt(0)
	v_mfma_f32_16x16x32_bf16 v[124:127], v[146:149], v[186:189], 0
	v_mfma_f32_16x16x32_bf16 v[120:123], v[162:165], v[186:189], 0
	v_mfma_f32_16x16x32_bf16 v[108:111], v[146:149], v[194:197], 0
	v_mfma_f32_16x16x32_bf16 v[104:107], v[162:165], v[194:197], 0
	v_mfma_f32_16x16x32_bf16 v[92:95], v[146:149], v[202:205], 0
	v_mfma_f32_16x16x32_bf16 v[88:91], v[162:165], v[202:205], 0
	v_mfma_f32_16x16x32_bf16 v[76:79], v[146:149], v[212:215], 0
	v_mfma_f32_16x16x32_bf16 v[72:75], v[162:165], v[212:215], 0
	v_mfma_f32_16x16x32_bf16 v[124:127], v[158:161], v[190:193], v[124:127]
	v_mfma_f32_16x16x32_bf16 v[120:123], v[166:169], v[190:193], v[120:123]
	v_mfma_f32_16x16x32_bf16 v[108:111], v[158:161], v[198:201], v[108:111]
	v_mfma_f32_16x16x32_bf16 v[104:107], v[166:169], v[198:201], v[104:107]
	v_mfma_f32_16x16x32_bf16 v[92:95], v[158:161], v[206:209], v[92:95]
	v_mfma_f32_16x16x32_bf16 v[88:91], v[166:169], v[206:209], v[88:91]
	v_mfma_f32_16x16x32_bf16 v[76:79], v[158:161], v[216:219], v[76:79]
	v_mfma_f32_16x16x32_bf16 v[72:75], v[166:169], v[216:219], v[72:75]
	s_setprio 0
	s_setprio 1
	v_mfma_f32_16x16x32_bf16 v[116:119], v[170:173], v[186:189], 0
	v_mfma_f32_16x16x32_bf16 v[112:115], v[178:181], v[186:189], 0
	v_mfma_f32_16x16x32_bf16 v[100:103], v[170:173], v[194:197], 0
	v_mfma_f32_16x16x32_bf16 v[96:99], v[178:181], v[194:197], 0
	v_mfma_f32_16x16x32_bf16 v[84:87], v[170:173], v[202:205], 0
	v_mfma_f32_16x16x32_bf16 v[80:83], v[178:181], v[202:205], 0
	v_mfma_f32_16x16x32_bf16 v[68:71], v[170:173], v[212:215], 0
	v_mfma_f32_16x16x32_bf16 v[64:67], v[178:181], v[212:215], 0
	v_mfma_f32_16x16x32_bf16 v[116:119], v[174:177], v[190:193], v[116:119]
	v_mfma_f32_16x16x32_bf16 v[112:115], v[182:185], v[190:193], v[112:115]
	v_mfma_f32_16x16x32_bf16 v[100:103], v[174:177], v[198:201], v[100:103]
	v_mfma_f32_16x16x32_bf16 v[96:99], v[182:185], v[198:201], v[96:99]
	v_mfma_f32_16x16x32_bf16 v[84:87], v[174:177], v[206:209], v[84:87]
	v_mfma_f32_16x16x32_bf16 v[80:83], v[182:185], v[206:209], v[80:83]
	v_mfma_f32_16x16x32_bf16 v[68:71], v[174:177], v[216:219], v[68:71]
	v_mfma_f32_16x16x32_bf16 v[64:67], v[182:185], v[216:219], v[64:67]
	s_setprio 0
	s_barrier
	s_add_i32 s26, s73, s66
	s_mov_b32 m0, s26
	ds_read_b128 v[186:189], v155 offset:16384
	ds_read_b128 v[190:193], v155 offset:17408
	ds_read_b128 v[194:197], v155 offset:18432
	ds_read_b128 v[198:201], v155 offset:19456
	ds_read_b128 v[202:205], v155 offset:20480
	ds_read_b128 v[206:209], v155 offset:21504
	ds_read_b128 v[212:215], v155 offset:22528
	ds_read_b128 v[216:219], v155 offset:23552
	global_load_lds_dwordx4 v130, s[60:61]
	s_add_i32 m0, s26, 0x2000
	s_add_u32 s26, s60, 0x20000
	s_addc_u32 s27, s61, 0
	s_add_i32 s33, s74, s66
	global_load_lds_dwordx4 v134, s[60:61]
	s_mov_b32 m0, s33
	s_nop 0
	global_load_lds_dwordx4 v130, s[26:27]
	s_add_i32 m0, s33, 0x2000
	s_nop 0
	global_load_lds_dwordx4 v134, s[26:27]
	s_mov_b32 m0, s57
	s_nop 0
	global_load_lds_dwordx4 v128, s[62:63]
	s_mov_b32 m0, s67
	s_nop 0
	global_load_lds_dwordx4 v132, s[62:63]
	s_waitcnt vmcnt(8)
	s_waitcnt lgkmcnt(0)
	s_barrier
; #define PG8_STAGE(bufoff, gbase, voff) do { _Pragma("unroll") for (int _i = 0; _i < 2; ++_i) \
;         __builtin_amdgcn_global_load_lds((const unsigned*)((const char*)(gbase) + (voff)[_i]), (PG8_LAS unsigned*)(lds + (bufoff) + ldsw + _i * 8192), 16, 0, 0); } while (0)
; #define PG8_LDA(dst, b, h) do { _Pragma("unroll") for (int m = 0; m < 4; ++m) _Pragma("unroll") for (int k = 0; k < 2; ++k) dst[m][k] = *(const PG8_LAS bf16x8*)(lds + PG8_SA(b, h) + aoff + m * 2048 + k * 1024); } while (0)
; #define PG8_LDB(dst, b, h) do { _Pragma("unroll") for (int n = 0; n < 2; ++n) _Pragma("unroll") for (int k = 0; k < 2; ++k) dst[n][k] = *(const PG8_LAS bf16x8*)(lds + PG8_SB(b, h) + boff + n * 2048 + k * 1024); } while (0)
; #define PG8_MMA(ai, bj, At, Bt) do { __builtin_amdgcn_s_setprio(1); _Pragma("unroll") for (int m = 0; m < 4; ++m) _Pragma("unroll") for (int n = 0; n < 2; ++n) _Pragma("unroll") for (int k = 0; k < 2; ++k) \
;         acc[ai][bj][m][n] = __builtin_amdgcn_mfma_f32_16x16x32_bf16(Bt[n][k], At[m][k], acc[ai][bj][m][n], 0, 0, 0); __builtin_amdgcn_s_setprio(0); } while (0)
; #define PG8_WAIT_V(n) asm volatile("s_waitcnt vmcnt(" #n ")" ::: "memory")
; #define PG8_WAIT_L(n) asm volatile("s_waitcnt lgkmcnt(" #n ")" ::: "memory")
; #define PG8_BAR __builtin_amdgcn_s_barrier()
; #define PG8_SCHED __builtin_amdgcn_sched_barrier(0)
; template <class Epi, class Sched, bool ALIGN_EPI = false, bool SP2 = false>
; __device__ __forceinline__ void gemm_phase(PG8_LAS unsigned char* lds, const Gemm g, const Sched& S, const Epi& E, int tid_in) {
;     ...
;             PG8_WAIT_V(8); PG8_WAIT_L(0); PG8_BAR; PG8_MMA(1, 0, At, B0); PG8_MMA(1, 1, At, B1); PG8_BAR; PG8_SCHED;
;             PG8_LDB(B0, 1, 0); PG8_LDB(B1, 1, 1); PG8_SCHED; PG8_LDA(At, 1, 0); PG8_STAGE(PG8_SA(0, 1), a2 + hstep, voffA);
;             PG8_WAIT_V(8); PG8_WAIT_L(0); PG8_BAR; PG8_MMA(0, 0, At, B0); PG8_MMA(0, 1, At, B1); PG8_BAR; PG8_SCHED;
	s_setprio 1
	s_waitcnt lgkmcnt(0)
	v_mfma_f32_16x16x32_bf16 v[60:63], v[146:149], v[186:189], 0
	v_mfma_f32_16x16x32_bf16 v[56:59], v[162:165], v[186:189], 0
	v_mfma_f32_16x16x32_bf16 v[44:47], v[146:149], v[194:197], 0
	v_mfma_f32_16x16x32_bf16 v[40:43], v[162:165], v[194:197], 0
	v_mfma_f32_16x16x32_bf16 v[28:31], v[146:149], v[202:205], 0
	v_mfma_f32_16x16x32_bf16 v[24:27], v[162:165], v[202:205], 0
	v_mfma_f32_16x16x32_bf16 v[12:15], v[146:149], v[212:215], 0
	v_mfma_f32_16x16x32_bf16 v[8:11], v[162:165], v[212:215], 0
	v_mfma_f32_16x16x32_bf16 v[60:63], v[158:161], v[190:193], v[60:63]
	v_mfma_f32_16x16x32_bf16 v[56:59], v[166:169], v[190:193], v[56:59]
	v_mfma_f32_16x16x32_bf16 v[44:47], v[158:161], v[198:201], v[44:47]
	v_mfma_f32_16x16x32_bf16 v[40:43], v[166:169], v[198:201], v[40:43]
	v_mfma_f32_16x16x32_bf16 v[28:31], v[158:161], v[206:209], v[28:31]
	v_mfma_f32_16x16x32_bf16 v[24:27], v[166:169], v[206:209], v[24:27]
	v_mfma_f32_16x16x32_bf16 v[12:15], v[158:161], v[216:219], v[12:15]
	v_mfma_f32_16x16x32_bf16 v[8:11], v[166:169], v[216:219], v[8:11]
	s_setprio 0
	s_setprio 1
	v_mfma_f32_16x16x32_bf16 v[52:55], v[170:173], v[186:189], 0
	v_mfma_f32_16x16x32_bf16 v[48:51], v[178:181], v[186:189], 0
	v_mfma_f32_16x16x32_bf16 v[36:39], v[170:173], v[194:197], 0
	v_mfma_f32_16x16x32_bf16 v[32:35], v[178:181], v[194:197], 0
	v_mfma_f32_16x16x32_bf16 v[20:23], v[170:173], v[202:205], 0
	v_mfma_f32_16x16x32_bf16 v[16:19], v[178:181], v[202:205], 0
	v_mfma_f32_16x16x32_bf16 v[4:7], v[170:173], v[212:215], 0
	v_mfma_f32_16x16x32_bf16 v[0:3], v[178:181], v[212:215], 0
	v_mfma_f32_16x16x32_bf16 v[52:55], v[174:177], v[190:193], v[52:55]
	v_mfma_f32_16x16x32_bf16 v[48:51], v[182:185], v[190:193], v[48:51]
	v_mfma_f32_16x16x32_bf16 v[36:39], v[174:177], v[198:201], v[36:39]
	v_mfma_f32_16x16x32_bf16 v[32:35], v[182:185], v[198:201], v[32:35]
	v_mfma_f32_16x16x32_bf16 v[20:23], v[174:177], v[206:209], v[20:23]
	v_mfma_f32_16x16x32_bf16 v[16:19], v[182:185], v[206:209], v[16:19]
	v_mfma_f32_16x16x32_bf16 v[4:7], v[174:177], v[216:219], v[4:7]
	v_mfma_f32_16x16x32_bf16 v[0:3], v[182:185], v[216:219], v[0:3]
	s_setprio 0
	s_barrier
	s_add_i32 s33, 0, 0x18000
	s_add_i32 s84, 0, 0x1c000
	v_add_u32_e32 v166, s33, v137
	v_add_u32_e32 v182, s84, v137
	ds_read_b128 v[146:149], v166
	ds_read_b128 v[158:161], v166 offset:1024
	ds_read_b128 v[162:165], v166 offset:2048
	ds_read_b128 v[166:169], v166 offset:3072
	ds_read_b128 v[170:173], v182
	ds_read_b128 v[174:177], v182 offset:1024
	ds_read_b128 v[178:181], v182 offset:2048
	ds_read_b128 v[182:185], v182 offset:3072
	s_add_u32 s26, s62, 0x80000
	s_addc_u32 s27, s63, 0
	s_mov_b32 m0, s68
	ds_read_b128 v[186:189], v155 offset:32768
	ds_read_b128 v[190:193], v155 offset:33792
	ds_read_b128 v[194:197], v155 offset:34816
	ds_read_b128 v[198:201], v155 offset:35840
	ds_read_b128 v[202:205], v155 offset:36864
	ds_read_b128 v[206:209], v155 offset:37888
	ds_read_b128 v[212:215], v155 offset:38912
	ds_read_b128 v[216:219], v155 offset:39936
	global_load_lds_dwordx4 v128, s[26:27]
	s_mov_b32 m0, s69
	s_nop 0
	global_load_lds_dwordx4 v132, s[26:27]
	s_waitcnt vmcnt(8)
	s_waitcnt lgkmcnt(0)
	s_barrier
	s_setprio 1
	s_waitcnt lgkmcnt(0)
	v_mfma_f32_16x16x32_bf16 v[124:127], v[146:149], v[186:189], v[124:127]
	v_mfma_f32_16x16x32_bf16 v[120:123], v[162:165], v[186:189], v[120:123]
	v_mfma_f32_16x16x32_bf16 v[108:111], v[146:149], v[194:197], v[108:111]
	v_mfma_f32_16x16x32_bf16 v[104:107], v[162:165], v[194:197], v[104:107]
	v_mfma_f32_16x16x32_bf16 v[92:95], v[146:149], v[202:205], v[92:95]
	v_mfma_f32_16x16x32_bf16 v[88:91], v[162:165], v[202:205], v[88:91]
	v_mfma_f32_16x16x32_bf16 v[76:79], v[146:149], v[212:215], v[76:79]
	v_mfma_f32_16x16x32_bf16 v[72:75], v[162:165], v[212:215], v[72:75]
	v_mfma_f32_16x16x32_bf16 v[124:127], v[158:161], v[190:193], v[124:127]
	v_mfma_f32_16x16x32_bf16 v[120:123], v[166:169], v[190:193], v[120:123]
	v_mfma_f32_16x16x32_bf16 v[108:111], v[158:161], v[198:201], v[108:111]
	v_mfma_f32_16x16x32_bf16 v[104:107], v[166:169], v[198:201], v[104:107]
	v_mfma_f32_16x16x32_bf16 v[92:95], v[158:161], v[206:209], v[92:95]
	v_mfma_f32_16x16x32_bf16 v[88:91], v[166:169], v[206:209], v[88:91]
	v_mfma_f32_16x16x32_bf16 v[76:79], v[158:161], v[216:219], v[76:79]
	v_mfma_f32_16x16x32_bf16 v[72:75], v[166:169], v[216:219], v[72:75]
	s_setprio 0
	s_setprio 1
	v_mfma_f32_16x16x32_bf16 v[116:119], v[170:173], v[186:189], v[116:119]
	v_mfma_f32_16x16x32_bf16 v[112:115], v[178:181], v[186:189], v[112:115]
	v_mfma_f32_16x16x32_bf16 v[100:103], v[170:173], v[194:197], v[100:103]
	v_mfma_f32_16x16x32_bf16 v[96:99], v[178:181], v[194:197], v[96:99]
	v_mfma_f32_16x16x32_bf16 v[84:87], v[170:173], v[202:205], v[84:87]
	v_mfma_f32_16x16x32_bf16 v[80:83], v[178:181], v[202:205], v[80:83]
	v_mfma_f32_16x16x32_bf16 v[68:71], v[170:173], v[212:215], v[68:71]
	v_mfma_f32_16x16x32_bf16 v[64:67], v[178:181], v[212:215], v[64:67]
	v_mfma_f32_16x16x32_bf16 v[116:119], v[174:177], v[190:193], v[116:119]
	v_mfma_f32_16x16x32_bf16 v[112:115], v[182:185], v[190:193], v[112:115]
	v_mfma_f32_16x16x32_bf16 v[100:103], v[174:177], v[198:201], v[100:103]
	v_mfma_f32_16x16x32_bf16 v[96:99], v[182:185], v[198:201], v[96:99]
	v_mfma_f32_16x16x32_bf16 v[84:87], v[174:177], v[206:209], v[84:87]
	v_mfma_f32_16x16x32_bf16 v[80:83], v[182:185], v[206:209], v[80:83]
	v_mfma_f32_16x16x32_bf16 v[68:71], v[174:177], v[216:219], v[68:71]
	v_mfma_f32_16x16x32_bf16 v[64:67], v[182:185], v[216:219], v[64:67]
	s_setprio 0
	s_barrier
; #define PG8_STAGE(bufoff, gbase, voff) do { _Pragma("unroll") for (int _i = 0; _i < 2; ++_i) \
;         __builtin_amdgcn_global_load_lds((const unsigned*)((const char*)(gbase) + (voff)[_i]), (PG8_LAS unsigned*)(lds + (bufoff) + ldsw + _i * 8192), 16, 0, 0); } while (0)
; #define PG8_LDA(dst, b, h) do { _Pragma("unroll") for (int m = 0; m < 4; ++m) _Pragma("unroll") for (int k = 0; k < 2; ++k) dst[m][k] = *(const PG8_LAS bf16x8*)(lds + PG8_SA(b, h) + aoff + m * 2048 + k * 1024); } while (0)
; #define PG8_MMA(ai, bj, At, Bt) do { __builtin_amdgcn_s_setprio(1); _Pragma("unroll") for (int m = 0; m < 4; ++m) _Pragma("unroll") for (int n = 0; n < 2; ++n) _Pragma("unroll") for (int k = 0; k < 2; ++k) \
;         acc[ai][bj][m][n] = __builtin_amdgcn_mfma_f32_16x16x32_bf16(Bt[n][k], At[m][k], acc[ai][bj][m][n], 0, 0, 0); __builtin_amdgcn_s_setprio(0); } while (0)
; #define PG8_WAIT_V(n) asm volatile("s_waitcnt vmcnt(" #n ")" ::: "memory")
; #define PG8_WAIT_L(n) asm volatile("s_waitcnt lgkmcnt(" #n ")" ::: "memory")
; #define PG8_BAR __builtin_amdgcn_s_barrier()
; #define PG8_SCHED __builtin_amdgcn_sched_barrier(0)
; template <class Epi, class Sched, bool ALIGN_EPI = false, bool SP2 = false>
; __device__ __forceinline__ void gemm_phase(PG8_LAS unsigned char* lds, const Gemm g, const Sched& S, const Epi& E, int tid_in) {
;     ...
;         for (int t = 0; t < nt; t += 2) {
;             const bool last = (t == nt - 2);
;     ...
;             PG8_LDA(At, 1, 1); PG8_STAGE(PG8_SB(1, 0), b3, voffB); PG8_STAGE(PG8_SB(1, 1), b3 + hstepB, voffB); PG8_STAGE(PG8_SA(1, 0), a3, voffA);
;             PG8_WAIT_V(8); PG8_WAIT_L(0); PG8_BAR; PG8_MMA(1, 0, At, B0); PG8_MMA(1, 1, At, B1); PG8_BAR; PG8_SCHED;
	s_add_i32 s26, s33, s66
	s_add_i32 m0, s26, 0xffffff80
	ds_read_b128 v[186:189], v155 offset:49152
	ds_read_b128 v[190:193], v155 offset:50176
	ds_read_b128 v[194:197], v155 offset:51200
	ds_read_b128 v[198:201], v155 offset:52224
	ds_read_b128 v[202:205], v155 offset:53248
	ds_read_b128 v[206:209], v155 offset:54272
	ds_read_b128 v[212:215], v155 offset:55296
	ds_read_b128 v[216:219], v155 offset:56320
	global_load_lds_dwordx4 v130, s[60:61] offset:128
	s_add_i32 m0, s26, 0x1f80
	s_add_u32 s26, s60, 0x20080
	s_addc_u32 s27, s61, 0
	s_add_i32 s33, s84, s66
	global_load_lds_dwordx4 v134, s[60:61] offset:128
	s_mov_b32 m0, s33
	s_nop 0
	global_load_lds_dwordx4 v130, s[26:27]
	s_add_i32 m0, s33, 0x2000
	s_nop 0
	global_load_lds_dwordx4 v134, s[26:27]
	s_add_i32 m0, s71, 0xffffff80
	s_nop 0
	global_load_lds_dwordx4 v128, s[62:63] offset:128
	s_add_i32 m0, s72, 0xffffff80
	s_nop 0
	global_load_lds_dwordx4 v132, s[62:63] offset:128
	s_waitcnt vmcnt(8)
	s_waitcnt lgkmcnt(0)
	s_barrier
	s_setprio 1
	s_waitcnt lgkmcnt(0)
	v_mfma_f32_16x16x32_bf16 v[60:63], v[146:149], v[186:189], v[60:63]
	v_mfma_f32_16x16x32_bf16 v[56:59], v[162:165], v[186:189], v[56:59]
	v_mfma_f32_16x16x32_bf16 v[44:47], v[146:149], v[194:197], v[44:47]
	v_mfma_f32_16x16x32_bf16 v[40:43], v[162:165], v[194:197], v[40:43]
	v_mfma_f32_16x16x32_bf16 v[28:31], v[146:149], v[202:205], v[28:31]
	v_mfma_f32_16x16x32_bf16 v[24:27], v[162:165], v[202:205], v[24:27]
	v_mfma_f32_16x16x32_bf16 v[12:15], v[146:149], v[212:215], v[12:15]
	v_mfma_f32_16x16x32_bf16 v[8:11], v[162:165], v[212:215], v[8:11]
	v_mfma_f32_16x16x32_bf16 v[60:63], v[158:161], v[190:193], v[60:63]
	v_mfma_f32_16x16x32_bf16 v[56:59], v[166:169], v[190:193], v[56:59]
	v_mfma_f32_16x16x32_bf16 v[44:47], v[158:161], v[198:201], v[44:47]
	v_mfma_f32_16x16x32_bf16 v[40:43], v[166:169], v[198:201], v[40:43]
	v_mfma_f32_16x16x32_bf16 v[28:31], v[158:161], v[206:209], v[28:31]
	v_mfma_f32_16x16x32_bf16 v[24:27], v[166:169], v[206:209], v[24:27]
	v_mfma_f32_16x16x32_bf16 v[12:15], v[158:161], v[216:219], v[12:15]
	v_mfma_f32_16x16x32_bf16 v[8:11], v[166:169], v[216:219], v[8:11]
	s_setprio 0
	s_setprio 1
	v_mfma_f32_16x16x32_bf16 v[52:55], v[170:173], v[186:189], v[52:55]
	v_mfma_f32_16x16x32_bf16 v[48:51], v[178:181], v[186:189], v[48:51]
	v_mfma_f32_16x16x32_bf16 v[36:39], v[170:173], v[194:197], v[36:39]
	v_mfma_f32_16x16x32_bf16 v[32:35], v[178:181], v[194:197], v[32:35]
	v_mfma_f32_16x16x32_bf16 v[20:23], v[170:173], v[202:205], v[20:23]
	v_mfma_f32_16x16x32_bf16 v[16:19], v[178:181], v[202:205], v[16:19]
	v_mfma_f32_16x16x32_bf16 v[4:7], v[170:173], v[212:215], v[4:7]
	v_mfma_f32_16x16x32_bf16 v[0:3], v[178:181], v[212:215], v[0:3]
	v_mfma_f32_16x16x32_bf16 v[52:55], v[174:177], v[190:193], v[52:55]
	v_mfma_f32_16x16x32_bf16 v[48:51], v[182:185], v[190:193], v[48:51]
	v_mfma_f32_16x16x32_bf16 v[36:39], v[174:177], v[198:201], v[36:39]
	v_mfma_f32_16x16x32_bf16 v[32:35], v[182:185], v[198:201], v[32:35]
	v_mfma_f32_16x16x32_bf16 v[20:23], v[174:177], v[206:209], v[20:23]
	v_mfma_f32_16x16x32_bf16 v[16:19], v[182:185], v[206:209], v[16:19]
	v_mfma_f32_16x16x32_bf16 v[4:7], v[174:177], v[216:219], v[4:7]
	v_mfma_f32_16x16x32_bf16 v[0:3], v[182:185], v[216:219], v[0:3]
	s_setprio 0
	s_barrier
	s_add_i32 s79, s79, 2
	s_add_u32 s58, s58, 0x100
	s_addc_u32 s59, s59, 0
	s_add_u32 s76, s76, 0x100
	s_addc_u32 s77, s77, 0
	s_cmp_gt_u32 s79, 29

; #define PG8_STAGE(bufoff, gbase, voff) do { _Pragma("unroll") for (int _i = 0; _i < 2; ++_i) \
;         __builtin_amdgcn_global_load_lds((const unsigned*)((const char*)(gbase) + (voff)[_i]), (PG8_LAS unsigned*)(lds + (bufoff) + ldsw + _i * 8192), 16, 0, 0); } while (0)
; #define PG8_LDA(dst, b, h) do { _Pragma("unroll") for (int m = 0; m < 4; ++m) _Pragma("unroll") for (int k = 0; k < 2; ++k) dst[m][k] = *(const PG8_LAS bf16x8*)(lds + PG8_SA(b, h) + aoff + m * 2048 + k * 1024); } while (0)
; #define PG8_LDB(dst, b, h) do { _Pragma("unroll") for (int n = 0; n < 2; ++n) _Pragma("unroll") for (int k = 0; k < 2; ++k) dst[n][k] = *(const PG8_LAS bf16x8*)(lds + PG8_SB(b, h) + boff + n * 2048 + k * 1024); } while (0)
; #define PG8_MMA(ai, bj, At, Bt) do { __builtin_amdgcn_s_setprio(1); _Pragma("unroll") for (int m = 0; m < 4; ++m) _Pragma("unroll") for (int n = 0; n < 2; ++n) _Pragma("unroll") for (int k = 0; k < 2; ++k) \
;         acc[ai][bj][m][n] = __builtin_amdgcn_mfma_f32_16x16x32_bf16(Bt[n][k], At[m][k], acc[ai][bj][m][n], 0, 0, 0); __builtin_amdgcn_s_setprio(0); } while (0)
; #define PG8_WAIT_V(n) asm volatile("s_waitcnt vmcnt(" #n ")" ::: "memory")
; #define PG8_WAIT_L(n) asm volatile("s_waitcnt lgkmcnt(" #n ")" ::: "memory")
; #define PG8_BAR __builtin_amdgcn_s_barrier()
; #define PG8_SCHED __builtin_amdgcn_sched_barrier(0)
; template <class Epi, class Sched, bool ALIGN_EPI = false, bool SP2 = false>
; __device__ __forceinline__ void gemm_phase(PG8_LAS unsigned char* lds, const Gemm g, const Sched& S, const Epi& E, int tid_in) {
;     ...
;     f32x4 acc[2][2][4][2];
; #pragma unroll
;     for (int a = 0; a < 2; ++a)
; #pragma unroll
;         for (int b = 0; b < 2; ++b)
; #pragma unroll
;             for (int m = 0; m < 4; ++m)
; #pragma unroll
;                 for (int n = 0; n < 2; ++n) acc[a][b][m][n] = (f32x4){0.f, 0.f, 0.f, 0.f};
;     ...
;             PG8_LDB(B0, 0, 0); PG8_LDB(B1, 0, 1); PG8_SCHED; PG8_LDA(At, 0, 0); PG8_STAGE(PG8_SA(1, 1), a1 + hstep, voffA);
;             PG8_WAIT_V(8); PG8_WAIT_L(0); PG8_BAR; PG8_MMA(0, 0, At, B0); PG8_MMA(0, 1, At, B1); PG8_BAR; PG8_SCHED;
;             PG8_LDA(At, 0, 1); PG8_STAGE(PG8_SB(0, 0), b2, voffB); PG8_STAGE(PG8_SB(0, 1), b2 + hstepB, voffB); PG8_STAGE(PG8_SA(0, 0), a2, voffA);
.LBB0_393:
	s_ashr_i32 s45, s44, 31
	s_lshl_b64 s[26:27], s[44:45], 20
	s_add_u32 s46, s38, s26
	s_addc_u32 s47, s39, s27
	s_and_b64 s[26:27], s[8:9], exec
	s_cselect_b32 s45, s47, s53
	s_cselect_b32 s72, s46, s52
	s_ashr_i32 s43, s42, 31
	s_lshl_b64 s[26:27], s[42:43], 20
	s_add_u32 s48, s58, s26
	s_addc_u32 s49, s59, s27
	s_and_b64 s[26:27], s[8:9], exec
	s_cselect_b32 s43, s49, s55
	s_cselect_b32 s73, s48, s54
	s_add_u32 s52, s52, 0x80080
	s_addc_u32 s53, s53, 0
	s_add_u32 s74, s54, 0x100
	s_addc_u32 s75, s55, 0
	s_mov_b32 s76, -2
	s_cmp_eq_u32 s98, 1
	s_cbranch_scc0 .Lkb_skip_2
	s_mov_b32 s98, 0
	s_barrier
.Lkb_skip_2:
	ds_read_b128 v[156:159], v150
	ds_read_b128 v[160:163], v150 offset:1024
	ds_read_b128 v[164:167], v150 offset:2048
	ds_read_b128 v[168:171], v150 offset:3072
	ds_read_b128 v[172:175], v151
	ds_read_b128 v[176:179], v151 offset:1024
	ds_read_b128 v[180:183], v151 offset:2048
	ds_read_b128 v[184:187], v151 offset:3072
	s_add_u32 s26, s52, 0xfff80080
	s_addc_u32 s27, s53, -1
	s_cmp_eq_u32 s76, 28
	s_cselect_b32 s57, s45, s27
	s_cselect_b32 s56, s72, s26
	s_cselect_b32 s55, s43, s75
	s_cselect_b32 s54, s73, s74
	s_add_i32 m0, s51, 0xc000
	ds_read_b128 v[188:191], v152
	ds_read_b128 v[192:195], v152 offset:1024
	ds_read_b128 v[196:199], v152 offset:2048
	ds_read_b128 v[200:203], v152 offset:3072
	ds_read_b128 v[204:207], v152 offset:4096
	ds_read_b128 v[212:215], v152 offset:5120
	ds_read_b128 v[216:219], v152 offset:6144
	ds_read_b128 v[220:223], v152 offset:7168
	global_load_lds_dwordx4 v138, s[52:53]
	s_add_i32 m0, s51, 0xe000
	s_nop 0
	global_load_lds_dwordx4 v140, s[52:53]
	s_waitcnt vmcnt(8)
	s_waitcnt lgkmcnt(0)
	s_barrier
	s_setprio 1
	s_waitcnt lgkmcnt(0)
	v_mfma_f32_16x16x32_bf16 v[124:127], v[156:159], v[188:191], 0
	v_mfma_f32_16x16x32_bf16 v[120:123], v[164:167], v[188:191], 0
	v_mfma_f32_16x16x32_bf16 v[108:111], v[156:159], v[196:199], 0
	v_mfma_f32_16x16x32_bf16 v[104:107], v[164:167], v[196:199], 0
	v_mfma_f32_16x16x32_bf16 v[92:95], v[156:159], v[204:207], 0
	v_mfma_f32_16x16x32_bf16 v[88:91], v[164:167], v[204:207], 0
	v_mfma_f32_16x16x32_bf16 v[76:79], v[156:159], v[216:219], 0
	v_mfma_f32_16x16x32_bf16 v[72:75], v[164:167], v[216:219], 0
	v_mfma_f32_16x16x32_bf16 v[124:127], v[160:163], v[192:195], v[124:127]
	v_mfma_f32_16x16x32_bf16 v[120:123], v[168:171], v[192:195], v[120:123]
	v_mfma_f32_16x16x32_bf16 v[108:111], v[160:163], v[200:203], v[108:111]
	v_mfma_f32_16x16x32_bf16 v[104:107], v[168:171], v[200:203], v[104:107]
	v_mfma_f32_16x16x32_bf16 v[92:95], v[160:163], v[212:215], v[92:95]
	v_mfma_f32_16x16x32_bf16 v[88:91], v[168:171], v[212:215], v[88:91]
	v_mfma_f32_16x16x32_bf16 v[76:79], v[160:163], v[220:223], v[76:79]
	v_mfma_f32_16x16x32_bf16 v[72:75], v[168:171], v[220:223], v[72:75]
	s_setprio 0
	s_setprio 1
	v_mfma_f32_16x16x32_bf16 v[116:119], v[172:175], v[188:191], 0
	v_mfma_f32_16x16x32_bf16 v[112:115], v[180:183], v[188:191], 0
	v_mfma_f32_16x16x32_bf16 v[100:103], v[172:175], v[196:199], 0
	v_mfma_f32_16x16x32_bf16 v[96:99], v[180:183], v[196:199], 0
	v_mfma_f32_16x16x32_bf16 v[84:87], v[172:175], v[204:207], 0
	v_mfma_f32_16x16x32_bf16 v[80:83], v[180:183], v[204:207], 0
	v_mfma_f32_16x16x32_bf16 v[68:71], v[172:175], v[216:219], 0
	v_mfma_f32_16x16x32_bf16 v[64:67], v[180:183], v[216:219], 0
	v_mfma_f32_16x16x32_bf16 v[116:119], v[176:179], v[192:195], v[116:119]
	v_mfma_f32_16x16x32_bf16 v[112:115], v[184:187], v[192:195], v[112:115]
	v_mfma_f32_16x16x32_bf16 v[100:103], v[176:179], v[200:203], v[100:103]
	v_mfma_f32_16x16x32_bf16 v[96:99], v[184:187], v[200:203], v[96:99]
	v_mfma_f32_16x16x32_bf16 v[84:87], v[176:179], v[212:215], v[84:87]
	v_mfma_f32_16x16x32_bf16 v[80:83], v[184:187], v[212:215], v[80:83]
	v_mfma_f32_16x16x32_bf16 v[68:71], v[176:179], v[220:223], v[68:71]
	v_mfma_f32_16x16x32_bf16 v[64:67], v[184:187], v[220:223], v[64:67]
	s_setprio 0
	s_barrier
	s_add_i32 s26, s68, s60
	s_mov_b32 m0, s26
	ds_read_b128 v[188:191], v152 offset:16384
	ds_read_b128 v[192:195], v152 offset:17408
	ds_read_b128 v[196:199], v152 offset:18432
	ds_read_b128 v[200:203], v152 offset:19456
	ds_read_b128 v[204:207], v152 offset:20480
	ds_read_b128 v[212:215], v152 offset:21504
	ds_read_b128 v[216:219], v152 offset:22528
	ds_read_b128 v[220:223], v152 offset:23552
	global_load_lds_dwordx4 v130, s[54:55]
	s_add_i32 m0, s26, 0x2000
	s_add_u32 s26, s54, 0x20000
	s_addc_u32 s27, s55, 0
	s_add_i32 s33, s69, s60
	global_load_lds_dwordx4 v134, s[54:55]
	s_mov_b32 m0, s33
	s_nop 0
	global_load_lds_dwordx4 v130, s[26:27]
	s_add_i32 m0, s33, 0x2000
	s_nop 0
	global_load_lds_dwordx4 v134, s[26:27]
	s_mov_b32 m0, s51
	s_nop 0
	global_load_lds_dwordx4 v128, s[56:57]
	s_mov_b32 m0, s61
	s_nop 0
	global_load_lds_dwordx4 v132, s[56:57]
	s_waitcnt vmcnt(8)
	s_waitcnt lgkmcnt(0)
	s_barrier
; #define PG8_STAGE(bufoff, gbase, voff) do { _Pragma("unroll") for (int _i = 0; _i < 2; ++_i) \
;         __builtin_amdgcn_global_load_lds((const unsigned*)((const char*)(gbase) + (voff)[_i]), (PG8_LAS unsigned*)(lds + (bufoff) + ldsw + _i * 8192), 16, 0, 0); } while (0)
; #define PG8_LDA(dst, b, h) do { _Pragma("unroll") for (int m = 0; m < 4; ++m) _Pragma("unroll") for (int k = 0; k < 2; ++k) dst[m][k] = *(const PG8_LAS bf16x8*)(lds + PG8_SA(b, h) + aoff + m * 2048 + k * 1024); } while (0)
; #define PG8_LDB(dst, b, h) do { _Pragma("unroll") for (int n = 0; n < 2; ++n) _Pragma("unroll") for (int k = 0; k < 2; ++k) dst[n][k] = *(const PG8_LAS bf16x8*)(lds + PG8_SB(b, h) + boff + n * 2048 + k * 1024); } while (0)
; #define PG8_MMA(ai, bj, At, Bt) do { __builtin_amdgcn_s_setprio(1); _Pragma("unroll") for (int m = 0; m < 4; ++m) _Pragma("unroll") for (int n = 0; n < 2; ++n) _Pragma("unroll") for (int k = 0; k < 2; ++k) \
;         acc[ai][bj][m][n] = __builtin_amdgcn_mfma_f32_16x16x32_bf16(Bt[n][k], At[m][k], acc[ai][bj][m][n], 0, 0, 0); __builtin_amdgcn_s_setprio(0); } while (0)
; #define PG8_WAIT_V(n) asm volatile("s_waitcnt vmcnt(" #n ")" ::: "memory")
; #define PG8_WAIT_L(n) asm volatile("s_waitcnt lgkmcnt(" #n ")" ::: "memory")
; #define PG8_BAR __builtin_amdgcn_s_barrier()
; #define PG8_SCHED __builtin_amdgcn_sched_barrier(0)
; template <class Epi, class Sched, bool ALIGN_EPI = false, bool SP2 = false>
; __device__ __forceinline__ void gemm_phase(PG8_LAS unsigned char* lds, const Gemm g, const Sched& S, const Epi& E, int tid_in) {
;     ...
;             PG8_WAIT_V(8); PG8_WAIT_L(0); PG8_BAR; PG8_MMA(1, 0, At, B0); PG8_MMA(1, 1, At, B1); PG8_BAR; PG8_SCHED;
;             PG8_LDB(B0, 1, 0); PG8_LDB(B1, 1, 1); PG8_SCHED; PG8_LDA(At, 1, 0); PG8_STAGE(PG8_SA(0, 1), a2 + hstep, voffA);
;             PG8_WAIT_V(8); PG8_WAIT_L(0); PG8_BAR; PG8_MMA(0, 0, At, B0); PG8_MMA(0, 1, At, B1); PG8_BAR; PG8_SCHED;
	s_setprio 1
	s_waitcnt lgkmcnt(0)
	v_mfma_f32_16x16x32_bf16 v[60:63], v[156:159], v[188:191], 0
	v_mfma_f32_16x16x32_bf16 v[56:59], v[164:167], v[188:191], 0
	v_mfma_f32_16x16x32_bf16 v[44:47], v[156:159], v[196:199], 0
	v_mfma_f32_16x16x32_bf16 v[40:43], v[164:167], v[196:199], 0
	v_mfma_f32_16x16x32_bf16 v[28:31], v[156:159], v[204:207], 0
	v_mfma_f32_16x16x32_bf16 v[24:27], v[164:167], v[204:207], 0
	v_mfma_f32_16x16x32_bf16 v[12:15], v[156:159], v[216:219], 0
	v_mfma_f32_16x16x32_bf16 v[8:11], v[164:167], v[216:219], 0
	v_mfma_f32_16x16x32_bf16 v[60:63], v[160:163], v[192:195], v[60:63]
	v_mfma_f32_16x16x32_bf16 v[56:59], v[168:171], v[192:195], v[56:59]
	v_mfma_f32_16x16x32_bf16 v[44:47], v[160:163], v[200:203], v[44:47]
	v_mfma_f32_16x16x32_bf16 v[40:43], v[168:171], v[200:203], v[40:43]
	v_mfma_f32_16x16x32_bf16 v[28:31], v[160:163], v[212:215], v[28:31]
	v_mfma_f32_16x16x32_bf16 v[24:27], v[168:171], v[212:215], v[24:27]
	v_mfma_f32_16x16x32_bf16 v[12:15], v[160:163], v[220:223], v[12:15]
	v_mfma_f32_16x16x32_bf16 v[8:11], v[168:171], v[220:223], v[8:11]
	s_setprio 0
	s_setprio 1
	v_mfma_f32_16x16x32_bf16 v[52:55], v[172:175], v[188:191], 0
	v_mfma_f32_16x16x32_bf16 v[48:51], v[180:183], v[188:191], 0
	v_mfma_f32_16x16x32_bf16 v[36:39], v[172:175], v[196:199], 0
	v_mfma_f32_16x16x32_bf16 v[32:35], v[180:183], v[196:199], 0
	v_mfma_f32_16x16x32_bf16 v[20:23], v[172:175], v[204:207], 0
	v_mfma_f32_16x16x32_bf16 v[16:19], v[180:183], v[204:207], 0
	v_mfma_f32_16x16x32_bf16 v[4:7], v[172:175], v[216:219], 0
	v_mfma_f32_16x16x32_bf16 v[0:3], v[180:183], v[216:219], 0
	v_mfma_f32_16x16x32_bf16 v[52:55], v[176:179], v[192:195], v[52:55]
	v_mfma_f32_16x16x32_bf16 v[48:51], v[184:187], v[192:195], v[48:51]
	v_mfma_f32_16x16x32_bf16 v[36:39], v[176:179], v[200:203], v[36:39]
	v_mfma_f32_16x16x32_bf16 v[32:35], v[184:187], v[200:203], v[32:35]
	v_mfma_f32_16x16x32_bf16 v[20:23], v[176:179], v[212:215], v[20:23]
	v_mfma_f32_16x16x32_bf16 v[16:19], v[184:187], v[212:215], v[16:19]
	v_mfma_f32_16x16x32_bf16 v[4:7], v[176:179], v[220:223], v[4:7]
	v_mfma_f32_16x16x32_bf16 v[0:3], v[184:187], v[220:223], v[0:3]
	s_setprio 0
	s_barrier
	s_add_i32 s33, 0, 0x18000
	v_add_u32_e32 v155, s33, v146
	s_add_i32 s77, 0, 0x1c000
	ds_read_b128 v[156:159], v155
	ds_read_b128 v[160:163], v155 offset:1024
	ds_read_b128 v[164:167], v155 offset:2048
	ds_read_b128 v[168:171], v155 offset:3072
	v_add_u32_e32 v155, s77, v146
	ds_read_b128 v[172:175], v155
	ds_read_b128 v[176:179], v155 offset:1024
	ds_read_b128 v[180:183], v155 offset:2048
	ds_read_b128 v[184:187], v155 offset:3072
	s_add_u32 s26, s56, 0x80000
	s_addc_u32 s27, s57, 0
	s_mov_b32 m0, s62
	ds_read_b128 v[188:191], v152 offset:32768
	ds_read_b128 v[192:195], v152 offset:33792
	ds_read_b128 v[196:199], v152 offset:34816
	ds_read_b128 v[200:203], v152 offset:35840
	ds_read_b128 v[204:207], v152 offset:36864
	ds_read_b128 v[212:215], v152 offset:37888
	ds_read_b128 v[216:219], v152 offset:38912
	ds_read_b128 v[220:223], v152 offset:39936
	global_load_lds_dwordx4 v128, s[26:27]
	s_mov_b32 m0, s63
	s_nop 0
	global_load_lds_dwordx4 v132, s[26:27]
	s_waitcnt vmcnt(8)
	s_waitcnt lgkmcnt(0)
	s_barrier
	s_setprio 1
	s_waitcnt lgkmcnt(0)
	v_mfma_f32_16x16x32_bf16 v[124:127], v[156:159], v[188:191], v[124:127]
	v_mfma_f32_16x16x32_bf16 v[120:123], v[164:167], v[188:191], v[120:123]
	v_mfma_f32_16x16x32_bf16 v[108:111], v[156:159], v[196:199], v[108:111]
	v_mfma_f32_16x16x32_bf16 v[104:107], v[164:167], v[196:199], v[104:107]
	v_mfma_f32_16x16x32_bf16 v[92:95], v[156:159], v[204:207], v[92:95]
	v_mfma_f32_16x16x32_bf16 v[88:91], v[164:167], v[204:207], v[88:91]
	v_mfma_f32_16x16x32_bf16 v[76:79], v[156:159], v[216:219], v[76:79]
	v_mfma_f32_16x16x32_bf16 v[72:75], v[164:167], v[216:219], v[72:75]
	v_mfma_f32_16x16x32_bf16 v[124:127], v[160:163], v[192:195], v[124:127]
	v_mfma_f32_16x16x32_bf16 v[120:123], v[168:171], v[192:195], v[120:123]
	v_mfma_f32_16x16x32_bf16 v[108:111], v[160:163], v[200:203], v[108:111]
	v_mfma_f32_16x16x32_bf16 v[104:107], v[168:171], v[200:203], v[104:107]
	v_mfma_f32_16x16x32_bf16 v[92:95], v[160:163], v[212:215], v[92:95]
	v_mfma_f32_16x16x32_bf16 v[88:91], v[168:171], v[212:215], v[88:91]
	v_mfma_f32_16x16x32_bf16 v[76:79], v[160:163], v[220:223], v[76:79]
	v_mfma_f32_16x16x32_bf16 v[72:75], v[168:171], v[220:223], v[72:75]
	s_setprio 0
	s_setprio 1
	v_mfma_f32_16x16x32_bf16 v[116:119], v[172:175], v[188:191], v[116:119]
	v_mfma_f32_16x16x32_bf16 v[112:115], v[180:183], v[188:191], v[112:115]
	v_mfma_f32_16x16x32_bf16 v[100:103], v[172:175], v[196:199], v[100:103]
	v_mfma_f32_16x16x32_bf16 v[96:99], v[180:183], v[196:199], v[96:99]
	v_mfma_f32_16x16x32_bf16 v[84:87], v[172:175], v[204:207], v[84:87]
	v_mfma_f32_16x16x32_bf16 v[80:83], v[180:183], v[204:207], v[80:83]
	v_mfma_f32_16x16x32_bf16 v[68:71], v[172:175], v[216:219], v[68:71]
	v_mfma_f32_16x16x32_bf16 v[64:67], v[180:183], v[216:219], v[64:67]
	v_mfma_f32_16x16x32_bf16 v[116:119], v[176:179], v[192:195], v[116:119]
	v_mfma_f32_16x16x32_bf16 v[112:115], v[184:187], v[192:195], v[112:115]
	v_mfma_f32_16x16x32_bf16 v[100:103], v[176:179], v[200:203], v[100:103]
	v_mfma_f32_16x16x32_bf16 v[96:99], v[184:187], v[200:203], v[96:99]
	v_mfma_f32_16x16x32_bf16 v[84:87], v[176:179], v[212:215], v[84:87]
	v_mfma_f32_16x16x32_bf16 v[80:83], v[184:187], v[212:215], v[80:83]
	v_mfma_f32_16x16x32_bf16 v[68:71], v[176:179], v[220:223], v[68:71]
	v_mfma_f32_16x16x32_bf16 v[64:67], v[184:187], v[220:223], v[64:67]
	s_setprio 0
	s_barrier
; #define PG8_STAGE(bufoff, gbase, voff) do { _Pragma("unroll") for (int _i = 0; _i < 2; ++_i) \
;         __builtin_amdgcn_global_load_lds((const unsigned*)((const char*)(gbase) + (voff)[_i]), (PG8_LAS unsigned*)(lds + (bufoff) + ldsw + _i * 8192), 16, 0, 0); } while (0)
; #define PG8_LDA(dst, b, h) do { _Pragma("unroll") for (int m = 0; m < 4; ++m) _Pragma("unroll") for (int k = 0; k < 2; ++k) dst[m][k] = *(const PG8_LAS bf16x8*)(lds + PG8_SA(b, h) + aoff + m * 2048 + k * 1024); } while (0)
; #define PG8_MMA(ai, bj, At, Bt) do { __builtin_amdgcn_s_setprio(1); _Pragma("unroll") for (int m = 0; m < 4; ++m) _Pragma("unroll") for (int n = 0; n < 2; ++n) _Pragma("unroll") for (int k = 0; k < 2; ++k) \
;         acc[ai][bj][m][n] = __builtin_amdgcn_mfma_f32_16x16x32_bf16(Bt[n][k], At[m][k], acc[ai][bj][m][n], 0, 0, 0); __builtin_amdgcn_s_setprio(0); } while (0)
; #define PG8_WAIT_V(n) asm volatile("s_waitcnt vmcnt(" #n ")" ::: "memory")
; #define PG8_WAIT_L(n) asm volatile("s_waitcnt lgkmcnt(" #n ")" ::: "memory")
; #define PG8_BAR __builtin_amdgcn_s_barrier()
; #define PG8_SCHED __builtin_amdgcn_sched_barrier(0)
; template <class Epi, class Sched, bool ALIGN_EPI = false, bool SP2 = false>
; __device__ __forceinline__ void gemm_phase(PG8_LAS unsigned char* lds, const Gemm g, const Sched& S, const Epi& E, int tid_in) {
;     ...
;         for (int t = 0; t < nt; t += 2) {
;             const bool last = (t == nt - 2);
;     ...
;             PG8_LDA(At, 1, 1); PG8_STAGE(PG8_SB(1, 0), b3, voffB); PG8_STAGE(PG8_SB(1, 1), b3 + hstepB, voffB); PG8_STAGE(PG8_SA(1, 0), a3, voffA);
;             PG8_WAIT_V(8); PG8_WAIT_L(0); PG8_BAR; PG8_MMA(1, 0, At, B0); PG8_MMA(1, 1, At, B1); PG8_BAR; PG8_SCHED;
	s_add_i32 s26, s33, s60
	s_add_i32 m0, s26, 0xffffff80
	ds_read_b128 v[188:191], v152 offset:49152
	ds_read_b128 v[192:195], v152 offset:50176
	ds_read_b128 v[196:199], v152 offset:51200
	ds_read_b128 v[200:203], v152 offset:52224
	ds_read_b128 v[204:207], v152 offset:53248
	ds_read_b128 v[212:215], v152 offset:54272
	ds_read_b128 v[216:219], v152 offset:55296
	ds_read_b128 v[220:223], v152 offset:56320
	global_load_lds_dwordx4 v130, s[54:55] offset:128
	s_add_i32 m0, s26, 0x1f80
	s_add_u32 s26, s54, 0x20080
	s_addc_u32 s27, s55, 0
	s_add_i32 s33, s77, s60
	global_load_lds_dwordx4 v134, s[54:55] offset:128
	s_mov_b32 m0, s33
	s_nop 0
	global_load_lds_dwordx4 v130, s[26:27]
	s_add_i32 m0, s33, 0x2000
	s_nop 0
	global_load_lds_dwordx4 v134, s[26:27]
	s_add_i32 m0, s66, 0xffffff80
	s_nop 0
	global_load_lds_dwordx4 v128, s[56:57] offset:128
	s_add_i32 m0, s67, 0xffffff80
	s_nop 0
	global_load_lds_dwordx4 v132, s[56:57] offset:128
	s_waitcnt vmcnt(8)
	s_waitcnt lgkmcnt(0)
	s_barrier
	s_setprio 1
	s_waitcnt lgkmcnt(0)
	v_mfma_f32_16x16x32_bf16 v[60:63], v[156:159], v[188:191], v[60:63]
	v_mfma_f32_16x16x32_bf16 v[56:59], v[164:167], v[188:191], v[56:59]
	v_mfma_f32_16x16x32_bf16 v[44:47], v[156:159], v[196:199], v[44:47]
	v_mfma_f32_16x16x32_bf16 v[40:43], v[164:167], v[196:199], v[40:43]
	v_mfma_f32_16x16x32_bf16 v[28:31], v[156:159], v[204:207], v[28:31]
	v_mfma_f32_16x16x32_bf16 v[24:27], v[164:167], v[204:207], v[24:27]
	v_mfma_f32_16x16x32_bf16 v[12:15], v[156:159], v[216:219], v[12:15]
	v_mfma_f32_16x16x32_bf16 v[8:11], v[164:167], v[216:219], v[8:11]
	v_mfma_f32_16x16x32_bf16 v[60:63], v[160:163], v[192:195], v[60:63]
	v_mfma_f32_16x16x32_bf16 v[56:59], v[168:171], v[192:195], v[56:59]
	v_mfma_f32_16x16x32_bf16 v[44:47], v[160:163], v[200:203], v[44:47]
	v_mfma_f32_16x16x32_bf16 v[40:43], v[168:171], v[200:203], v[40:43]
	v_mfma_f32_16x16x32_bf16 v[28:31], v[160:163], v[212:215], v[28:31]
	v_mfma_f32_16x16x32_bf16 v[24:27], v[168:171], v[212:215], v[24:27]
	v_mfma_f32_16x16x32_bf16 v[12:15], v[160:163], v[220:223], v[12:15]
	v_mfma_f32_16x16x32_bf16 v[8:11], v[168:171], v[220:223], v[8:11]
	s_setprio 0
	s_setprio 1
	v_mfma_f32_16x16x32_bf16 v[52:55], v[172:175], v[188:191], v[52:55]
	v_mfma_f32_16x16x32_bf16 v[48:51], v[180:183], v[188:191], v[48:51]
	v_mfma_f32_16x16x32_bf16 v[36:39], v[172:175], v[196:199], v[36:39]
	v_mfma_f32_16x16x32_bf16 v[32:35], v[180:183], v[196:199], v[32:35]
	v_mfma_f32_16x16x32_bf16 v[20:23], v[172:175], v[204:207], v[20:23]
	v_mfma_f32_16x16x32_bf16 v[16:19], v[180:183], v[204:207], v[16:19]
	v_mfma_f32_16x16x32_bf16 v[4:7], v[172:175], v[216:219], v[4:7]
	v_mfma_f32_16x16x32_bf16 v[0:3], v[180:183], v[216:219], v[0:3]
	v_mfma_f32_16x16x32_bf16 v[52:55], v[176:179], v[192:195], v[52:55]
	v_mfma_f32_16x16x32_bf16 v[48:51], v[184:187], v[192:195], v[48:51]
	v_mfma_f32_16x16x32_bf16 v[36:39], v[176:179], v[200:203], v[36:39]
	v_mfma_f32_16x16x32_bf16 v[32:35], v[184:187], v[200:203], v[32:35]
	v_mfma_f32_16x16x32_bf16 v[20:23], v[176:179], v[212:215], v[20:23]
	v_mfma_f32_16x16x32_bf16 v[16:19], v[184:187], v[212:215], v[16:19]
	v_mfma_f32_16x16x32_bf16 v[4:7], v[176:179], v[220:223], v[4:7]
	v_mfma_f32_16x16x32_bf16 v[0:3], v[184:187], v[220:223], v[0:3]
	s_setprio 0
	s_barrier
	s_add_i32 s76, s76, 2
	s_add_u32 s52, s52, 0x100
	s_addc_u32 s53, s53, 0
	s_add_u32 s74, s74, 0x100
	s_addc_u32 s75, s75, 0
	s_cmp_gt_u32 s76, 29

; #define PG8_STAGE(bufoff, gbase, voff) do { _Pragma("unroll") for (int _i = 0; _i < 2; ++_i) \
;         __builtin_amdgcn_global_load_lds((const unsigned*)((const char*)(gbase) + (voff)[_i]), (PG8_LAS unsigned*)(lds + (bufoff) + ldsw + _i * 8192), 16, 0, 0); } while (0)
; #define PG8_LDA(dst, b, h) do { _Pragma("unroll") for (int m = 0; m < 4; ++m) _Pragma("unroll") for (int k = 0; k < 2; ++k) dst[m][k] = *(const PG8_LAS bf16x8*)(lds + PG8_SA(b, h) + aoff + m * 2048 + k * 1024); } while (0)
; #define PG8_LDB(dst, b, h) do { _Pragma("unroll") for (int n = 0; n < 2; ++n) _Pragma("unroll") for (int k = 0; k < 2; ++k) dst[n][k] = *(const PG8_LAS bf16x8*)(lds + PG8_SB(b, h) + boff + n * 2048 + k * 1024); } while (0)
; #define PG8_MMA(ai, bj, At, Bt) do { __builtin_amdgcn_s_setprio(1); _Pragma("unroll") for (int m = 0; m < 4; ++m) _Pragma("unroll") for (int n = 0; n < 2; ++n) _Pragma("unroll") for (int k = 0; k < 2; ++k) \
;         acc[ai][bj][m][n] = __builtin_amdgcn_mfma_f32_16x16x32_bf16(Bt[n][k], At[m][k], acc[ai][bj][m][n], 0, 0, 0); __builtin_amdgcn_s_setprio(0); } while (0)
; #define PG8_WAIT_V(n) asm volatile("s_waitcnt vmcnt(" #n ")" ::: "memory")
; #define PG8_WAIT_L(n) asm volatile("s_waitcnt lgkmcnt(" #n ")" ::: "memory")
; #define PG8_BAR __builtin_amdgcn_s_barrier()
; #define PG8_SCHED __builtin_amdgcn_sched_barrier(0)
; template <class Epi, class Sched, bool ALIGN_EPI = false, bool SP2 = false>
; __device__ __forceinline__ void gemm_phase(PG8_LAS unsigned char* lds, const Gemm g, const Sched& S, const Epi& E, int tid_in) {
;     ...
;     f32x4 acc[2][2][4][2];
; #pragma unroll
;     for (int a = 0; a < 2; ++a)
; #pragma unroll
;         for (int b = 0; b < 2; ++b)
; #pragma unroll
;             for (int m = 0; m < 4; ++m)
; #pragma unroll
;                 for (int n = 0; n < 2; ++n) acc[a][b][m][n] = (f32x4){0.f, 0.f, 0.f, 0.f};
;     ...
;             PG8_LDB(B0, 0, 0); PG8_LDB(B1, 0, 1); PG8_SCHED; PG8_LDA(At, 0, 0); PG8_STAGE(PG8_SA(1, 1), a1 + hstep, voffA);
;             PG8_WAIT_V(8); PG8_WAIT_L(0); PG8_BAR; PG8_MMA(0, 0, At, B0); PG8_MMA(0, 1, At, B1); PG8_BAR; PG8_SCHED;
;             PG8_LDA(At, 0, 1); PG8_STAGE(PG8_SB(0, 0), b2, voffB); PG8_STAGE(PG8_SB(0, 1), b2 + hstepB, voffB); PG8_STAGE(PG8_SA(0, 0), a2, voffA);
.LBB0_473:
	s_ashr_i32 s49, s48, 31
	s_lshl_b64 s[26:27], s[48:49], 22
	s_add_u32 s52, s62, s26
	s_addc_u32 s53, s63, s27
	s_and_b64 s[12:13], s[12:13], exec
	s_cselect_b32 s49, s53, s59
	s_cselect_b32 s75, s52, s58
	s_add_u32 s76, s58, 0x100
	s_addc_u32 s77, s59, 0
	s_mov_b32 s79, -2
	s_waitcnt lgkmcnt(0)
	s_cmp_eq_u32 s98, 1
	s_cbranch_scc0 .Lkb_skip_3
	s_mov_b32 s98, 0
	s_barrier
.Lkb_skip_3:
	ds_read_b128 v[146:149], v153
	ds_read_b128 v[158:161], v153 offset:1024
	ds_read_b128 v[162:165], v153 offset:2048
	ds_read_b128 v[166:169], v153 offset:3072
	ds_read_b128 v[170:173], v154
	ds_read_b128 v[174:177], v154 offset:1024
	ds_read_b128 v[178:181], v154 offset:2048
	ds_read_b128 v[182:185], v154 offset:3072
	s_add_u32 s12, s56, 0x100
	s_addc_u32 s13, s57, 0
	s_cmpk_eq_i32 s79, 0x7c
	s_cselect_b32 s61, s51, s13
	s_cselect_b32 s60, s50, s12
	s_cselect_b32 s59, s49, s77
	s_cselect_b32 s58, s75, s76
	s_add_i32 m0, s55, 0xc000
	ds_read_b128 v[186:189], v155
	ds_read_b128 v[190:193], v155 offset:1024
	ds_read_b128 v[194:197], v155 offset:2048
	ds_read_b128 v[198:201], v155 offset:3072
	ds_read_b128 v[202:205], v155 offset:4096
	ds_read_b128 v[206:209], v155 offset:5120
	ds_read_b128 v[212:215], v155 offset:6144
	ds_read_b128 v[216:219], v155 offset:7168
	global_load_lds_dwordx4 v138, s[56:57]
	s_add_i32 m0, s55, 0xe000
	s_nop 0
	global_load_lds_dwordx4 v140, s[56:57]
	s_waitcnt vmcnt(8)
	s_waitcnt lgkmcnt(0)
	s_barrier
	s_setprio 1
	s_waitcnt lgkmcnt(0)
	v_mfma_f32_16x16x32_bf16 v[124:127], v[146:149], v[186:189], 0
	v_mfma_f32_16x16x32_bf16 v[120:123], v[162:165], v[186:189], 0
	v_mfma_f32_16x16x32_bf16 v[108:111], v[146:149], v[194:197], 0
	v_mfma_f32_16x16x32_bf16 v[104:107], v[162:165], v[194:197], 0
	v_mfma_f32_16x16x32_bf16 v[92:95], v[146:149], v[202:205], 0
	v_mfma_f32_16x16x32_bf16 v[88:91], v[162:165], v[202:205], 0
	v_mfma_f32_16x16x32_bf16 v[76:79], v[146:149], v[212:215], 0
	v_mfma_f32_16x16x32_bf16 v[72:75], v[162:165], v[212:215], 0
	v_mfma_f32_16x16x32_bf16 v[124:127], v[158:161], v[190:193], v[124:127]
	v_mfma_f32_16x16x32_bf16 v[120:123], v[166:169], v[190:193], v[120:123]
	v_mfma_f32_16x16x32_bf16 v[108:111], v[158:161], v[198:201], v[108:111]
	v_mfma_f32_16x16x32_bf16 v[104:107], v[166:169], v[198:201], v[104:107]
	v_mfma_f32_16x16x32_bf16 v[92:95], v[158:161], v[206:209], v[92:95]
	v_mfma_f32_16x16x32_bf16 v[88:91], v[166:169], v[206:209], v[88:91]
	v_mfma_f32_16x16x32_bf16 v[76:79], v[158:161], v[216:219], v[76:79]
	v_mfma_f32_16x16x32_bf16 v[72:75], v[166:169], v[216:219], v[72:75]
	s_setprio 0
	s_setprio 1
	v_mfma_f32_16x16x32_bf16 v[116:119], v[170:173], v[186:189], 0
	v_mfma_f32_16x16x32_bf16 v[112:115], v[178:181], v[186:189], 0
	v_mfma_f32_16x16x32_bf16 v[100:103], v[170:173], v[194:197], 0
	v_mfma_f32_16x16x32_bf16 v[96:99], v[178:181], v[194:197], 0
	v_mfma_f32_16x16x32_bf16 v[84:87], v[170:173], v[202:205], 0
	v_mfma_f32_16x16x32_bf16 v[80:83], v[178:181], v[202:205], 0
	v_mfma_f32_16x16x32_bf16 v[68:71], v[170:173], v[212:215], 0
	v_mfma_f32_16x16x32_bf16 v[64:67], v[178:181], v[212:215], 0
	v_mfma_f32_16x16x32_bf16 v[116:119], v[174:177], v[190:193], v[116:119]
	v_mfma_f32_16x16x32_bf16 v[112:115], v[182:185], v[190:193], v[112:115]
	v_mfma_f32_16x16x32_bf16 v[100:103], v[174:177], v[198:201], v[100:103]
	v_mfma_f32_16x16x32_bf16 v[96:99], v[182:185], v[198:201], v[96:99]
	v_mfma_f32_16x16x32_bf16 v[84:87], v[174:177], v[206:209], v[84:87]
	v_mfma_f32_16x16x32_bf16 v[80:83], v[182:185], v[206:209], v[80:83]
	v_mfma_f32_16x16x32_bf16 v[68:71], v[174:177], v[216:219], v[68:71]
	v_mfma_f32_16x16x32_bf16 v[64:67], v[182:185], v[216:219], v[64:67]
	s_setprio 0
	s_barrier
	s_add_i32 s26, s71, s64
	s_mov_b32 m0, s26
	ds_read_b128 v[186:189], v155 offset:16384
	ds_read_b128 v[190:193], v155 offset:17408
	ds_read_b128 v[194:197], v155 offset:18432
	ds_read_b128 v[198:201], v155 offset:19456
	ds_read_b128 v[202:205], v155 offset:20480
	ds_read_b128 v[206:209], v155 offset:21504
	ds_read_b128 v[212:215], v155 offset:22528
	ds_read_b128 v[216:219], v155 offset:23552
	global_load_lds_dwordx4 v130, s[58:59]
	s_add_i32 m0, s26, 0x2000
	s_add_u32 s26, s58, 0x80000
	s_addc_u32 s27, s59, 0
	s_add_i32 s33, s72, s64
	global_load_lds_dwordx4 v134, s[58:59]
	s_mov_b32 m0, s33
	s_nop 0
	global_load_lds_dwordx4 v130, s[26:27]
	s_add_i32 m0, s33, 0x2000
	s_nop 0
	global_load_lds_dwordx4 v134, s[26:27]
	s_mov_b32 m0, s55
	s_nop 0
	global_load_lds_dwordx4 v128, s[60:61]
	s_mov_b32 m0, s65
	s_nop 0
	global_load_lds_dwordx4 v132, s[60:61]
	s_waitcnt vmcnt(8)
	s_waitcnt lgkmcnt(0)
	s_barrier
; #define PG8_STAGE(bufoff, gbase, voff) do { _Pragma("unroll") for (int _i = 0; _i < 2; ++_i) \
;         __builtin_amdgcn_global_load_lds((const unsigned*)((const char*)(gbase) + (voff)[_i]), (PG8_LAS unsigned*)(lds + (bufoff) + ldsw + _i * 8192), 16, 0, 0); } while (0)
; #define PG8_LDA(dst, b, h) do { _Pragma("unroll") for (int m = 0; m < 4; ++m) _Pragma("unroll") for (int k = 0; k < 2; ++k) dst[m][k] = *(const PG8_LAS bf16x8*)(lds + PG8_SA(b, h) + aoff + m * 2048 + k * 1024); } while (0)
; #define PG8_LDB(dst, b, h) do { _Pragma("unroll") for (int n = 0; n < 2; ++n) _Pragma("unroll") for (int k = 0; k < 2; ++k) dst[n][k] = *(const PG8_LAS bf16x8*)(lds + PG8_SB(b, h) + boff + n * 2048 + k * 1024); } while (0)
; #define PG8_MMA(ai, bj, At, Bt) do { __builtin_amdgcn_s_setprio(1); _Pragma("unroll") for (int m = 0; m < 4; ++m) _Pragma("unroll") for (int n = 0; n < 2; ++n) _Pragma("unroll") for (int k = 0; k < 2; ++k) \
;         acc[ai][bj][m][n] = __builtin_amdgcn_mfma_f32_16x16x32_bf16(Bt[n][k], At[m][k], acc[ai][bj][m][n], 0, 0, 0); __builtin_amdgcn_s_setprio(0); } while (0)
; #define PG8_WAIT_V(n) asm volatile("s_waitcnt vmcnt(" #n ")" ::: "memory")
; #define PG8_WAIT_L(n) asm volatile("s_waitcnt lgkmcnt(" #n ")" ::: "memory")
; #define PG8_BAR __builtin_amdgcn_s_barrier()
; #define PG8_SCHED __builtin_amdgcn_sched_barrier(0)
; template <class Epi, class Sched, bool ALIGN_EPI = false, bool SP2 = false>
; __device__ __forceinline__ void gemm_phase(PG8_LAS unsigned char* lds, const Gemm g, const Sched& S, const Epi& E, int tid_in) {
;     ...
;             PG8_WAIT_V(8); PG8_WAIT_L(0); PG8_BAR; PG8_MMA(1, 0, At, B0); PG8_MMA(1, 1, At, B1); PG8_BAR; PG8_SCHED;
;             PG8_LDB(B0, 1, 0); PG8_LDB(B1, 1, 1); PG8_SCHED; PG8_LDA(At, 1, 0); PG8_STAGE(PG8_SA(0, 1), a2 + hstep, voffA);
;             PG8_WAIT_V(8); PG8_WAIT_L(0); PG8_BAR; PG8_MMA(0, 0, At, B0); PG8_MMA(0, 1, At, B1); PG8_BAR; PG8_SCHED;
	s_setprio 1
	s_waitcnt lgkmcnt(0)
	v_mfma_f32_16x16x32_bf16 v[60:63], v[146:149], v[186:189], 0
	v_mfma_f32_16x16x32_bf16 v[56:59], v[162:165], v[186:189], 0
	v_mfma_f32_16x16x32_bf16 v[44:47], v[146:149], v[194:197], 0
	v_mfma_f32_16x16x32_bf16 v[40:43], v[162:165], v[194:197], 0
	v_mfma_f32_16x16x32_bf16 v[28:31], v[146:149], v[202:205], 0
	v_mfma_f32_16x16x32_bf16 v[24:27], v[162:165], v[202:205], 0
	v_mfma_f32_16x16x32_bf16 v[12:15], v[146:149], v[212:215], 0
	v_mfma_f32_16x16x32_bf16 v[8:11], v[162:165], v[212:215], 0
	v_mfma_f32_16x16x32_bf16 v[60:63], v[158:161], v[190:193], v[60:63]
	v_mfma_f32_16x16x32_bf16 v[56:59], v[166:169], v[190:193], v[56:59]
	v_mfma_f32_16x16x32_bf16 v[44:47], v[158:161], v[198:201], v[44:47]
	v_mfma_f32_16x16x32_bf16 v[40:43], v[166:169], v[198:201], v[40:43]
	v_mfma_f32_16x16x32_bf16 v[28:31], v[158:161], v[206:209], v[28:31]
	v_mfma_f32_16x16x32_bf16 v[24:27], v[166:169], v[206:209], v[24:27]
	v_mfma_f32_16x16x32_bf16 v[12:15], v[158:161], v[216:219], v[12:15]
	v_mfma_f32_16x16x32_bf16 v[8:11], v[166:169], v[216:219], v[8:11]
	s_setprio 0
	s_setprio 1
	v_mfma_f32_16x16x32_bf16 v[52:55], v[170:173], v[186:189], 0
	v_mfma_f32_16x16x32_bf16 v[48:51], v[178:181], v[186:189], 0
	v_mfma_f32_16x16x32_bf16 v[36:39], v[170:173], v[194:197], 0
	v_mfma_f32_16x16x32_bf16 v[32:35], v[178:181], v[194:197], 0
	v_mfma_f32_16x16x32_bf16 v[20:23], v[170:173], v[202:205], 0
	v_mfma_f32_16x16x32_bf16 v[16:19], v[178:181], v[202:205], 0
	v_mfma_f32_16x16x32_bf16 v[4:7], v[170:173], v[212:215], 0
	v_mfma_f32_16x16x32_bf16 v[0:3], v[178:181], v[212:215], 0
	v_mfma_f32_16x16x32_bf16 v[52:55], v[174:177], v[190:193], v[52:55]
	v_mfma_f32_16x16x32_bf16 v[48:51], v[182:185], v[190:193], v[48:51]
	v_mfma_f32_16x16x32_bf16 v[36:39], v[174:177], v[198:201], v[36:39]
	v_mfma_f32_16x16x32_bf16 v[32:35], v[182:185], v[198:201], v[32:35]
	v_mfma_f32_16x16x32_bf16 v[20:23], v[174:177], v[206:209], v[20:23]
	v_mfma_f32_16x16x32_bf16 v[16:19], v[182:185], v[206:209], v[16:19]
	v_mfma_f32_16x16x32_bf16 v[4:7], v[174:177], v[216:219], v[4:7]
	v_mfma_f32_16x16x32_bf16 v[0:3], v[182:185], v[216:219], v[0:3]
	s_setprio 0
	s_barrier
	s_add_i32 s33, 0, 0x18000
	s_add_i32 s56, 0, 0x1c000
	v_add_u32_e32 v166, s33, v137
	v_add_u32_e32 v182, s56, v137
	ds_read_b128 v[146:149], v166
	ds_read_b128 v[158:161], v166 offset:1024
	ds_read_b128 v[162:165], v166 offset:2048
	ds_read_b128 v[166:169], v166 offset:3072
	ds_read_b128 v[170:173], v182
	ds_read_b128 v[174:177], v182 offset:1024
	ds_read_b128 v[178:181], v182 offset:2048
	ds_read_b128 v[182:185], v182 offset:3072
	s_add_u32 s26, s60, 0x204000
	s_addc_u32 s27, s61, 0
	s_mov_b32 m0, s66
	ds_read_b128 v[186:189], v155 offset:32768
	ds_read_b128 v[190:193], v155 offset:33792
	ds_read_b128 v[194:197], v155 offset:34816
	ds_read_b128 v[198:201], v155 offset:35840
	ds_read_b128 v[202:205], v155 offset:36864
	ds_read_b128 v[206:209], v155 offset:37888
	ds_read_b128 v[212:215], v155 offset:38912
	ds_read_b128 v[216:219], v155 offset:39936
	global_load_lds_dwordx4 v128, s[26:27]
	s_mov_b32 m0, s67
	s_nop 0
	global_load_lds_dwordx4 v132, s[26:27]
	s_waitcnt vmcnt(8)
	s_waitcnt lgkmcnt(0)
	s_barrier
	s_setprio 1
	s_waitcnt lgkmcnt(0)
	v_mfma_f32_16x16x32_bf16 v[124:127], v[146:149], v[186:189], v[124:127]
	v_mfma_f32_16x16x32_bf16 v[120:123], v[162:165], v[186:189], v[120:123]
	v_mfma_f32_16x16x32_bf16 v[108:111], v[146:149], v[194:197], v[108:111]
	v_mfma_f32_16x16x32_bf16 v[104:107], v[162:165], v[194:197], v[104:107]
	v_mfma_f32_16x16x32_bf16 v[92:95], v[146:149], v[202:205], v[92:95]
	v_mfma_f32_16x16x32_bf16 v[88:91], v[162:165], v[202:205], v[88:91]
	v_mfma_f32_16x16x32_bf16 v[76:79], v[146:149], v[212:215], v[76:79]
	v_mfma_f32_16x16x32_bf16 v[72:75], v[162:165], v[212:215], v[72:75]
	v_mfma_f32_16x16x32_bf16 v[124:127], v[158:161], v[190:193], v[124:127]
	v_mfma_f32_16x16x32_bf16 v[120:123], v[166:169], v[190:193], v[120:123]
	v_mfma_f32_16x16x32_bf16 v[108:111], v[158:161], v[198:201], v[108:111]
	v_mfma_f32_16x16x32_bf16 v[104:107], v[166:169], v[198:201], v[104:107]
	v_mfma_f32_16x16x32_bf16 v[92:95], v[158:161], v[206:209], v[92:95]
	v_mfma_f32_16x16x32_bf16 v[88:91], v[166:169], v[206:209], v[88:91]
	v_mfma_f32_16x16x32_bf16 v[76:79], v[158:161], v[216:219], v[76:79]
	v_mfma_f32_16x16x32_bf16 v[72:75], v[166:169], v[216:219], v[72:75]
	s_setprio 0
	s_setprio 1
	v_mfma_f32_16x16x32_bf16 v[116:119], v[170:173], v[186:189], v[116:119]
	v_mfma_f32_16x16x32_bf16 v[112:115], v[178:181], v[186:189], v[112:115]
	v_mfma_f32_16x16x32_bf16 v[100:103], v[170:173], v[194:197], v[100:103]
	v_mfma_f32_16x16x32_bf16 v[96:99], v[178:181], v[194:197], v[96:99]
	v_mfma_f32_16x16x32_bf16 v[84:87], v[170:173], v[202:205], v[84:87]
	v_mfma_f32_16x16x32_bf16 v[80:83], v[178:181], v[202:205], v[80:83]
	v_mfma_f32_16x16x32_bf16 v[68:71], v[170:173], v[212:215], v[68:71]
	v_mfma_f32_16x16x32_bf16 v[64:67], v[178:181], v[212:215], v[64:67]
	v_mfma_f32_16x16x32_bf16 v[116:119], v[174:177], v[190:193], v[116:119]
	v_mfma_f32_16x16x32_bf16 v[112:115], v[182:185], v[190:193], v[112:115]
	v_mfma_f32_16x16x32_bf16 v[100:103], v[174:177], v[198:201], v[100:103]
	v_mfma_f32_16x16x32_bf16 v[96:99], v[182:185], v[198:201], v[96:99]
	v_mfma_f32_16x16x32_bf16 v[84:87], v[174:177], v[206:209], v[84:87]
	v_mfma_f32_16x16x32_bf16 v[80:83], v[182:185], v[206:209], v[80:83]
	v_mfma_f32_16x16x32_bf16 v[68:71], v[174:177], v[216:219], v[68:71]
	v_mfma_f32_16x16x32_bf16 v[64:67], v[182:185], v[216:219], v[64:67]
	s_setprio 0
	s_barrier
; #define PG8_STAGE(bufoff, gbase, voff) do { _Pragma("unroll") for (int _i = 0; _i < 2; ++_i) \
;         __builtin_amdgcn_global_load_lds((const unsigned*)((const char*)(gbase) + (voff)[_i]), (PG8_LAS unsigned*)(lds + (bufoff) + ldsw + _i * 8192), 16, 0, 0); } while (0)
; #define PG8_LDA(dst, b, h) do { _Pragma("unroll") for (int m = 0; m < 4; ++m) _Pragma("unroll") for (int k = 0; k < 2; ++k) dst[m][k] = *(const PG8_LAS bf16x8*)(lds + PG8_SA(b, h) + aoff + m * 2048 + k * 1024); } while (0)
; #define PG8_MMA(ai, bj, At, Bt) do { __builtin_amdgcn_s_setprio(1); _Pragma("unroll") for (int m = 0; m < 4; ++m) _Pragma("unroll") for (int n = 0; n < 2; ++n) _Pragma("unroll") for (int k = 0; k < 2; ++k) \
;         acc[ai][bj][m][n] = __builtin_amdgcn_mfma_f32_16x16x32_bf16(Bt[n][k], At[m][k], acc[ai][bj][m][n], 0, 0, 0); __builtin_amdgcn_s_setprio(0); } while (0)
; #define PG8_WAIT_V(n) asm volatile("s_waitcnt vmcnt(" #n ")" ::: "memory")
; #define PG8_WAIT_L(n) asm volatile("s_waitcnt lgkmcnt(" #n ")" ::: "memory")
; #define PG8_BAR __builtin_amdgcn_s_barrier()
; #define PG8_SCHED __builtin_amdgcn_sched_barrier(0)
; template <class Epi, class Sched, bool ALIGN_EPI = false, bool SP2 = false>
; __device__ __forceinline__ void gemm_phase(PG8_LAS unsigned char* lds, const Gemm g, const Sched& S, const Epi& E, int tid_in) {
;     ...
;         for (int t = 0; t < nt; t += 2) {
;             const bool last = (t == nt - 2);
;     ...
;             PG8_LDA(At, 1, 1); PG8_STAGE(PG8_SB(1, 0), b3, voffB); PG8_STAGE(PG8_SB(1, 1), b3 + hstepB, voffB); PG8_STAGE(PG8_SA(1, 0), a3, voffA);
;             PG8_WAIT_V(8); PG8_WAIT_L(0); PG8_BAR; PG8_MMA(1, 0, At, B0); PG8_MMA(1, 1, At, B1); PG8_BAR; PG8_SCHED;
	s_add_i32 s26, s33, s64
	s_add_i32 m0, s26, 0xffffff80
	ds_read_b128 v[186:189], v155 offset:49152
	ds_read_b128 v[190:193], v155 offset:50176
	ds_read_b128 v[194:197], v155 offset:51200
	ds_read_b128 v[198:201], v155 offset:52224
	ds_read_b128 v[202:205], v155 offset:53248
	ds_read_b128 v[206:209], v155 offset:54272
	ds_read_b128 v[212:215], v155 offset:55296
	ds_read_b128 v[216:219], v155 offset:56320
	global_load_lds_dwordx4 v130, s[58:59] offset:128
	s_add_i32 m0, s26, 0x1f80
	s_add_u32 s26, s58, 0x80080
	s_addc_u32 s27, s59, 0
	s_add_i32 s33, s56, s64
	global_load_lds_dwordx4 v134, s[58:59] offset:128
	s_mov_b32 m0, s33
	s_nop 0
	global_load_lds_dwordx4 v130, s[26:27]
	s_add_i32 m0, s33, 0x2000
	s_nop 0
	global_load_lds_dwordx4 v134, s[26:27]
	s_add_i32 m0, s69, 0xffffff80
	s_nop 0
	global_load_lds_dwordx4 v128, s[60:61] offset:128
	s_add_i32 m0, s70, 0xffffff80
	s_nop 0
	global_load_lds_dwordx4 v132, s[60:61] offset:128
	s_waitcnt vmcnt(8)
	s_waitcnt lgkmcnt(0)
	s_barrier
	s_setprio 1
	s_waitcnt lgkmcnt(0)
	v_mfma_f32_16x16x32_bf16 v[60:63], v[146:149], v[186:189], v[60:63]
	v_mfma_f32_16x16x32_bf16 v[56:59], v[162:165], v[186:189], v[56:59]
	v_mfma_f32_16x16x32_bf16 v[44:47], v[146:149], v[194:197], v[44:47]
	v_mfma_f32_16x16x32_bf16 v[40:43], v[162:165], v[194:197], v[40:43]
	v_mfma_f32_16x16x32_bf16 v[28:31], v[146:149], v[202:205], v[28:31]
	v_mfma_f32_16x16x32_bf16 v[24:27], v[162:165], v[202:205], v[24:27]
	v_mfma_f32_16x16x32_bf16 v[12:15], v[146:149], v[212:215], v[12:15]
	v_mfma_f32_16x16x32_bf16 v[8:11], v[162:165], v[212:215], v[8:11]
	v_mfma_f32_16x16x32_bf16 v[60:63], v[158:161], v[190:193], v[60:63]
	v_mfma_f32_16x16x32_bf16 v[56:59], v[166:169], v[190:193], v[56:59]
	v_mfma_f32_16x16x32_bf16 v[44:47], v[158:161], v[198:201], v[44:47]
	v_mfma_f32_16x16x32_bf16 v[40:43], v[166:169], v[198:201], v[40:43]
	v_mfma_f32_16x16x32_bf16 v[28:31], v[158:161], v[206:209], v[28:31]
	v_mfma_f32_16x16x32_bf16 v[24:27], v[166:169], v[206:209], v[24:27]
	v_mfma_f32_16x16x32_bf16 v[12:15], v[158:161], v[216:219], v[12:15]
	v_mfma_f32_16x16x32_bf16 v[8:11], v[166:169], v[216:219], v[8:11]
	s_setprio 0
	s_setprio 1
	v_mfma_f32_16x16x32_bf16 v[52:55], v[170:173], v[186:189], v[52:55]
	v_mfma_f32_16x16x32_bf16 v[48:51], v[178:181], v[186:189], v[48:51]
	v_mfma_f32_16x16x32_bf16 v[36:39], v[170:173], v[194:197], v[36:39]
	v_mfma_f32_16x16x32_bf16 v[32:35], v[178:181], v[194:197], v[32:35]
	v_mfma_f32_16x16x32_bf16 v[20:23], v[170:173], v[202:205], v[20:23]
	v_mfma_f32_16x16x32_bf16 v[16:19], v[178:181], v[202:205], v[16:19]
	v_mfma_f32_16x16x32_bf16 v[4:7], v[170:173], v[212:215], v[4:7]
	v_mfma_f32_16x16x32_bf16 v[0:3], v[178:181], v[212:215], v[0:3]
	v_mfma_f32_16x16x32_bf16 v[52:55], v[174:177], v[190:193], v[52:55]
	v_mfma_f32_16x16x32_bf16 v[48:51], v[182:185], v[190:193], v[48:51]
	v_mfma_f32_16x16x32_bf16 v[36:39], v[174:177], v[198:201], v[36:39]
	v_mfma_f32_16x16x32_bf16 v[32:35], v[182:185], v[198:201], v[32:35]
	v_mfma_f32_16x16x32_bf16 v[20:23], v[174:177], v[206:209], v[20:23]
	v_mfma_f32_16x16x32_bf16 v[16:19], v[182:185], v[206:209], v[16:19]
	v_mfma_f32_16x16x32_bf16 v[4:7], v[174:177], v[216:219], v[4:7]
	v_mfma_f32_16x16x32_bf16 v[0:3], v[182:185], v[216:219], v[0:3]
	s_setprio 0
	s_barrier
	s_add_i32 s79, s79, 2
	s_add_u32 s76, s76, 0x100
	s_addc_u32 s77, s77, 0
	s_cmpk_gt_u32 s79, 0x7d
	s_mov_b64 s[56:57], s[12:13]

; #define PG8_STAGE(bufoff, gbase, voff) do { _Pragma("unroll") for (int _i = 0; _i < 2; ++_i) \
;         __builtin_amdgcn_global_load_lds((const unsigned*)((const char*)(gbase) + (voff)[_i]), (PG8_LAS unsigned*)(lds + (bufoff) + ldsw + _i * 8192), 16, 0, 0); } while (0)
; #define PG8_LDA(dst, b, h) do { _Pragma("unroll") for (int m = 0; m < 4; ++m) _Pragma("unroll") for (int k = 0; k < 2; ++k) dst[m][k] = *(const PG8_LAS bf16x8*)(lds + PG8_SA(b, h) + aoff + m * 2048 + k * 1024); } while (0)
; #define PG8_LDB(dst, b, h) do { _Pragma("unroll") for (int n = 0; n < 2; ++n) _Pragma("unroll") for (int k = 0; k < 2; ++k) dst[n][k] = *(const PG8_LAS bf16x8*)(lds + PG8_SB(b, h) + boff + n * 2048 + k * 1024); } while (0)
; #define PG8_MMA(ai, bj, At, Bt) do { __builtin_amdgcn_s_setprio(1); _Pragma("unroll") for (int m = 0; m < 4; ++m) _Pragma("unroll") for (int n = 0; n < 2; ++n) _Pragma("unroll") for (int k = 0; k < 2; ++k) \
;         acc[ai][bj][m][n] = __builtin_amdgcn_mfma_f32_16x16x32_bf16(Bt[n][k], At[m][k], acc[ai][bj][m][n], 0, 0, 0); __builtin_amdgcn_s_setprio(0); } while (0)
; #define PG8_WAIT_V(n) asm volatile("s_waitcnt vmcnt(" #n ")" ::: "memory")
; #define PG8_WAIT_L(n) asm volatile("s_waitcnt lgkmcnt(" #n ")" ::: "memory")
; #define PG8_BAR __builtin_amdgcn_s_barrier()
; #define PG8_SCHED __builtin_amdgcn_sched_barrier(0)
; template <class Epi, class Sched, bool ALIGN_EPI = false, bool SP2 = false>
; __device__ __forceinline__ void gemm_phase(PG8_LAS unsigned char* lds, const Gemm g, const Sched& S, const Epi& E, int tid_in) {
;     ...
;     f32x4 acc[2][2][4][2];
; #pragma unroll
;     for (int a = 0; a < 2; ++a)
; #pragma unroll
;         for (int b = 0; b < 2; ++b)
; #pragma unroll
;             for (int m = 0; m < 4; ++m)
; #pragma unroll
;                 for (int n = 0; n < 2; ++n) acc[a][b][m][n] = (f32x4){0.f, 0.f, 0.f, 0.f};
;     ...
;             PG8_LDB(B0, 0, 0); PG8_LDB(B1, 0, 1); PG8_SCHED; PG8_LDA(At, 0, 0); PG8_STAGE(PG8_SA(1, 1), a1 + hstep, voffA);
;             PG8_WAIT_V(8); PG8_WAIT_L(0); PG8_BAR; PG8_MMA(0, 0, At, B0); PG8_MMA(0, 1, At, B1); PG8_BAR; PG8_SCHED;
;             PG8_LDA(At, 0, 1); PG8_STAGE(PG8_SB(0, 0), b2, voffB); PG8_STAGE(PG8_SB(0, 1), b2 + hstepB, voffB); PG8_STAGE(PG8_SA(0, 0), a2, voffA);
.LBB0_596:
	s_ashr_i32 s53, s52, 31
	s_lshl_b64 s[26:27], s[52:53], 20
	s_add_u32 s54, s28, s26
	s_addc_u32 s55, s29, s27
	s_and_b64 s[26:27], s[8:9], exec
	s_cselect_b32 s11, s55, s61
	s_cselect_b32 s53, s54, s60
	s_ashr_i32 s51, s50, 31
	s_lshl_b64 s[26:27], s[50:51], 20
	s_add_u32 s56, s66, s26
	s_addc_u32 s57, s67, s27
	s_and_b64 s[26:27], s[8:9], exec
	s_cselect_b32 s51, s57, s63
	s_cselect_b32 s85, s56, s62
	s_add_u32 s60, s60, 0x80080
	s_addc_u32 s61, s61, 0
	s_add_u32 s86, s62, 0x100
	s_addc_u32 s87, s63, 0
	s_mov_b32 s88, -2
	s_waitcnt vmcnt(0)
	s_cmp_eq_u32 s98, 1
	s_cbranch_scc0 .Lkb_skip_4
	s_mov_b32 s98, 0
	s_barrier
.Lkb_skip_4:
	ds_read_b128 v[128:131], v171
	ds_read_b128 v[132:135], v171 offset:1024
	ds_read_b128 v[136:139], v171 offset:2048
	ds_read_b128 v[184:187], v171 offset:3072
	ds_read_b128 v[188:191], v172
	ds_read_b128 v[192:195], v172 offset:1024
	ds_read_b128 v[196:199], v172 offset:2048
	ds_read_b128 v[200:203], v172 offset:3072
	s_add_u32 s26, s60, 0xfff80080
	s_addc_u32 s27, s61, -1
	s_cmp_eq_u32 s88, 28
	s_cselect_b32 s65, s11, s27
	s_cselect_b32 s64, s53, s26
	s_cselect_b32 s63, s51, s87
	s_cselect_b32 s62, s85, s86
	s_add_i32 m0, s59, 0xc000
	ds_read_b128 v[204:207], v173
	ds_read_b128 v[212:215], v173 offset:1024
	ds_read_b128 v[216:219], v173 offset:2048
	ds_read_b128 v[220:223], v173 offset:3072
	ds_read_b128 v[224:227], v173 offset:4096
	ds_read_b128 v[228:231], v173 offset:5120
	ds_read_b128 v[232:235], v173 offset:6144
	ds_read_b128 v[236:239], v173 offset:7168
	global_load_lds_dwordx4 v158, s[60:61]
	s_add_i32 m0, s59, 0xe000
	s_nop 0
	global_load_lds_dwordx4 v160, s[60:61]
	s_waitcnt vmcnt(8)
	s_waitcnt lgkmcnt(0)
	s_barrier
	s_setprio 1
	s_waitcnt lgkmcnt(0)
	v_mfma_f32_16x16x32_bf16 v[124:127], v[128:131], v[204:207], 0
	v_mfma_f32_16x16x32_bf16 v[120:123], v[136:139], v[204:207], 0
	v_mfma_f32_16x16x32_bf16 v[108:111], v[128:131], v[216:219], 0
	v_mfma_f32_16x16x32_bf16 v[104:107], v[136:139], v[216:219], 0
	v_mfma_f32_16x16x32_bf16 v[92:95], v[128:131], v[224:227], 0
	v_mfma_f32_16x16x32_bf16 v[88:91], v[136:139], v[224:227], 0
	v_mfma_f32_16x16x32_bf16 v[76:79], v[128:131], v[232:235], 0
	v_mfma_f32_16x16x32_bf16 v[72:75], v[136:139], v[232:235], 0
	v_mfma_f32_16x16x32_bf16 v[124:127], v[132:135], v[212:215], v[124:127]
	v_mfma_f32_16x16x32_bf16 v[120:123], v[184:187], v[212:215], v[120:123]
	v_mfma_f32_16x16x32_bf16 v[108:111], v[132:135], v[220:223], v[108:111]
	v_mfma_f32_16x16x32_bf16 v[104:107], v[184:187], v[220:223], v[104:107]
	v_mfma_f32_16x16x32_bf16 v[92:95], v[132:135], v[228:231], v[92:95]
	v_mfma_f32_16x16x32_bf16 v[88:91], v[184:187], v[228:231], v[88:91]
	v_mfma_f32_16x16x32_bf16 v[76:79], v[132:135], v[236:239], v[76:79]
	v_mfma_f32_16x16x32_bf16 v[72:75], v[184:187], v[236:239], v[72:75]
	s_setprio 0
	s_setprio 1
	v_mfma_f32_16x16x32_bf16 v[116:119], v[188:191], v[204:207], 0
	v_mfma_f32_16x16x32_bf16 v[112:115], v[196:199], v[204:207], 0
	v_mfma_f32_16x16x32_bf16 v[100:103], v[188:191], v[216:219], 0
	v_mfma_f32_16x16x32_bf16 v[96:99], v[196:199], v[216:219], 0
	v_mfma_f32_16x16x32_bf16 v[84:87], v[188:191], v[224:227], 0
	v_mfma_f32_16x16x32_bf16 v[80:83], v[196:199], v[224:227], 0
	v_mfma_f32_16x16x32_bf16 v[68:71], v[188:191], v[232:235], 0
	v_mfma_f32_16x16x32_bf16 v[64:67], v[196:199], v[232:235], 0
	v_mfma_f32_16x16x32_bf16 v[116:119], v[192:195], v[212:215], v[116:119]
	v_mfma_f32_16x16x32_bf16 v[112:115], v[200:203], v[212:215], v[112:115]
	v_mfma_f32_16x16x32_bf16 v[100:103], v[192:195], v[220:223], v[100:103]
	v_mfma_f32_16x16x32_bf16 v[96:99], v[200:203], v[220:223], v[96:99]
	v_mfma_f32_16x16x32_bf16 v[84:87], v[192:195], v[228:231], v[84:87]
	v_mfma_f32_16x16x32_bf16 v[80:83], v[200:203], v[228:231], v[80:83]
	v_mfma_f32_16x16x32_bf16 v[68:71], v[192:195], v[236:239], v[68:71]
	v_mfma_f32_16x16x32_bf16 v[64:67], v[200:203], v[236:239], v[64:67]
	s_setprio 0
	s_barrier
	s_add_i32 s26, s78, s68
	s_mov_b32 m0, s26
	ds_read_b128 v[204:207], v173 offset:16384
	ds_read_b128 v[212:215], v173 offset:17408
	ds_read_b128 v[216:219], v173 offset:18432
	ds_read_b128 v[220:223], v173 offset:19456
	ds_read_b128 v[224:227], v173 offset:20480
	ds_read_b128 v[228:231], v173 offset:21504
	ds_read_b128 v[232:235], v173 offset:22528
	ds_read_b128 v[236:239], v173 offset:23552
	global_load_lds_dwordx4 v144, s[62:63]
	s_add_i32 m0, s26, 0x2000
	s_add_u32 s26, s62, 0x20000
	s_addc_u32 s27, s63, 0
	s_add_i32 s33, s79, s68
	global_load_lds_dwordx4 v148, s[62:63]
	s_mov_b32 m0, s33
	s_nop 0
	global_load_lds_dwordx4 v144, s[26:27]
	s_add_i32 m0, s33, 0x2000
	s_nop 0
	global_load_lds_dwordx4 v148, s[26:27]
	s_mov_b32 m0, s59
	s_nop 0
	global_load_lds_dwordx4 v142, s[64:65]
	s_mov_b32 m0, s69
	s_nop 0
	global_load_lds_dwordx4 v146, s[64:65]
	s_waitcnt vmcnt(8)
	s_waitcnt lgkmcnt(0)
	s_barrier
; #define PG8_STAGE(bufoff, gbase, voff) do { _Pragma("unroll") for (int _i = 0; _i < 2; ++_i) \
;         __builtin_amdgcn_global_load_lds((const unsigned*)((const char*)(gbase) + (voff)[_i]), (PG8_LAS unsigned*)(lds + (bufoff) + ldsw + _i * 8192), 16, 0, 0); } while (0)
; #define PG8_LDA(dst, b, h) do { _Pragma("unroll") for (int m = 0; m < 4; ++m) _Pragma("unroll") for (int k = 0; k < 2; ++k) dst[m][k] = *(const PG8_LAS bf16x8*)(lds + PG8_SA(b, h) + aoff + m * 2048 + k * 1024); } while (0)
; #define PG8_LDB(dst, b, h) do { _Pragma("unroll") for (int n = 0; n < 2; ++n) _Pragma("unroll") for (int k = 0; k < 2; ++k) dst[n][k] = *(const PG8_LAS bf16x8*)(lds + PG8_SB(b, h) + boff + n * 2048 + k * 1024); } while (0)
; #define PG8_MMA(ai, bj, At, Bt) do { __builtin_amdgcn_s_setprio(1); _Pragma("unroll") for (int m = 0; m < 4; ++m) _Pragma("unroll") for (int n = 0; n < 2; ++n) _Pragma("unroll") for (int k = 0; k < 2; ++k) \
;         acc[ai][bj][m][n] = __builtin_amdgcn_mfma_f32_16x16x32_bf16(Bt[n][k], At[m][k], acc[ai][bj][m][n], 0, 0, 0); __builtin_amdgcn_s_setprio(0); } while (0)
; #define PG8_WAIT_V(n) asm volatile("s_waitcnt vmcnt(" #n ")" ::: "memory")
; #define PG8_WAIT_L(n) asm volatile("s_waitcnt lgkmcnt(" #n ")" ::: "memory")
; #define PG8_BAR __builtin_amdgcn_s_barrier()
; #define PG8_SCHED __builtin_amdgcn_sched_barrier(0)
; template <class Epi, class Sched, bool ALIGN_EPI = false, bool SP2 = false>
; __device__ __forceinline__ void gemm_phase(PG8_LAS unsigned char* lds, const Gemm g, const Sched& S, const Epi& E, int tid_in) {
;     ...
;             PG8_WAIT_V(8); PG8_WAIT_L(0); PG8_BAR; PG8_MMA(1, 0, At, B0); PG8_MMA(1, 1, At, B1); PG8_BAR; PG8_SCHED;
;             PG8_LDB(B0, 1, 0); PG8_LDB(B1, 1, 1); PG8_SCHED; PG8_LDA(At, 1, 0); PG8_STAGE(PG8_SA(0, 1), a2 + hstep, voffA);
;             PG8_WAIT_V(8); PG8_WAIT_L(0); PG8_BAR; PG8_MMA(0, 0, At, B0); PG8_MMA(0, 1, At, B1); PG8_BAR; PG8_SCHED;
	s_setprio 1
	s_waitcnt lgkmcnt(0)
	v_mfma_f32_16x16x32_bf16 v[60:63], v[128:131], v[204:207], 0
	v_mfma_f32_16x16x32_bf16 v[56:59], v[136:139], v[204:207], 0
	v_mfma_f32_16x16x32_bf16 v[44:47], v[128:131], v[216:219], 0
	v_mfma_f32_16x16x32_bf16 v[40:43], v[136:139], v[216:219], 0
	v_mfma_f32_16x16x32_bf16 v[28:31], v[128:131], v[224:227], 0
	v_mfma_f32_16x16x32_bf16 v[24:27], v[136:139], v[224:227], 0
	v_mfma_f32_16x16x32_bf16 v[12:15], v[128:131], v[232:235], 0
	v_mfma_f32_16x16x32_bf16 v[8:11], v[136:139], v[232:235], 0
	v_mfma_f32_16x16x32_bf16 v[60:63], v[132:135], v[212:215], v[60:63]
	v_mfma_f32_16x16x32_bf16 v[56:59], v[184:187], v[212:215], v[56:59]
	v_mfma_f32_16x16x32_bf16 v[44:47], v[132:135], v[220:223], v[44:47]
	v_mfma_f32_16x16x32_bf16 v[40:43], v[184:187], v[220:223], v[40:43]
	v_mfma_f32_16x16x32_bf16 v[28:31], v[132:135], v[228:231], v[28:31]
	v_mfma_f32_16x16x32_bf16 v[24:27], v[184:187], v[228:231], v[24:27]
	v_mfma_f32_16x16x32_bf16 v[12:15], v[132:135], v[236:239], v[12:15]
	v_mfma_f32_16x16x32_bf16 v[8:11], v[184:187], v[236:239], v[8:11]
	s_setprio 0
	s_setprio 1
	v_mfma_f32_16x16x32_bf16 v[52:55], v[188:191], v[204:207], 0
	v_mfma_f32_16x16x32_bf16 v[48:51], v[196:199], v[204:207], 0
	v_mfma_f32_16x16x32_bf16 v[36:39], v[188:191], v[216:219], 0
	v_mfma_f32_16x16x32_bf16 v[32:35], v[196:199], v[216:219], 0
	v_mfma_f32_16x16x32_bf16 v[20:23], v[188:191], v[224:227], 0
	v_mfma_f32_16x16x32_bf16 v[16:19], v[196:199], v[224:227], 0
	v_mfma_f32_16x16x32_bf16 v[4:7], v[188:191], v[232:235], 0
	v_mfma_f32_16x16x32_bf16 v[0:3], v[196:199], v[232:235], 0
	v_mfma_f32_16x16x32_bf16 v[52:55], v[192:195], v[212:215], v[52:55]
	v_mfma_f32_16x16x32_bf16 v[48:51], v[200:203], v[212:215], v[48:51]
	v_mfma_f32_16x16x32_bf16 v[36:39], v[192:195], v[220:223], v[36:39]
	v_mfma_f32_16x16x32_bf16 v[32:35], v[200:203], v[220:223], v[32:35]
	v_mfma_f32_16x16x32_bf16 v[20:23], v[192:195], v[228:231], v[20:23]
	v_mfma_f32_16x16x32_bf16 v[16:19], v[200:203], v[228:231], v[16:19]
	v_mfma_f32_16x16x32_bf16 v[4:7], v[192:195], v[236:239], v[4:7]
	v_mfma_f32_16x16x32_bf16 v[0:3], v[200:203], v[236:239], v[0:3]
	s_setprio 0
	s_barrier
	s_add_i32 s33, 0, 0x18000
	v_add_u32_e32 v150, s33, v167
	s_add_i32 s89, 0, 0x1c000
	ds_read_b128 v[128:131], v150
	ds_read_b128 v[132:135], v150 offset:1024
	ds_read_b128 v[136:139], v150 offset:2048
	ds_read_b128 v[184:187], v150 offset:3072
	v_add_u32_e32 v150, s89, v167
	ds_read_b128 v[188:191], v150
	ds_read_b128 v[192:195], v150 offset:1024
	ds_read_b128 v[196:199], v150 offset:2048
	ds_read_b128 v[200:203], v150 offset:3072
	s_add_u32 s26, s64, 0x80000
	s_addc_u32 s27, s65, 0
	s_mov_b32 m0, s70
	ds_read_b128 v[204:207], v173 offset:32768
	ds_read_b128 v[212:215], v173 offset:33792
	ds_read_b128 v[216:219], v173 offset:34816
	ds_read_b128 v[220:223], v173 offset:35840
	ds_read_b128 v[224:227], v173 offset:36864
	ds_read_b128 v[228:231], v173 offset:37888
	ds_read_b128 v[232:235], v173 offset:38912
	ds_read_b128 v[236:239], v173 offset:39936
	global_load_lds_dwordx4 v142, s[26:27]
	s_mov_b32 m0, s71
	s_nop 0
	global_load_lds_dwordx4 v146, s[26:27]
	s_waitcnt vmcnt(8)
	s_waitcnt lgkmcnt(0)
	s_barrier
	s_setprio 1
	s_waitcnt lgkmcnt(0)
	v_mfma_f32_16x16x32_bf16 v[124:127], v[128:131], v[204:207], v[124:127]
	v_mfma_f32_16x16x32_bf16 v[120:123], v[136:139], v[204:207], v[120:123]
	v_mfma_f32_16x16x32_bf16 v[108:111], v[128:131], v[216:219], v[108:111]
	v_mfma_f32_16x16x32_bf16 v[104:107], v[136:139], v[216:219], v[104:107]
	v_mfma_f32_16x16x32_bf16 v[92:95], v[128:131], v[224:227], v[92:95]
	v_mfma_f32_16x16x32_bf16 v[88:91], v[136:139], v[224:227], v[88:91]
	v_mfma_f32_16x16x32_bf16 v[76:79], v[128:131], v[232:235], v[76:79]
	v_mfma_f32_16x16x32_bf16 v[72:75], v[136:139], v[232:235], v[72:75]
	v_mfma_f32_16x16x32_bf16 v[124:127], v[132:135], v[212:215], v[124:127]
	v_mfma_f32_16x16x32_bf16 v[120:123], v[184:187], v[212:215], v[120:123]
	v_mfma_f32_16x16x32_bf16 v[108:111], v[132:135], v[220:223], v[108:111]
	v_mfma_f32_16x16x32_bf16 v[104:107], v[184:187], v[220:223], v[104:107]
	v_mfma_f32_16x16x32_bf16 v[92:95], v[132:135], v[228:231], v[92:95]
	v_mfma_f32_16x16x32_bf16 v[88:91], v[184:187], v[228:231], v[88:91]
	v_mfma_f32_16x16x32_bf16 v[76:79], v[132:135], v[236:239], v[76:79]
	v_mfma_f32_16x16x32_bf16 v[72:75], v[184:187], v[236:239], v[72:75]
	s_setprio 0
	s_setprio 1
	v_mfma_f32_16x16x32_bf16 v[116:119], v[188:191], v[204:207], v[116:119]
	v_mfma_f32_16x16x32_bf16 v[112:115], v[196:199], v[204:207], v[112:115]
	v_mfma_f32_16x16x32_bf16 v[100:103], v[188:191], v[216:219], v[100:103]
	v_mfma_f32_16x16x32_bf16 v[96:99], v[196:199], v[216:219], v[96:99]
	v_mfma_f32_16x16x32_bf16 v[84:87], v[188:191], v[224:227], v[84:87]
	v_mfma_f32_16x16x32_bf16 v[80:83], v[196:199], v[224:227], v[80:83]
	v_mfma_f32_16x16x32_bf16 v[68:71], v[188:191], v[232:235], v[68:71]
	v_mfma_f32_16x16x32_bf16 v[64:67], v[196:199], v[232:235], v[64:67]
	v_mfma_f32_16x16x32_bf16 v[116:119], v[192:195], v[212:215], v[116:119]
	v_mfma_f32_16x16x32_bf16 v[112:115], v[200:203], v[212:215], v[112:115]
	v_mfma_f32_16x16x32_bf16 v[100:103], v[192:195], v[220:223], v[100:103]
	v_mfma_f32_16x16x32_bf16 v[96:99], v[200:203], v[220:223], v[96:99]
	v_mfma_f32_16x16x32_bf16 v[84:87], v[192:195], v[228:231], v[84:87]
	v_mfma_f32_16x16x32_bf16 v[80:83], v[200:203], v[228:231], v[80:83]
	v_mfma_f32_16x16x32_bf16 v[68:71], v[192:195], v[236:239], v[68:71]
	v_mfma_f32_16x16x32_bf16 v[64:67], v[200:203], v[236:239], v[64:67]
	s_setprio 0
	s_barrier
; #define PG8_STAGE(bufoff, gbase, voff) do { _Pragma("unroll") for (int _i = 0; _i < 2; ++_i) \
;         __builtin_amdgcn_global_load_lds((const unsigned*)((const char*)(gbase) + (voff)[_i]), (PG8_LAS unsigned*)(lds + (bufoff) + ldsw + _i * 8192), 16, 0, 0); } while (0)
; #define PG8_LDA(dst, b, h) do { _Pragma("unroll") for (int m = 0; m < 4; ++m) _Pragma("unroll") for (int k = 0; k < 2; ++k) dst[m][k] = *(const PG8_LAS bf16x8*)(lds + PG8_SA(b, h) + aoff + m * 2048 + k * 1024); } while (0)
; #define PG8_MMA(ai, bj, At, Bt) do { __builtin_amdgcn_s_setprio(1); _Pragma("unroll") for (int m = 0; m < 4; ++m) _Pragma("unroll") for (int n = 0; n < 2; ++n) _Pragma("unroll") for (int k = 0; k < 2; ++k) \
;         acc[ai][bj][m][n] = __builtin_amdgcn_mfma_f32_16x16x32_bf16(Bt[n][k], At[m][k], acc[ai][bj][m][n], 0, 0, 0); __builtin_amdgcn_s_setprio(0); } while (0)
; #define PG8_WAIT_V(n) asm volatile("s_waitcnt vmcnt(" #n ")" ::: "memory")
; #define PG8_WAIT_L(n) asm volatile("s_waitcnt lgkmcnt(" #n ")" ::: "memory")
; #define PG8_BAR __builtin_amdgcn_s_barrier()
; #define PG8_SCHED __builtin_amdgcn_sched_barrier(0)
; template <class Epi, class Sched, bool ALIGN_EPI = false, bool SP2 = false>
; __device__ __forceinline__ void gemm_phase(PG8_LAS unsigned char* lds, const Gemm g, const Sched& S, const Epi& E, int tid_in) {
;     ...
;         for (int t = 0; t < nt; t += 2) {
;             const bool last = (t == nt - 2);
;     ...
;             PG8_LDA(At, 1, 1); PG8_STAGE(PG8_SB(1, 0), b3, voffB); PG8_STAGE(PG8_SB(1, 1), b3 + hstepB, voffB); PG8_STAGE(PG8_SA(1, 0), a3, voffA);
;             PG8_WAIT_V(8); PG8_WAIT_L(0); PG8_BAR; PG8_MMA(1, 0, At, B0); PG8_MMA(1, 1, At, B1); PG8_BAR; PG8_SCHED;
	s_add_i32 s26, s33, s68
	s_add_i32 m0, s26, 0xffffff80
	ds_read_b128 v[204:207], v173 offset:49152
	ds_read_b128 v[212:215], v173 offset:50176
	ds_read_b128 v[216:219], v173 offset:51200
	ds_read_b128 v[220:223], v173 offset:52224
	ds_read_b128 v[224:227], v173 offset:53248
	ds_read_b128 v[228:231], v173 offset:54272
	ds_read_b128 v[232:235], v173 offset:55296
	ds_read_b128 v[236:239], v173 offset:56320
	global_load_lds_dwordx4 v144, s[62:63] offset:128
	s_add_i32 m0, s26, 0x1f80
	s_add_u32 s26, s62, 0x20080
	s_addc_u32 s27, s63, 0
	s_add_i32 s33, s89, s68
	global_load_lds_dwordx4 v148, s[62:63] offset:128
	s_mov_b32 m0, s33
	s_nop 0
	global_load_lds_dwordx4 v144, s[26:27]
	s_add_i32 m0, s33, 0x2000
	s_nop 0
	global_load_lds_dwordx4 v148, s[26:27]
	s_add_i32 m0, s74, 0xffffff80
	s_nop 0
	global_load_lds_dwordx4 v142, s[64:65] offset:128
	s_add_i32 m0, s75, 0xffffff80
	s_nop 0
	global_load_lds_dwordx4 v146, s[64:65] offset:128
	s_waitcnt vmcnt(8)
	s_waitcnt lgkmcnt(0)
	s_barrier
	s_setprio 1
	s_waitcnt lgkmcnt(0)
	v_mfma_f32_16x16x32_bf16 v[60:63], v[128:131], v[204:207], v[60:63]
	v_mfma_f32_16x16x32_bf16 v[56:59], v[136:139], v[204:207], v[56:59]
	v_mfma_f32_16x16x32_bf16 v[44:47], v[128:131], v[216:219], v[44:47]
	v_mfma_f32_16x16x32_bf16 v[40:43], v[136:139], v[216:219], v[40:43]
	v_mfma_f32_16x16x32_bf16 v[28:31], v[128:131], v[224:227], v[28:31]
	v_mfma_f32_16x16x32_bf16 v[24:27], v[136:139], v[224:227], v[24:27]
	v_mfma_f32_16x16x32_bf16 v[12:15], v[128:131], v[232:235], v[12:15]
	v_mfma_f32_16x16x32_bf16 v[8:11], v[136:139], v[232:235], v[8:11]
	v_mfma_f32_16x16x32_bf16 v[60:63], v[132:135], v[212:215], v[60:63]
	v_mfma_f32_16x16x32_bf16 v[56:59], v[184:187], v[212:215], v[56:59]
	v_mfma_f32_16x16x32_bf16 v[44:47], v[132:135], v[220:223], v[44:47]
	v_mfma_f32_16x16x32_bf16 v[40:43], v[184:187], v[220:223], v[40:43]
	v_mfma_f32_16x16x32_bf16 v[28:31], v[132:135], v[228:231], v[28:31]
	v_mfma_f32_16x16x32_bf16 v[24:27], v[184:187], v[228:231], v[24:27]
	v_mfma_f32_16x16x32_bf16 v[12:15], v[132:135], v[236:239], v[12:15]
	v_mfma_f32_16x16x32_bf16 v[8:11], v[184:187], v[236:239], v[8:11]
	s_setprio 0
	s_setprio 1
	v_mfma_f32_16x16x32_bf16 v[52:55], v[188:191], v[204:207], v[52:55]
	v_mfma_f32_16x16x32_bf16 v[48:51], v[196:199], v[204:207], v[48:51]
	v_mfma_f32_16x16x32_bf16 v[36:39], v[188:191], v[216:219], v[36:39]
	v_mfma_f32_16x16x32_bf16 v[32:35], v[196:199], v[216:219], v[32:35]
	v_mfma_f32_16x16x32_bf16 v[20:23], v[188:191], v[224:227], v[20:23]
	v_mfma_f32_16x16x32_bf16 v[16:19], v[196:199], v[224:227], v[16:19]
	v_mfma_f32_16x16x32_bf16 v[4:7], v[188:191], v[232:235], v[4:7]
	v_mfma_f32_16x16x32_bf16 v[0:3], v[196:199], v[232:235], v[0:3]
	v_mfma_f32_16x16x32_bf16 v[52:55], v[192:195], v[212:215], v[52:55]
	v_mfma_f32_16x16x32_bf16 v[48:51], v[200:203], v[212:215], v[48:51]
	v_mfma_f32_16x16x32_bf16 v[36:39], v[192:195], v[220:223], v[36:39]
	v_mfma_f32_16x16x32_bf16 v[32:35], v[200:203], v[220:223], v[32:35]
	v_mfma_f32_16x16x32_bf16 v[20:23], v[192:195], v[228:231], v[20:23]
	v_mfma_f32_16x16x32_bf16 v[16:19], v[200:203], v[228:231], v[16:19]
	v_mfma_f32_16x16x32_bf16 v[4:7], v[192:195], v[236:239], v[4:7]
	v_mfma_f32_16x16x32_bf16 v[0:3], v[200:203], v[236:239], v[0:3]
	s_setprio 0
	s_barrier
	s_add_i32 s88, s88, 2
	s_add_u32 s60, s60, 0x100
	s_addc_u32 s61, s61, 0
	s_add_u32 s86, s86, 0x100
	s_addc_u32 s87, s87, 0
	s_cmp_gt_u32 s88, 29

; #define PG8_STAGE(bufoff, gbase, voff) do { _Pragma("unroll") for (int _i = 0; _i < 2; ++_i) \
;         __builtin_amdgcn_global_load_lds((const unsigned*)((const char*)(gbase) + (voff)[_i]), (PG8_LAS unsigned*)(lds + (bufoff) + ldsw + _i * 8192), 16, 0, 0); } while (0)
; #define PG8_LDA(dst, b, h) do { _Pragma("unroll") for (int m = 0; m < 4; ++m) _Pragma("unroll") for (int k = 0; k < 2; ++k) dst[m][k] = *(const PG8_LAS bf16x8*)(lds + PG8_SA(b, h) + aoff + m * 2048 + k * 1024); } while (0)
; #define PG8_LDB(dst, b, h) do { _Pragma("unroll") for (int n = 0; n < 2; ++n) _Pragma("unroll") for (int k = 0; k < 2; ++k) dst[n][k] = *(const PG8_LAS bf16x8*)(lds + PG8_SB(b, h) + boff + n * 2048 + k * 1024); } while (0)
; #define PG8_MMA(ai, bj, At, Bt) do { __builtin_amdgcn_s_setprio(1); _Pragma("unroll") for (int m = 0; m < 4; ++m) _Pragma("unroll") for (int n = 0; n < 2; ++n) _Pragma("unroll") for (int k = 0; k < 2; ++k) \
;         acc[ai][bj][m][n] = __builtin_amdgcn_mfma_f32_16x16x32_bf16(Bt[n][k], At[m][k], acc[ai][bj][m][n], 0, 0, 0); __builtin_amdgcn_s_setprio(0); } while (0)
; #define PG8_WAIT_V(n) asm volatile("s_waitcnt vmcnt(" #n ")" ::: "memory")
; template <class Epi, class Sched, bool ALIGN_EPI = false, bool SP2 = false>
; __device__ __forceinline__ void gemm_phase(PG8_LAS unsigned char* lds, const Gemm g, const Sched& S, const Epi& E, int tid_in) {
;     ...
;         const bool has_next = S.next(ui + 1, nxt);
;         const char* nA = has_next ? (const char*)g.A + (size_t)nxt.pm * tstep : cA; const char* nB = has_next ? (const char*)g.Bt + (size_t)nxt.pn * tstepB : cB;
;         for (int t = 0; t < nt; t += 2) {
;             const bool last = (t == nt - 2);
;             const char* a1 = cA + (size_t)(t + 1) * kstep;
;             const char* a2 = last ? nA : cA + (size_t)(t + 2) * kstep; const char* b2 = last ? nB : cB + (size_t)(t + 2) * kstep;
;     ...
;             PG8_LDB(B0, 0, 0); PG8_LDB(B1, 0, 1); PG8_SCHED; PG8_LDA(At, 0, 0); PG8_STAGE(PG8_SA(1, 1), a1 + hstep, voffA);
;             PG8_WAIT_V(8); PG8_WAIT_L(0); PG8_BAR; PG8_MMA(0, 0, At, B0); PG8_MMA(0, 1, At, B1); PG8_BAR; PG8_SCHED;
;             PG8_LDA(At, 0, 1); PG8_STAGE(PG8_SB(0, 0), b2, voffB); PG8_STAGE(PG8_SB(0, 1), b2 + hstepB, voffB); PG8_STAGE(PG8_SA(0, 0), a2, voffA);
;             PG8_WAIT_V(8); PG8_WAIT_L(0); PG8_BAR; PG8_MMA(1, 0, At, B0); PG8_MMA(1, 1, At, B1); PG8_BAR; PG8_SCHED;
.LBB0_766:
	s_ashr_i32 s53, s52, 31
	s_lshl_b64 s[26:27], s[52:53], 19
	s_add_u32 s54, s38, s26
	s_addc_u32 s55, s39, s27
	s_and_b64 s[26:27], s[10:11], exec
	s_cselect_b32 s53, s55, s63
	s_cselect_b32 s59, s54, s62
	s_ashr_i32 s51, s50, 31
	s_lshl_b64 s[26:27], s[50:51], 19
	s_add_u32 s56, s36, s26
	s_addc_u32 s57, s37, s27
	s_and_b64 s[26:27], s[10:11], exec
	s_cselect_b32 s51, s57, s65
	s_cselect_b32 s77, s56, s64
	s_add_u32 s62, s62, 0x40080
	s_addc_u32 s63, s63, 0
	s_add_u32 s78, s64, 0x100
	s_addc_u32 s79, s65, 0
	s_mov_b32 s83, -2
	s_waitcnt lgkmcnt(0)
	s_cmp_eq_u32 s98, 1
	s_cbranch_scc0 .Lkb_skip_5
	s_mov_b32 s98, 0
	s_barrier
.Lkb_skip_5:
	ds_read_b128 v[146:149], v153
	ds_read_b128 v[158:161], v153 offset:1024
	ds_read_b128 v[162:165], v153 offset:2048
	ds_read_b128 v[166:169], v153 offset:3072
	ds_read_b128 v[170:173], v154
	ds_read_b128 v[174:177], v154 offset:1024
	ds_read_b128 v[178:181], v154 offset:2048
	ds_read_b128 v[182:185], v154 offset:3072
	s_add_u32 s26, s62, 0xfffc0080
	s_addc_u32 s27, s63, -1
	s_cmp_eq_u32 s83, 12
	s_cselect_b32 s67, s53, s27
	s_cselect_b32 s66, s59, s26
	s_cselect_b32 s65, s51, s79
	s_cselect_b32 s64, s77, s78
	s_add_i32 m0, s61, 0xc000
	ds_read_b128 v[186:189], v155
	ds_read_b128 v[190:193], v155 offset:1024
	ds_read_b128 v[194:197], v155 offset:2048
	ds_read_b128 v[198:201], v155 offset:3072
	ds_read_b128 v[202:205], v155 offset:4096
	ds_read_b128 v[206:209], v155 offset:5120
	ds_read_b128 v[210:213], v155 offset:6144
	ds_read_b128 v[214:217], v155 offset:7168
	global_load_lds_dwordx4 v138, s[62:63]
	s_add_i32 m0, s61, 0xe000
	s_nop 0
	global_load_lds_dwordx4 v140, s[62:63]
	s_waitcnt vmcnt(8)
	s_waitcnt lgkmcnt(0)
	s_barrier
	s_setprio 1
	s_waitcnt lgkmcnt(0)
	v_mfma_f32_16x16x32_bf16 v[124:127], v[146:149], v[186:189], 0
	v_mfma_f32_16x16x32_bf16 v[120:123], v[162:165], v[186:189], 0
	v_mfma_f32_16x16x32_bf16 v[108:111], v[146:149], v[194:197], 0
	v_mfma_f32_16x16x32_bf16 v[104:107], v[162:165], v[194:197], 0
	v_mfma_f32_16x16x32_bf16 v[92:95], v[146:149], v[202:205], 0
	v_mfma_f32_16x16x32_bf16 v[88:91], v[162:165], v[202:205], 0
	v_mfma_f32_16x16x32_bf16 v[76:79], v[146:149], v[210:213], 0
	v_mfma_f32_16x16x32_bf16 v[72:75], v[162:165], v[210:213], 0
	v_mfma_f32_16x16x32_bf16 v[124:127], v[158:161], v[190:193], v[124:127]
	v_mfma_f32_16x16x32_bf16 v[120:123], v[166:169], v[190:193], v[120:123]
	v_mfma_f32_16x16x32_bf16 v[108:111], v[158:161], v[198:201], v[108:111]
	v_mfma_f32_16x16x32_bf16 v[104:107], v[166:169], v[198:201], v[104:107]
	v_mfma_f32_16x16x32_bf16 v[92:95], v[158:161], v[206:209], v[92:95]
	v_mfma_f32_16x16x32_bf16 v[88:91], v[166:169], v[206:209], v[88:91]
	v_mfma_f32_16x16x32_bf16 v[76:79], v[158:161], v[214:217], v[76:79]
	v_mfma_f32_16x16x32_bf16 v[72:75], v[166:169], v[214:217], v[72:75]
	s_setprio 0
	s_setprio 1
	v_mfma_f32_16x16x32_bf16 v[116:119], v[170:173], v[186:189], 0
	v_mfma_f32_16x16x32_bf16 v[112:115], v[178:181], v[186:189], 0
	v_mfma_f32_16x16x32_bf16 v[100:103], v[170:173], v[194:197], 0
	v_mfma_f32_16x16x32_bf16 v[96:99], v[178:181], v[194:197], 0
	v_mfma_f32_16x16x32_bf16 v[84:87], v[170:173], v[202:205], 0
	v_mfma_f32_16x16x32_bf16 v[80:83], v[178:181], v[202:205], 0
	v_mfma_f32_16x16x32_bf16 v[68:71], v[170:173], v[210:213], 0
	v_mfma_f32_16x16x32_bf16 v[64:67], v[178:181], v[210:213], 0
	v_mfma_f32_16x16x32_bf16 v[116:119], v[174:177], v[190:193], v[116:119]
	v_mfma_f32_16x16x32_bf16 v[112:115], v[182:185], v[190:193], v[112:115]
	v_mfma_f32_16x16x32_bf16 v[100:103], v[174:177], v[198:201], v[100:103]
	v_mfma_f32_16x16x32_bf16 v[96:99], v[182:185], v[198:201], v[96:99]
	v_mfma_f32_16x16x32_bf16 v[84:87], v[174:177], v[206:209], v[84:87]
	v_mfma_f32_16x16x32_bf16 v[80:83], v[182:185], v[206:209], v[80:83]
	v_mfma_f32_16x16x32_bf16 v[68:71], v[174:177], v[214:217], v[68:71]
	v_mfma_f32_16x16x32_bf16 v[64:67], v[182:185], v[214:217], v[64:67]
	s_setprio 0
	s_barrier
	s_add_i32 s26, s75, s68
	s_mov_b32 m0, s26
	ds_read_b128 v[186:189], v155 offset:16384
	ds_read_b128 v[190:193], v155 offset:17408
	ds_read_b128 v[194:197], v155 offset:18432
	ds_read_b128 v[198:201], v155 offset:19456
	ds_read_b128 v[202:205], v155 offset:20480
	ds_read_b128 v[206:209], v155 offset:21504
	ds_read_b128 v[210:213], v155 offset:22528
	ds_read_b128 v[214:217], v155 offset:23552
	global_load_lds_dwordx4 v130, s[64:65]
	s_add_i32 m0, s26, 0x2000
	s_add_u32 s26, s64, 0x10000
	s_addc_u32 s27, s65, 0
	s_add_i32 s33, s76, s68
	global_load_lds_dwordx4 v134, s[64:65]
	s_mov_b32 m0, s33
	s_nop 0
	global_load_lds_dwordx4 v130, s[26:27]
	s_add_i32 m0, s33, 0x2000
	s_nop 0
	global_load_lds_dwordx4 v134, s[26:27]
	s_mov_b32 m0, s61
	s_nop 0
	global_load_lds_dwordx4 v128, s[66:67]
	s_mov_b32 m0, s69
	s_nop 0
	global_load_lds_dwordx4 v132, s[66:67]
	s_waitcnt vmcnt(8)
	s_waitcnt lgkmcnt(0)
	s_barrier
; #define PG8_STAGE(bufoff, gbase, voff) do { _Pragma("unroll") for (int _i = 0; _i < 2; ++_i) \
;         __builtin_amdgcn_global_load_lds((const unsigned*)((const char*)(gbase) + (voff)[_i]), (PG8_LAS unsigned*)(lds + (bufoff) + ldsw + _i * 8192), 16, 0, 0); } while (0)
; #define PG8_LDA(dst, b, h) do { _Pragma("unroll") for (int m = 0; m < 4; ++m) _Pragma("unroll") for (int k = 0; k < 2; ++k) dst[m][k] = *(const PG8_LAS bf16x8*)(lds + PG8_SA(b, h) + aoff + m * 2048 + k * 1024); } while (0)
; #define PG8_LDB(dst, b, h) do { _Pragma("unroll") for (int n = 0; n < 2; ++n) _Pragma("unroll") for (int k = 0; k < 2; ++k) dst[n][k] = *(const PG8_LAS bf16x8*)(lds + PG8_SB(b, h) + boff + n * 2048 + k * 1024); } while (0)
; #define PG8_MMA(ai, bj, At, Bt) do { __builtin_amdgcn_s_setprio(1); _Pragma("unroll") for (int m = 0; m < 4; ++m) _Pragma("unroll") for (int n = 0; n < 2; ++n) _Pragma("unroll") for (int k = 0; k < 2; ++k) \
;         acc[ai][bj][m][n] = __builtin_amdgcn_mfma_f32_16x16x32_bf16(Bt[n][k], At[m][k], acc[ai][bj][m][n], 0, 0, 0); __builtin_amdgcn_s_setprio(0); } while (0)
; #define PG8_WAIT_V(n) asm volatile("s_waitcnt vmcnt(" #n ")" ::: "memory")
; #define PG8_WAIT_L(n) asm volatile("s_waitcnt lgkmcnt(" #n ")" ::: "memory")
; #define PG8_BAR __builtin_amdgcn_s_barrier()
; #define PG8_SCHED __builtin_amdgcn_sched_barrier(0)
; template <class Epi, class Sched, bool ALIGN_EPI = false, bool SP2 = false>
; __device__ __forceinline__ void gemm_phase(PG8_LAS unsigned char* lds, const Gemm g, const Sched& S, const Epi& E, int tid_in) {
;     ...
;             PG8_WAIT_V(8); PG8_WAIT_L(0); PG8_BAR; PG8_MMA(1, 0, At, B0); PG8_MMA(1, 1, At, B1); PG8_BAR; PG8_SCHED;
;             PG8_LDB(B0, 1, 0); PG8_LDB(B1, 1, 1); PG8_SCHED; PG8_LDA(At, 1, 0); PG8_STAGE(PG8_SA(0, 1), a2 + hstep, voffA);
;             PG8_WAIT_V(8); PG8_WAIT_L(0); PG8_BAR; PG8_MMA(0, 0, At, B0); PG8_MMA(0, 1, At, B1); PG8_BAR; PG8_SCHED;
;             PG8_LDA(At, 1, 1); PG8_STAGE(PG8_SB(1, 0), b3, voffB); PG8_STAGE(PG8_SB(1, 1), b3 + hstepB, voffB); PG8_STAGE(PG8_SA(1, 0), a3, voffA);
	s_setprio 1
	s_waitcnt lgkmcnt(0)
	v_mfma_f32_16x16x32_bf16 v[60:63], v[146:149], v[186:189], 0
	v_mfma_f32_16x16x32_bf16 v[56:59], v[162:165], v[186:189], 0
	v_mfma_f32_16x16x32_bf16 v[44:47], v[146:149], v[194:197], 0
	v_mfma_f32_16x16x32_bf16 v[40:43], v[162:165], v[194:197], 0
	v_mfma_f32_16x16x32_bf16 v[28:31], v[146:149], v[202:205], 0
	v_mfma_f32_16x16x32_bf16 v[24:27], v[162:165], v[202:205], 0
	v_mfma_f32_16x16x32_bf16 v[12:15], v[146:149], v[210:213], 0
	v_mfma_f32_16x16x32_bf16 v[8:11], v[162:165], v[210:213], 0
	v_mfma_f32_16x16x32_bf16 v[60:63], v[158:161], v[190:193], v[60:63]
	v_mfma_f32_16x16x32_bf16 v[56:59], v[166:169], v[190:193], v[56:59]
	v_mfma_f32_16x16x32_bf16 v[44:47], v[158:161], v[198:201], v[44:47]
	v_mfma_f32_16x16x32_bf16 v[40:43], v[166:169], v[198:201], v[40:43]
	v_mfma_f32_16x16x32_bf16 v[28:31], v[158:161], v[206:209], v[28:31]
	v_mfma_f32_16x16x32_bf16 v[24:27], v[166:169], v[206:209], v[24:27]
	v_mfma_f32_16x16x32_bf16 v[12:15], v[158:161], v[214:217], v[12:15]
	v_mfma_f32_16x16x32_bf16 v[8:11], v[166:169], v[214:217], v[8:11]
	s_setprio 0
	s_setprio 1
	v_mfma_f32_16x16x32_bf16 v[52:55], v[170:173], v[186:189], 0
	v_mfma_f32_16x16x32_bf16 v[48:51], v[178:181], v[186:189], 0
	v_mfma_f32_16x16x32_bf16 v[36:39], v[170:173], v[194:197], 0
	v_mfma_f32_16x16x32_bf16 v[32:35], v[178:181], v[194:197], 0
	v_mfma_f32_16x16x32_bf16 v[20:23], v[170:173], v[202:205], 0
	v_mfma_f32_16x16x32_bf16 v[16:19], v[178:181], v[202:205], 0
	v_mfma_f32_16x16x32_bf16 v[4:7], v[170:173], v[210:213], 0
	v_mfma_f32_16x16x32_bf16 v[0:3], v[178:181], v[210:213], 0
	v_mfma_f32_16x16x32_bf16 v[52:55], v[174:177], v[190:193], v[52:55]
	v_mfma_f32_16x16x32_bf16 v[48:51], v[182:185], v[190:193], v[48:51]
	v_mfma_f32_16x16x32_bf16 v[36:39], v[174:177], v[198:201], v[36:39]
	v_mfma_f32_16x16x32_bf16 v[32:35], v[182:185], v[198:201], v[32:35]
	v_mfma_f32_16x16x32_bf16 v[20:23], v[174:177], v[206:209], v[20:23]
	v_mfma_f32_16x16x32_bf16 v[16:19], v[182:185], v[206:209], v[16:19]
	v_mfma_f32_16x16x32_bf16 v[4:7], v[174:177], v[214:217], v[4:7]
	v_mfma_f32_16x16x32_bf16 v[0:3], v[182:185], v[214:217], v[0:3]
	s_setprio 0
	s_barrier
	s_add_i32 s33, 0, 0x18000
	s_add_i32 s84, 0, 0x1c000
	v_add_u32_e32 v166, s33, v137
	v_add_u32_e32 v182, s84, v137
	ds_read_b128 v[146:149], v166
	ds_read_b128 v[158:161], v166 offset:1024
	ds_read_b128 v[162:165], v166 offset:2048
	ds_read_b128 v[166:169], v166 offset:3072
	ds_read_b128 v[170:173], v182
	ds_read_b128 v[174:177], v182 offset:1024
	ds_read_b128 v[178:181], v182 offset:2048
	ds_read_b128 v[182:185], v182 offset:3072
	s_add_u32 s26, s66, 0x40000
	s_addc_u32 s27, s67, 0
	s_mov_b32 m0, s70
	ds_read_b128 v[186:189], v155 offset:32768
	ds_read_b128 v[190:193], v155 offset:33792
	ds_read_b128 v[194:197], v155 offset:34816
	ds_read_b128 v[198:201], v155 offset:35840
	ds_read_b128 v[202:205], v155 offset:36864
	ds_read_b128 v[206:209], v155 offset:37888
	ds_read_b128 v[210:213], v155 offset:38912
	ds_read_b128 v[214:217], v155 offset:39936
	global_load_lds_dwordx4 v128, s[26:27]
	s_mov_b32 m0, s71
	s_nop 0
	global_load_lds_dwordx4 v132, s[26:27]
	s_waitcnt vmcnt(8)
	s_waitcnt lgkmcnt(0)
	s_barrier
	s_setprio 1
	s_waitcnt lgkmcnt(0)
	v_mfma_f32_16x16x32_bf16 v[124:127], v[146:149], v[186:189], v[124:127]
	v_mfma_f32_16x16x32_bf16 v[120:123], v[162:165], v[186:189], v[120:123]
	v_mfma_f32_16x16x32_bf16 v[108:111], v[146:149], v[194:197], v[108:111]
	v_mfma_f32_16x16x32_bf16 v[104:107], v[162:165], v[194:197], v[104:107]
	v_mfma_f32_16x16x32_bf16 v[92:95], v[146:149], v[202:205], v[92:95]
	v_mfma_f32_16x16x32_bf16 v[88:91], v[162:165], v[202:205], v[88:91]
	v_mfma_f32_16x16x32_bf16 v[76:79], v[146:149], v[210:213], v[76:79]
	v_mfma_f32_16x16x32_bf16 v[72:75], v[162:165], v[210:213], v[72:75]
	v_mfma_f32_16x16x32_bf16 v[124:127], v[158:161], v[190:193], v[124:127]
	v_mfma_f32_16x16x32_bf16 v[120:123], v[166:169], v[190:193], v[120:123]
	v_mfma_f32_16x16x32_bf16 v[108:111], v[158:161], v[198:201], v[108:111]
	v_mfma_f32_16x16x32_bf16 v[104:107], v[166:169], v[198:201], v[104:107]
	v_mfma_f32_16x16x32_bf16 v[92:95], v[158:161], v[206:209], v[92:95]
	v_mfma_f32_16x16x32_bf16 v[88:91], v[166:169], v[206:209], v[88:91]
	v_mfma_f32_16x16x32_bf16 v[76:79], v[158:161], v[214:217], v[76:79]
	v_mfma_f32_16x16x32_bf16 v[72:75], v[166:169], v[214:217], v[72:75]
	s_setprio 0
	s_setprio 1
	v_mfma_f32_16x16x32_bf16 v[116:119], v[170:173], v[186:189], v[116:119]
	v_mfma_f32_16x16x32_bf16 v[112:115], v[178:181], v[186:189], v[112:115]
	v_mfma_f32_16x16x32_bf16 v[100:103], v[170:173], v[194:197], v[100:103]
	v_mfma_f32_16x16x32_bf16 v[96:99], v[178:181], v[194:197], v[96:99]
	v_mfma_f32_16x16x32_bf16 v[84:87], v[170:173], v[202:205], v[84:87]
	v_mfma_f32_16x16x32_bf16 v[80:83], v[178:181], v[202:205], v[80:83]
	v_mfma_f32_16x16x32_bf16 v[68:71], v[170:173], v[210:213], v[68:71]
	v_mfma_f32_16x16x32_bf16 v[64:67], v[178:181], v[210:213], v[64:67]
	v_mfma_f32_16x16x32_bf16 v[116:119], v[174:177], v[190:193], v[116:119]
	v_mfma_f32_16x16x32_bf16 v[112:115], v[182:185], v[190:193], v[112:115]
	v_mfma_f32_16x16x32_bf16 v[100:103], v[174:177], v[198:201], v[100:103]
	v_mfma_f32_16x16x32_bf16 v[96:99], v[182:185], v[198:201], v[96:99]
	v_mfma_f32_16x16x32_bf16 v[84:87], v[174:177], v[206:209], v[84:87]
	v_mfma_f32_16x16x32_bf16 v[80:83], v[182:185], v[206:209], v[80:83]
	v_mfma_f32_16x16x32_bf16 v[68:71], v[174:177], v[214:217], v[68:71]
	v_mfma_f32_16x16x32_bf16 v[64:67], v[182:185], v[214:217], v[64:67]
	s_setprio 0
	s_barrier
; #define PG8_STAGE(bufoff, gbase, voff) do { _Pragma("unroll") for (int _i = 0; _i < 2; ++_i) \
;         __builtin_amdgcn_global_load_lds((const unsigned*)((const char*)(gbase) + (voff)[_i]), (PG8_LAS unsigned*)(lds + (bufoff) + ldsw + _i * 8192), 16, 0, 0); } while (0)
; #define PG8_LDA(dst, b, h) do { _Pragma("unroll") for (int m = 0; m < 4; ++m) _Pragma("unroll") for (int k = 0; k < 2; ++k) dst[m][k] = *(const PG8_LAS bf16x8*)(lds + PG8_SA(b, h) + aoff + m * 2048 + k * 1024); } while (0)
; #define PG8_MMA(ai, bj, At, Bt) do { __builtin_amdgcn_s_setprio(1); _Pragma("unroll") for (int m = 0; m < 4; ++m) _Pragma("unroll") for (int n = 0; n < 2; ++n) _Pragma("unroll") for (int k = 0; k < 2; ++k) \
;         acc[ai][bj][m][n] = __builtin_amdgcn_mfma_f32_16x16x32_bf16(Bt[n][k], At[m][k], acc[ai][bj][m][n], 0, 0, 0); __builtin_amdgcn_s_setprio(0); } while (0)
; #define PG8_WAIT_V(n) asm volatile("s_waitcnt vmcnt(" #n ")" ::: "memory")
; #define PG8_WAIT_L(n) asm volatile("s_waitcnt lgkmcnt(" #n ")" ::: "memory")
; #define PG8_BAR __builtin_amdgcn_s_barrier()
; #define PG8_SCHED __builtin_amdgcn_sched_barrier(0)
; template <class Epi, class Sched, bool ALIGN_EPI = false, bool SP2 = false>
; __device__ __forceinline__ void gemm_phase(PG8_LAS unsigned char* lds, const Gemm g, const Sched& S, const Epi& E, int tid_in) {
;     ...
;         for (int t = 0; t < nt; t += 2) {
;     ...
;             PG8_WAIT_V(8); PG8_WAIT_L(0); PG8_BAR; PG8_MMA(0, 0, At, B0); PG8_MMA(0, 1, At, B1); PG8_BAR; PG8_SCHED;
;             PG8_LDA(At, 1, 1); PG8_STAGE(PG8_SB(1, 0), b3, voffB); PG8_STAGE(PG8_SB(1, 1), b3 + hstepB, voffB); PG8_STAGE(PG8_SA(1, 0), a3, voffA);
;             PG8_WAIT_V(8); PG8_WAIT_L(0); PG8_BAR; PG8_MMA(1, 0, At, B0); PG8_MMA(1, 1, At, B1); PG8_BAR; PG8_SCHED;
	s_add_i32 s26, s33, s68
	s_add_i32 m0, s26, 0xffffff80
	ds_read_b128 v[186:189], v155 offset:49152
	ds_read_b128 v[190:193], v155 offset:50176
	ds_read_b128 v[194:197], v155 offset:51200
	ds_read_b128 v[198:201], v155 offset:52224
	ds_read_b128 v[202:205], v155 offset:53248
	ds_read_b128 v[206:209], v155 offset:54272
	ds_read_b128 v[210:213], v155 offset:55296
	ds_read_b128 v[214:217], v155 offset:56320
	global_load_lds_dwordx4 v130, s[64:65] offset:128
	s_add_i32 m0, s26, 0x1f80
	s_add_u32 s26, s64, 0x10080
	s_addc_u32 s27, s65, 0
	s_add_i32 s33, s84, s68
	global_load_lds_dwordx4 v134, s[64:65] offset:128
	s_mov_b32 m0, s33
	s_nop 0
	global_load_lds_dwordx4 v130, s[26:27]
	s_add_i32 m0, s33, 0x2000
	s_nop 0
	global_load_lds_dwordx4 v134, s[26:27]
	s_add_i32 m0, s73, 0xffffff80
	s_nop 0
	global_load_lds_dwordx4 v128, s[66:67] offset:128
	s_add_i32 m0, s74, 0xffffff80
	s_nop 0
	global_load_lds_dwordx4 v132, s[66:67] offset:128
	s_waitcnt vmcnt(8)
	s_waitcnt lgkmcnt(0)
	s_barrier
	s_setprio 1
	s_waitcnt lgkmcnt(0)
	v_mfma_f32_16x16x32_bf16 v[60:63], v[146:149], v[186:189], v[60:63]
	v_mfma_f32_16x16x32_bf16 v[56:59], v[162:165], v[186:189], v[56:59]
	v_mfma_f32_16x16x32_bf16 v[44:47], v[146:149], v[194:197], v[44:47]
	v_mfma_f32_16x16x32_bf16 v[40:43], v[162:165], v[194:197], v[40:43]
	v_mfma_f32_16x16x32_bf16 v[28:31], v[146:149], v[202:205], v[28:31]
	v_mfma_f32_16x16x32_bf16 v[24:27], v[162:165], v[202:205], v[24:27]
	v_mfma_f32_16x16x32_bf16 v[12:15], v[146:149], v[210:213], v[12:15]
	v_mfma_f32_16x16x32_bf16 v[8:11], v[162:165], v[210:213], v[8:11]
	v_mfma_f32_16x16x32_bf16 v[60:63], v[158:161], v[190:193], v[60:63]
	v_mfma_f32_16x16x32_bf16 v[56:59], v[166:169], v[190:193], v[56:59]
	v_mfma_f32_16x16x32_bf16 v[44:47], v[158:161], v[198:201], v[44:47]
	v_mfma_f32_16x16x32_bf16 v[40:43], v[166:169], v[198:201], v[40:43]
	v_mfma_f32_16x16x32_bf16 v[28:31], v[158:161], v[206:209], v[28:31]
	v_mfma_f32_16x16x32_bf16 v[24:27], v[166:169], v[206:209], v[24:27]
	v_mfma_f32_16x16x32_bf16 v[12:15], v[158:161], v[214:217], v[12:15]
	v_mfma_f32_16x16x32_bf16 v[8:11], v[166:169], v[214:217], v[8:11]
	s_setprio 0
	s_setprio 1
	v_mfma_f32_16x16x32_bf16 v[52:55], v[170:173], v[186:189], v[52:55]
	v_mfma_f32_16x16x32_bf16 v[48:51], v[178:181], v[186:189], v[48:51]
	v_mfma_f32_16x16x32_bf16 v[36:39], v[170:173], v[194:197], v[36:39]
	v_mfma_f32_16x16x32_bf16 v[32:35], v[178:181], v[194:197], v[32:35]
	v_mfma_f32_16x16x32_bf16 v[20:23], v[170:173], v[202:205], v[20:23]
	v_mfma_f32_16x16x32_bf16 v[16:19], v[178:181], v[202:205], v[16:19]
	v_mfma_f32_16x16x32_bf16 v[4:7], v[170:173], v[210:213], v[4:7]
	v_mfma_f32_16x16x32_bf16 v[0:3], v[178:181], v[210:213], v[0:3]
	v_mfma_f32_16x16x32_bf16 v[52:55], v[174:177], v[190:193], v[52:55]
	v_mfma_f32_16x16x32_bf16 v[48:51], v[182:185], v[190:193], v[48:51]
	v_mfma_f32_16x16x32_bf16 v[36:39], v[174:177], v[198:201], v[36:39]
	v_mfma_f32_16x16x32_bf16 v[32:35], v[182:185], v[198:201], v[32:35]
	v_mfma_f32_16x16x32_bf16 v[20:23], v[174:177], v[206:209], v[20:23]
	v_mfma_f32_16x16x32_bf16 v[16:19], v[182:185], v[206:209], v[16:19]
	v_mfma_f32_16x16x32_bf16 v[4:7], v[174:177], v[214:217], v[4:7]
	v_mfma_f32_16x16x32_bf16 v[0:3], v[182:185], v[214:217], v[0:3]
	s_setprio 0
	s_barrier
	s_add_i32 s83, s83, 2
	s_add_u32 s62, s62, 0x100
	s_addc_u32 s63, s63, 0
	s_add_u32 s78, s78, 0x100
	s_addc_u32 s79, s79, 0
	s_cmp_gt_u32 s83, 13

; #define PG8_STAGE(bufoff, gbase, voff) do { _Pragma("unroll") for (int _i = 0; _i < 2; ++_i) \
;         __builtin_amdgcn_global_load_lds((const unsigned*)((const char*)(gbase) + (voff)[_i]), (PG8_LAS unsigned*)(lds + (bufoff) + ldsw + _i * 8192), 16, 0, 0); } while (0)
; #define PG8_LDA(dst, b, h) do { _Pragma("unroll") for (int m = 0; m < 4; ++m) _Pragma("unroll") for (int k = 0; k < 2; ++k) dst[m][k] = *(const PG8_LAS bf16x8*)(lds + PG8_SA(b, h) + aoff + m * 2048 + k * 1024); } while (0)
; #define PG8_LDB(dst, b, h) do { _Pragma("unroll") for (int n = 0; n < 2; ++n) _Pragma("unroll") for (int k = 0; k < 2; ++k) dst[n][k] = *(const PG8_LAS bf16x8*)(lds + PG8_SB(b, h) + boff + n * 2048 + k * 1024); } while (0)
; #define PG8_MMA(ai, bj, At, Bt) do { __builtin_amdgcn_s_setprio(1); _Pragma("unroll") for (int m = 0; m < 4; ++m) _Pragma("unroll") for (int n = 0; n < 2; ++n) _Pragma("unroll") for (int k = 0; k < 2; ++k) \
;         acc[ai][bj][m][n] = __builtin_amdgcn_mfma_f32_16x16x32_bf16(Bt[n][k], At[m][k], acc[ai][bj][m][n], 0, 0, 0); __builtin_amdgcn_s_setprio(0); } while (0)
; #define PG8_WAIT_V(n) asm volatile("s_waitcnt vmcnt(" #n ")" ::: "memory")
; template <class Epi, class Sched, bool ALIGN_EPI = false, bool SP2 = false>
; __device__ __forceinline__ void gemm_phase(PG8_LAS unsigned char* lds, const Gemm g, const Sched& S, const Epi& E, int tid_in) {
;     ...
;         const bool has_next = S.next(ui + 1, nxt);
;         const char* nA = has_next ? (const char*)g.A + (size_t)nxt.pm * tstep : cA; const char* nB = has_next ? (const char*)g.Bt + (size_t)nxt.pn * tstepB : cB;
;         for (int t = 0; t < nt; t += 2) {
;             const bool last = (t == nt - 2);
;             const char* a1 = cA + (size_t)(t + 1) * kstep;
;             const char* a2 = last ? nA : cA + (size_t)(t + 2) * kstep; const char* b2 = last ? nB : cB + (size_t)(t + 2) * kstep;
;     ...
;             PG8_LDB(B0, 0, 0); PG8_LDB(B1, 0, 1); PG8_SCHED; PG8_LDA(At, 0, 0); PG8_STAGE(PG8_SA(1, 1), a1 + hstep, voffA);
;             PG8_WAIT_V(8); PG8_WAIT_L(0); PG8_BAR; PG8_MMA(0, 0, At, B0); PG8_MMA(0, 1, At, B1); PG8_BAR; PG8_SCHED;
;             PG8_LDA(At, 0, 1); PG8_STAGE(PG8_SB(0, 0), b2, voffB); PG8_STAGE(PG8_SB(0, 1), b2 + hstepB, voffB); PG8_STAGE(PG8_SA(0, 0), a2, voffA);
;             PG8_WAIT_V(8); PG8_WAIT_L(0); PG8_BAR; PG8_MMA(1, 0, At, B0); PG8_MMA(1, 1, At, B1); PG8_BAR; PG8_SCHED;
.LBB0_868:
	s_ashr_i32 s41, s40, 31
	s_lshl_b64 s[26:27], s[40:41], 20
	s_add_u32 s44, s28, s26
	s_addc_u32 s45, s29, s27
	s_and_b64 s[26:27], s[8:9], exec
	s_cselect_b32 s41, s45, s51
	s_cselect_b32 s68, s44, s50
	s_ashr_i32 s39, s38, 31
	s_lshl_b64 s[26:27], s[38:39], 20
	s_add_u32 s46, s42, s26
	s_addc_u32 s47, s43, s27
	s_and_b64 s[26:27], s[8:9], exec
	s_cselect_b32 s39, s47, s53
	s_cselect_b32 s69, s46, s52
	s_add_u32 s50, s50, 0x80080
	s_addc_u32 s51, s51, 0
	s_add_u32 s70, s52, 0x100
	s_addc_u32 s71, s53, 0
	s_mov_b32 s72, -2
	s_cmp_eq_u32 s98, 1
	s_cbranch_scc0 .Lkb_skip_6
	s_mov_b32 s98, 0
	s_barrier
.Lkb_skip_6:
	ds_read_b128 v[156:159], v150
	ds_read_b128 v[160:163], v150 offset:1024
	ds_read_b128 v[164:167], v150 offset:2048
	ds_read_b128 v[168:171], v150 offset:3072
	ds_read_b128 v[172:175], v151
	ds_read_b128 v[176:179], v151 offset:1024
	ds_read_b128 v[180:183], v151 offset:2048
	ds_read_b128 v[184:187], v151 offset:3072
	s_add_u32 s26, s50, 0xfff80080
	s_addc_u32 s27, s51, -1
	s_cmp_eq_u32 s72, 28
	s_cselect_b32 s55, s41, s27
	s_cselect_b32 s54, s68, s26
	s_cselect_b32 s53, s39, s71
	s_cselect_b32 s52, s69, s70
	s_add_i32 m0, s49, 0xc000
	ds_read_b128 v[188:191], v152
	ds_read_b128 v[192:195], v152 offset:1024
	ds_read_b128 v[196:199], v152 offset:2048
	ds_read_b128 v[200:203], v152 offset:3072
	ds_read_b128 v[204:207], v152 offset:4096
	ds_read_b128 v[208:211], v152 offset:5120
	ds_read_b128 v[212:215], v152 offset:6144
	ds_read_b128 v[216:219], v152 offset:7168
	global_load_lds_dwordx4 v138, s[50:51]
	s_add_i32 m0, s49, 0xe000
	s_nop 0
	global_load_lds_dwordx4 v140, s[50:51]
	s_waitcnt vmcnt(8)
	s_waitcnt lgkmcnt(0)
	s_barrier
	s_setprio 1
	s_waitcnt lgkmcnt(0)
	v_mfma_f32_16x16x32_bf16 v[124:127], v[156:159], v[188:191], 0
	v_mfma_f32_16x16x32_bf16 v[120:123], v[164:167], v[188:191], 0
	v_mfma_f32_16x16x32_bf16 v[108:111], v[156:159], v[196:199], 0
	v_mfma_f32_16x16x32_bf16 v[104:107], v[164:167], v[196:199], 0
	v_mfma_f32_16x16x32_bf16 v[92:95], v[156:159], v[204:207], 0
	v_mfma_f32_16x16x32_bf16 v[88:91], v[164:167], v[204:207], 0
	v_mfma_f32_16x16x32_bf16 v[76:79], v[156:159], v[212:215], 0
	v_mfma_f32_16x16x32_bf16 v[72:75], v[164:167], v[212:215], 0
	v_mfma_f32_16x16x32_bf16 v[124:127], v[160:163], v[192:195], v[124:127]
	v_mfma_f32_16x16x32_bf16 v[120:123], v[168:171], v[192:195], v[120:123]
	v_mfma_f32_16x16x32_bf16 v[108:111], v[160:163], v[200:203], v[108:111]
	v_mfma_f32_16x16x32_bf16 v[104:107], v[168:171], v[200:203], v[104:107]
	v_mfma_f32_16x16x32_bf16 v[92:95], v[160:163], v[208:211], v[92:95]
	v_mfma_f32_16x16x32_bf16 v[88:91], v[168:171], v[208:211], v[88:91]
	v_mfma_f32_16x16x32_bf16 v[76:79], v[160:163], v[216:219], v[76:79]
	v_mfma_f32_16x16x32_bf16 v[72:75], v[168:171], v[216:219], v[72:75]
	s_setprio 0
	s_setprio 1
	v_mfma_f32_16x16x32_bf16 v[116:119], v[172:175], v[188:191], 0
	v_mfma_f32_16x16x32_bf16 v[112:115], v[180:183], v[188:191], 0
	v_mfma_f32_16x16x32_bf16 v[100:103], v[172:175], v[196:199], 0
	v_mfma_f32_16x16x32_bf16 v[96:99], v[180:183], v[196:199], 0
	v_mfma_f32_16x16x32_bf16 v[84:87], v[172:175], v[204:207], 0
	v_mfma_f32_16x16x32_bf16 v[80:83], v[180:183], v[204:207], 0
	v_mfma_f32_16x16x32_bf16 v[68:71], v[172:175], v[212:215], 0
	v_mfma_f32_16x16x32_bf16 v[64:67], v[180:183], v[212:215], 0
	v_mfma_f32_16x16x32_bf16 v[116:119], v[176:179], v[192:195], v[116:119]
	v_mfma_f32_16x16x32_bf16 v[112:115], v[184:187], v[192:195], v[112:115]
	v_mfma_f32_16x16x32_bf16 v[100:103], v[176:179], v[200:203], v[100:103]
	v_mfma_f32_16x16x32_bf16 v[96:99], v[184:187], v[200:203], v[96:99]
	v_mfma_f32_16x16x32_bf16 v[84:87], v[176:179], v[208:211], v[84:87]
	v_mfma_f32_16x16x32_bf16 v[80:83], v[184:187], v[208:211], v[80:83]
	v_mfma_f32_16x16x32_bf16 v[68:71], v[176:179], v[216:219], v[68:71]
	v_mfma_f32_16x16x32_bf16 v[64:67], v[184:187], v[216:219], v[64:67]
	s_setprio 0
	s_barrier
	s_add_i32 s26, s64, s56
	s_mov_b32 m0, s26
	ds_read_b128 v[188:191], v152 offset:16384
	ds_read_b128 v[192:195], v152 offset:17408
	ds_read_b128 v[196:199], v152 offset:18432
	ds_read_b128 v[200:203], v152 offset:19456
	ds_read_b128 v[204:207], v152 offset:20480
	ds_read_b128 v[208:211], v152 offset:21504
	ds_read_b128 v[212:215], v152 offset:22528
	ds_read_b128 v[216:219], v152 offset:23552
	global_load_lds_dwordx4 v130, s[52:53]
	s_add_i32 m0, s26, 0x2000
	s_add_u32 s26, s52, 0x20000
	s_addc_u32 s27, s53, 0
	s_add_i32 s33, s65, s56
	global_load_lds_dwordx4 v134, s[52:53]
	s_mov_b32 m0, s33
	s_nop 0
	global_load_lds_dwordx4 v130, s[26:27]
	s_add_i32 m0, s33, 0x2000
	s_nop 0
	global_load_lds_dwordx4 v134, s[26:27]
	s_mov_b32 m0, s49
	s_nop 0
	global_load_lds_dwordx4 v128, s[54:55]
	s_mov_b32 m0, s57
	s_nop 0
	global_load_lds_dwordx4 v132, s[54:55]
	s_waitcnt vmcnt(8)
	s_waitcnt lgkmcnt(0)
	s_barrier
; #define PG8_STAGE(bufoff, gbase, voff) do { _Pragma("unroll") for (int _i = 0; _i < 2; ++_i) \
;         __builtin_amdgcn_global_load_lds((const unsigned*)((const char*)(gbase) + (voff)[_i]), (PG8_LAS unsigned*)(lds + (bufoff) + ldsw + _i * 8192), 16, 0, 0); } while (0)
; #define PG8_LDA(dst, b, h) do { _Pragma("unroll") for (int m = 0; m < 4; ++m) _Pragma("unroll") for (int k = 0; k < 2; ++k) dst[m][k] = *(const PG8_LAS bf16x8*)(lds + PG8_SA(b, h) + aoff + m * 2048 + k * 1024); } while (0)
; #define PG8_LDB(dst, b, h) do { _Pragma("unroll") for (int n = 0; n < 2; ++n) _Pragma("unroll") for (int k = 0; k < 2; ++k) dst[n][k] = *(const PG8_LAS bf16x8*)(lds + PG8_SB(b, h) + boff + n * 2048 + k * 1024); } while (0)
; #define PG8_MMA(ai, bj, At, Bt) do { __builtin_amdgcn_s_setprio(1); _Pragma("unroll") for (int m = 0; m < 4; ++m) _Pragma("unroll") for (int n = 0; n < 2; ++n) _Pragma("unroll") for (int k = 0; k < 2; ++k) \
;         acc[ai][bj][m][n] = __builtin_amdgcn_mfma_f32_16x16x32_bf16(Bt[n][k], At[m][k], acc[ai][bj][m][n], 0, 0, 0); __builtin_amdgcn_s_setprio(0); } while (0)
; #define PG8_WAIT_V(n) asm volatile("s_waitcnt vmcnt(" #n ")" ::: "memory")
; #define PG8_WAIT_L(n) asm volatile("s_waitcnt lgkmcnt(" #n ")" ::: "memory")
; #define PG8_BAR __builtin_amdgcn_s_barrier()
; #define PG8_SCHED __builtin_amdgcn_sched_barrier(0)
; template <class Epi, class Sched, bool ALIGN_EPI = false, bool SP2 = false>
; __device__ __forceinline__ void gemm_phase(PG8_LAS unsigned char* lds, const Gemm g, const Sched& S, const Epi& E, int tid_in) {
;     ...
;             PG8_WAIT_V(8); PG8_WAIT_L(0); PG8_BAR; PG8_MMA(1, 0, At, B0); PG8_MMA(1, 1, At, B1); PG8_BAR; PG8_SCHED;
;             PG8_LDB(B0, 1, 0); PG8_LDB(B1, 1, 1); PG8_SCHED; PG8_LDA(At, 1, 0); PG8_STAGE(PG8_SA(0, 1), a2 + hstep, voffA);
;             PG8_WAIT_V(8); PG8_WAIT_L(0); PG8_BAR; PG8_MMA(0, 0, At, B0); PG8_MMA(0, 1, At, B1); PG8_BAR; PG8_SCHED;
;             PG8_LDA(At, 1, 1); PG8_STAGE(PG8_SB(1, 0), b3, voffB); PG8_STAGE(PG8_SB(1, 1), b3 + hstepB, voffB); PG8_STAGE(PG8_SA(1, 0), a3, voffA);
	s_setprio 1
	s_waitcnt lgkmcnt(0)
	v_mfma_f32_16x16x32_bf16 v[60:63], v[156:159], v[188:191], 0
	v_mfma_f32_16x16x32_bf16 v[56:59], v[164:167], v[188:191], 0
	v_mfma_f32_16x16x32_bf16 v[44:47], v[156:159], v[196:199], 0
	v_mfma_f32_16x16x32_bf16 v[40:43], v[164:167], v[196:199], 0
	v_mfma_f32_16x16x32_bf16 v[28:31], v[156:159], v[204:207], 0
	v_mfma_f32_16x16x32_bf16 v[24:27], v[164:167], v[204:207], 0
	v_mfma_f32_16x16x32_bf16 v[12:15], v[156:159], v[212:215], 0
	v_mfma_f32_16x16x32_bf16 v[8:11], v[164:167], v[212:215], 0
	v_mfma_f32_16x16x32_bf16 v[60:63], v[160:163], v[192:195], v[60:63]
	v_mfma_f32_16x16x32_bf16 v[56:59], v[168:171], v[192:195], v[56:59]
	v_mfma_f32_16x16x32_bf16 v[44:47], v[160:163], v[200:203], v[44:47]
	v_mfma_f32_16x16x32_bf16 v[40:43], v[168:171], v[200:203], v[40:43]
	v_mfma_f32_16x16x32_bf16 v[28:31], v[160:163], v[208:211], v[28:31]
	v_mfma_f32_16x16x32_bf16 v[24:27], v[168:171], v[208:211], v[24:27]
	v_mfma_f32_16x16x32_bf16 v[12:15], v[160:163], v[216:219], v[12:15]
	v_mfma_f32_16x16x32_bf16 v[8:11], v[168:171], v[216:219], v[8:11]
	s_setprio 0
	s_setprio 1
	v_mfma_f32_16x16x32_bf16 v[52:55], v[172:175], v[188:191], 0
	v_mfma_f32_16x16x32_bf16 v[48:51], v[180:183], v[188:191], 0
	v_mfma_f32_16x16x32_bf16 v[36:39], v[172:175], v[196:199], 0
	v_mfma_f32_16x16x32_bf16 v[32:35], v[180:183], v[196:199], 0
	v_mfma_f32_16x16x32_bf16 v[20:23], v[172:175], v[204:207], 0
	v_mfma_f32_16x16x32_bf16 v[16:19], v[180:183], v[204:207], 0
	v_mfma_f32_16x16x32_bf16 v[4:7], v[172:175], v[212:215], 0
	v_mfma_f32_16x16x32_bf16 v[0:3], v[180:183], v[212:215], 0
	v_mfma_f32_16x16x32_bf16 v[52:55], v[176:179], v[192:195], v[52:55]
	v_mfma_f32_16x16x32_bf16 v[48:51], v[184:187], v[192:195], v[48:51]
	v_mfma_f32_16x16x32_bf16 v[36:39], v[176:179], v[200:203], v[36:39]
	v_mfma_f32_16x16x32_bf16 v[32:35], v[184:187], v[200:203], v[32:35]
	v_mfma_f32_16x16x32_bf16 v[20:23], v[176:179], v[208:211], v[20:23]
	v_mfma_f32_16x16x32_bf16 v[16:19], v[184:187], v[208:211], v[16:19]
	v_mfma_f32_16x16x32_bf16 v[4:7], v[176:179], v[216:219], v[4:7]
	v_mfma_f32_16x16x32_bf16 v[0:3], v[184:187], v[216:219], v[0:3]
	s_setprio 0
	s_barrier
	s_add_i32 s33, 0, 0x18000
	v_add_u32_e32 v155, s33, v146
	s_add_i32 s73, 0, 0x1c000
	ds_read_b128 v[156:159], v155
	ds_read_b128 v[160:163], v155 offset:1024
	ds_read_b128 v[164:167], v155 offset:2048
	ds_read_b128 v[168:171], v155 offset:3072
	v_add_u32_e32 v155, s73, v146
	ds_read_b128 v[172:175], v155
	ds_read_b128 v[176:179], v155 offset:1024
	ds_read_b128 v[180:183], v155 offset:2048
	ds_read_b128 v[184:187], v155 offset:3072
	s_add_u32 s26, s54, 0x80000
	s_addc_u32 s27, s55, 0
	s_mov_b32 m0, s58
	ds_read_b128 v[188:191], v152 offset:32768
	ds_read_b128 v[192:195], v152 offset:33792
	ds_read_b128 v[196:199], v152 offset:34816
	ds_read_b128 v[200:203], v152 offset:35840
	ds_read_b128 v[204:207], v152 offset:36864
	ds_read_b128 v[208:211], v152 offset:37888
	ds_read_b128 v[212:215], v152 offset:38912
	ds_read_b128 v[216:219], v152 offset:39936
	global_load_lds_dwordx4 v128, s[26:27]
	s_mov_b32 m0, s59
	s_nop 0
	global_load_lds_dwordx4 v132, s[26:27]
	s_waitcnt vmcnt(8)
	s_waitcnt lgkmcnt(0)
	s_barrier
	s_setprio 1
	s_waitcnt lgkmcnt(0)
	v_mfma_f32_16x16x32_bf16 v[124:127], v[156:159], v[188:191], v[124:127]
	v_mfma_f32_16x16x32_bf16 v[120:123], v[164:167], v[188:191], v[120:123]
	v_mfma_f32_16x16x32_bf16 v[108:111], v[156:159], v[196:199], v[108:111]
	v_mfma_f32_16x16x32_bf16 v[104:107], v[164:167], v[196:199], v[104:107]
	v_mfma_f32_16x16x32_bf16 v[92:95], v[156:159], v[204:207], v[92:95]
	v_mfma_f32_16x16x32_bf16 v[88:91], v[164:167], v[204:207], v[88:91]
	v_mfma_f32_16x16x32_bf16 v[76:79], v[156:159], v[212:215], v[76:79]
	v_mfma_f32_16x16x32_bf16 v[72:75], v[164:167], v[212:215], v[72:75]
	v_mfma_f32_16x16x32_bf16 v[124:127], v[160:163], v[192:195], v[124:127]
	v_mfma_f32_16x16x32_bf16 v[120:123], v[168:171], v[192:195], v[120:123]
	v_mfma_f32_16x16x32_bf16 v[108:111], v[160:163], v[200:203], v[108:111]
	v_mfma_f32_16x16x32_bf16 v[104:107], v[168:171], v[200:203], v[104:107]
	v_mfma_f32_16x16x32_bf16 v[92:95], v[160:163], v[208:211], v[92:95]
	v_mfma_f32_16x16x32_bf16 v[88:91], v[168:171], v[208:211], v[88:91]
	v_mfma_f32_16x16x32_bf16 v[76:79], v[160:163], v[216:219], v[76:79]
	v_mfma_f32_16x16x32_bf16 v[72:75], v[168:171], v[216:219], v[72:75]
	s_setprio 0
	s_setprio 1
	v_mfma_f32_16x16x32_bf16 v[116:119], v[172:175], v[188:191], v[116:119]
	v_mfma_f32_16x16x32_bf16 v[112:115], v[180:183], v[188:191], v[112:115]
	v_mfma_f32_16x16x32_bf16 v[100:103], v[172:175], v[196:199], v[100:103]
	v_mfma_f32_16x16x32_bf16 v[96:99], v[180:183], v[196:199], v[96:99]
	v_mfma_f32_16x16x32_bf16 v[84:87], v[172:175], v[204:207], v[84:87]
	v_mfma_f32_16x16x32_bf16 v[80:83], v[180:183], v[204:207], v[80:83]
	v_mfma_f32_16x16x32_bf16 v[68:71], v[172:175], v[212:215], v[68:71]
	v_mfma_f32_16x16x32_bf16 v[64:67], v[180:183], v[212:215], v[64:67]
	v_mfma_f32_16x16x32_bf16 v[116:119], v[176:179], v[192:195], v[116:119]
	v_mfma_f32_16x16x32_bf16 v[112:115], v[184:187], v[192:195], v[112:115]
	v_mfma_f32_16x16x32_bf16 v[100:103], v[176:179], v[200:203], v[100:103]
	v_mfma_f32_16x16x32_bf16 v[96:99], v[184:187], v[200:203], v[96:99]
	v_mfma_f32_16x16x32_bf16 v[84:87], v[176:179], v[208:211], v[84:87]
	v_mfma_f32_16x16x32_bf16 v[80:83], v[184:187], v[208:211], v[80:83]
	v_mfma_f32_16x16x32_bf16 v[68:71], v[176:179], v[216:219], v[68:71]
	v_mfma_f32_16x16x32_bf16 v[64:67], v[184:187], v[216:219], v[64:67]
	s_setprio 0
	s_barrier
; #define PG8_STAGE(bufoff, gbase, voff) do { _Pragma("unroll") for (int _i = 0; _i < 2; ++_i) \
;         __builtin_amdgcn_global_load_lds((const unsigned*)((const char*)(gbase) + (voff)[_i]), (PG8_LAS unsigned*)(lds + (bufoff) + ldsw + _i * 8192), 16, 0, 0); } while (0)
; #define PG8_LDA(dst, b, h) do { _Pragma("unroll") for (int m = 0; m < 4; ++m) _Pragma("unroll") for (int k = 0; k < 2; ++k) dst[m][k] = *(const PG8_LAS bf16x8*)(lds + PG8_SA(b, h) + aoff + m * 2048 + k * 1024); } while (0)
; #define PG8_MMA(ai, bj, At, Bt) do { __builtin_amdgcn_s_setprio(1); _Pragma("unroll") for (int m = 0; m < 4; ++m) _Pragma("unroll") for (int n = 0; n < 2; ++n) _Pragma("unroll") for (int k = 0; k < 2; ++k) \
;         acc[ai][bj][m][n] = __builtin_amdgcn_mfma_f32_16x16x32_bf16(Bt[n][k], At[m][k], acc[ai][bj][m][n], 0, 0, 0); __builtin_amdgcn_s_setprio(0); } while (0)
; #define PG8_WAIT_V(n) asm volatile("s_waitcnt vmcnt(" #n ")" ::: "memory")
; #define PG8_WAIT_L(n) asm volatile("s_waitcnt lgkmcnt(" #n ")" ::: "memory")
; #define PG8_BAR __builtin_amdgcn_s_barrier()
; #define PG8_SCHED __builtin_amdgcn_sched_barrier(0)
; template <class Epi, class Sched, bool ALIGN_EPI = false, bool SP2 = false>
; __device__ __forceinline__ void gemm_phase(PG8_LAS unsigned char* lds, const Gemm g, const Sched& S, const Epi& E, int tid_in) {
;     ...
;         for (int t = 0; t < nt; t += 2) {
;     ...
;             PG8_WAIT_V(8); PG8_WAIT_L(0); PG8_BAR; PG8_MMA(0, 0, At, B0); PG8_MMA(0, 1, At, B1); PG8_BAR; PG8_SCHED;
;             PG8_LDA(At, 1, 1); PG8_STAGE(PG8_SB(1, 0), b3, voffB); PG8_STAGE(PG8_SB(1, 1), b3 + hstepB, voffB); PG8_STAGE(PG8_SA(1, 0), a3, voffA);
;             PG8_WAIT_V(8); PG8_WAIT_L(0); PG8_BAR; PG8_MMA(1, 0, At, B0); PG8_MMA(1, 1, At, B1); PG8_BAR; PG8_SCHED;
	s_add_i32 s26, s33, s56
	s_add_i32 m0, s26, 0xffffff80
	ds_read_b128 v[188:191], v152 offset:49152
	ds_read_b128 v[192:195], v152 offset:50176
	ds_read_b128 v[196:199], v152 offset:51200
	ds_read_b128 v[200:203], v152 offset:52224
	ds_read_b128 v[204:207], v152 offset:53248
	ds_read_b128 v[208:211], v152 offset:54272
	ds_read_b128 v[212:215], v152 offset:55296
	ds_read_b128 v[216:219], v152 offset:56320
	global_load_lds_dwordx4 v130, s[52:53] offset:128
	s_add_i32 m0, s26, 0x1f80
	s_add_u32 s26, s52, 0x20080
	s_addc_u32 s27, s53, 0
	s_add_i32 s33, s73, s56
	global_load_lds_dwordx4 v134, s[52:53] offset:128
	s_mov_b32 m0, s33
	s_nop 0
	global_load_lds_dwordx4 v130, s[26:27]
	s_add_i32 m0, s33, 0x2000
	s_nop 0
	global_load_lds_dwordx4 v134, s[26:27]
	s_add_i32 m0, s62, 0xffffff80
	s_nop 0
	global_load_lds_dwordx4 v128, s[54:55] offset:128
	s_add_i32 m0, s63, 0xffffff80
	s_nop 0
	global_load_lds_dwordx4 v132, s[54:55] offset:128
	s_waitcnt vmcnt(8)
	s_waitcnt lgkmcnt(0)
	s_barrier
	s_setprio 1
	s_waitcnt lgkmcnt(0)
	v_mfma_f32_16x16x32_bf16 v[60:63], v[156:159], v[188:191], v[60:63]
	v_mfma_f32_16x16x32_bf16 v[56:59], v[164:167], v[188:191], v[56:59]
	v_mfma_f32_16x16x32_bf16 v[44:47], v[156:159], v[196:199], v[44:47]
	v_mfma_f32_16x16x32_bf16 v[40:43], v[164:167], v[196:199], v[40:43]
	v_mfma_f32_16x16x32_bf16 v[28:31], v[156:159], v[204:207], v[28:31]
	v_mfma_f32_16x16x32_bf16 v[24:27], v[164:167], v[204:207], v[24:27]
	v_mfma_f32_16x16x32_bf16 v[12:15], v[156:159], v[212:215], v[12:15]
	v_mfma_f32_16x16x32_bf16 v[8:11], v[164:167], v[212:215], v[8:11]
	v_mfma_f32_16x16x32_bf16 v[60:63], v[160:163], v[192:195], v[60:63]
	v_mfma_f32_16x16x32_bf16 v[56:59], v[168:171], v[192:195], v[56:59]
	v_mfma_f32_16x16x32_bf16 v[44:47], v[160:163], v[200:203], v[44:47]
	v_mfma_f32_16x16x32_bf16 v[40:43], v[168:171], v[200:203], v[40:43]
	v_mfma_f32_16x16x32_bf16 v[28:31], v[160:163], v[208:211], v[28:31]
	v_mfma_f32_16x16x32_bf16 v[24:27], v[168:171], v[208:211], v[24:27]
	v_mfma_f32_16x16x32_bf16 v[12:15], v[160:163], v[216:219], v[12:15]
	v_mfma_f32_16x16x32_bf16 v[8:11], v[168:171], v[216:219], v[8:11]
	s_setprio 0
	s_setprio 1
	v_mfma_f32_16x16x32_bf16 v[52:55], v[172:175], v[188:191], v[52:55]
	v_mfma_f32_16x16x32_bf16 v[48:51], v[180:183], v[188:191], v[48:51]
	v_mfma_f32_16x16x32_bf16 v[36:39], v[172:175], v[196:199], v[36:39]
	v_mfma_f32_16x16x32_bf16 v[32:35], v[180:183], v[196:199], v[32:35]
	v_mfma_f32_16x16x32_bf16 v[20:23], v[172:175], v[204:207], v[20:23]
	v_mfma_f32_16x16x32_bf16 v[16:19], v[180:183], v[204:207], v[16:19]
	v_mfma_f32_16x16x32_bf16 v[4:7], v[172:175], v[212:215], v[4:7]
	v_mfma_f32_16x16x32_bf16 v[0:3], v[180:183], v[212:215], v[0:3]
	v_mfma_f32_16x16x32_bf16 v[52:55], v[176:179], v[192:195], v[52:55]
	v_mfma_f32_16x16x32_bf16 v[48:51], v[184:187], v[192:195], v[48:51]
	v_mfma_f32_16x16x32_bf16 v[36:39], v[176:179], v[200:203], v[36:39]
	v_mfma_f32_16x16x32_bf16 v[32:35], v[184:187], v[200:203], v[32:35]
	v_mfma_f32_16x16x32_bf16 v[20:23], v[176:179], v[208:211], v[20:23]
	v_mfma_f32_16x16x32_bf16 v[16:19], v[184:187], v[208:211], v[16:19]
	v_mfma_f32_16x16x32_bf16 v[4:7], v[176:179], v[216:219], v[4:7]
	v_mfma_f32_16x16x32_bf16 v[0:3], v[184:187], v[216:219], v[0:3]
	s_setprio 0
	s_barrier
	s_add_i32 s72, s72, 2
	s_add_u32 s50, s50, 0x100
	s_addc_u32 s51, s51, 0
	s_add_u32 s70, s70, 0x100
	s_addc_u32 s71, s71, 0
	s_cmp_gt_u32 s72, 29

; #define PG8_STAGE(bufoff, gbase, voff) do { _Pragma("unroll") for (int _i = 0; _i < 2; ++_i) \
;         __builtin_amdgcn_global_load_lds((const unsigned*)((const char*)(gbase) + (voff)[_i]), (PG8_LAS unsigned*)(lds + (bufoff) + ldsw + _i * 8192), 16, 0, 0); } while (0)
; #define PG8_LDA(dst, b, h) do { _Pragma("unroll") for (int m = 0; m < 4; ++m) _Pragma("unroll") for (int k = 0; k < 2; ++k) dst[m][k] = *(const PG8_LAS bf16x8*)(lds + PG8_SA(b, h) + aoff + m * 2048 + k * 1024); } while (0)
; #define PG8_LDB(dst, b, h) do { _Pragma("unroll") for (int n = 0; n < 2; ++n) _Pragma("unroll") for (int k = 0; k < 2; ++k) dst[n][k] = *(const PG8_LAS bf16x8*)(lds + PG8_SB(b, h) + boff + n * 2048 + k * 1024); } while (0)
; #define PG8_MMA(ai, bj, At, Bt) do { __builtin_amdgcn_s_setprio(1); _Pragma("unroll") for (int m = 0; m < 4; ++m) _Pragma("unroll") for (int n = 0; n < 2; ++n) _Pragma("unroll") for (int k = 0; k < 2; ++k) \
;         acc[ai][bj][m][n] = __builtin_amdgcn_mfma_f32_16x16x32_bf16(Bt[n][k], At[m][k], acc[ai][bj][m][n], 0, 0, 0); __builtin_amdgcn_s_setprio(0); } while (0)
; #define PG8_WAIT_V(n) asm volatile("s_waitcnt vmcnt(" #n ")" ::: "memory")
; template <class Epi, class Sched, bool ALIGN_EPI = false, bool SP2 = false>
; __device__ __forceinline__ void gemm_phase(PG8_LAS unsigned char* lds, const Gemm g, const Sched& S, const Epi& E, int tid_in) {
;     ...
;         const bool has_next = S.next(ui + 1, nxt);
;         const char* nA = has_next ? (const char*)g.A + (size_t)nxt.pm * tstep : cA; const char* nB = has_next ? (const char*)g.Bt + (size_t)nxt.pn * tstepB : cB;
;         for (int t = 0; t < nt; t += 2) {
;             const bool last = (t == nt - 2);
;             const char* a1 = cA + (size_t)(t + 1) * kstep;
;             const char* a2 = last ? nA : cA + (size_t)(t + 2) * kstep; const char* b2 = last ? nB : cB + (size_t)(t + 2) * kstep;
;     ...
;             PG8_LDB(B0, 0, 0); PG8_LDB(B1, 0, 1); PG8_SCHED; PG8_LDA(At, 0, 0); PG8_STAGE(PG8_SA(1, 1), a1 + hstep, voffA);
;             PG8_WAIT_V(8); PG8_WAIT_L(0); PG8_BAR; PG8_MMA(0, 0, At, B0); PG8_MMA(0, 1, At, B1); PG8_BAR; PG8_SCHED;
;             PG8_LDA(At, 0, 1); PG8_STAGE(PG8_SB(0, 0), b2, voffB); PG8_STAGE(PG8_SB(0, 1), b2 + hstepB, voffB); PG8_STAGE(PG8_SA(0, 0), a2, voffA);
;             PG8_WAIT_V(8); PG8_WAIT_L(0); PG8_BAR; PG8_MMA(1, 0, At, B0); PG8_MMA(1, 1, At, B1); PG8_BAR; PG8_SCHED;
.LBB0_948:
	s_ashr_i32 s43, s42, 31
	s_lshl_b64 s[26:27], s[42:43], 22
	s_add_u32 s46, s14, s26
	s_addc_u32 s47, s15, s27
	s_and_b64 s[10:11], s[10:11], exec
	s_cselect_b32 s43, s47, s53
	s_cselect_b32 s67, s46, s52
	s_add_u32 s68, s52, 0x100
	s_addc_u32 s69, s53, 0
	s_mov_b32 s70, -2
	s_waitcnt lgkmcnt(0)
	s_cmp_eq_u32 s98, 1
	s_cbranch_scc0 .Lkb_skip_7
	s_mov_b32 s98, 0
	s_barrier
.Lkb_skip_7:
	ds_read_b128 v[146:149], v153
	ds_read_b128 v[158:161], v153 offset:1024
	ds_read_b128 v[162:165], v153 offset:2048
	ds_read_b128 v[166:169], v153 offset:3072
	ds_read_b128 v[170:173], v154
	ds_read_b128 v[174:177], v154 offset:1024
	ds_read_b128 v[178:181], v154 offset:2048
	ds_read_b128 v[182:185], v154 offset:3072
	s_add_u32 s10, s50, 0x100
	s_addc_u32 s11, s51, 0
	s_cmpk_eq_i32 s70, 0x7c
	s_cselect_b32 s55, s45, s11
	s_cselect_b32 s54, s44, s10
	s_cselect_b32 s53, s43, s69
	s_cselect_b32 s52, s67, s68
	s_add_i32 m0, s49, 0xc000
	ds_read_b128 v[186:189], v155
	ds_read_b128 v[190:193], v155 offset:1024
	ds_read_b128 v[194:197], v155 offset:2048
	ds_read_b128 v[198:201], v155 offset:3072
	ds_read_b128 v[202:205], v155 offset:4096
	ds_read_b128 v[206:209], v155 offset:5120
	ds_read_b128 v[210:213], v155 offset:6144
	ds_read_b128 v[214:217], v155 offset:7168
	global_load_lds_dwordx4 v138, s[50:51]
	s_add_i32 m0, s49, 0xe000
	s_nop 0
	global_load_lds_dwordx4 v140, s[50:51]
	s_waitcnt vmcnt(8)
	s_waitcnt lgkmcnt(0)
	s_barrier
	s_setprio 1
	s_waitcnt lgkmcnt(0)
	v_mfma_f32_16x16x32_bf16 v[124:127], v[146:149], v[186:189], 0
	v_mfma_f32_16x16x32_bf16 v[120:123], v[162:165], v[186:189], 0
	v_mfma_f32_16x16x32_bf16 v[108:111], v[146:149], v[194:197], 0
	v_mfma_f32_16x16x32_bf16 v[104:107], v[162:165], v[194:197], 0
	v_mfma_f32_16x16x32_bf16 v[92:95], v[146:149], v[202:205], 0
	v_mfma_f32_16x16x32_bf16 v[88:91], v[162:165], v[202:205], 0
	v_mfma_f32_16x16x32_bf16 v[76:79], v[146:149], v[210:213], 0
	v_mfma_f32_16x16x32_bf16 v[72:75], v[162:165], v[210:213], 0
	v_mfma_f32_16x16x32_bf16 v[124:127], v[158:161], v[190:193], v[124:127]
	v_mfma_f32_16x16x32_bf16 v[120:123], v[166:169], v[190:193], v[120:123]
	v_mfma_f32_16x16x32_bf16 v[108:111], v[158:161], v[198:201], v[108:111]
	v_mfma_f32_16x16x32_bf16 v[104:107], v[166:169], v[198:201], v[104:107]
	v_mfma_f32_16x16x32_bf16 v[92:95], v[158:161], v[206:209], v[92:95]
	v_mfma_f32_16x16x32_bf16 v[88:91], v[166:169], v[206:209], v[88:91]
	v_mfma_f32_16x16x32_bf16 v[76:79], v[158:161], v[214:217], v[76:79]
	v_mfma_f32_16x16x32_bf16 v[72:75], v[166:169], v[214:217], v[72:75]
	s_setprio 0
	s_setprio 1
	v_mfma_f32_16x16x32_bf16 v[116:119], v[170:173], v[186:189], 0
	v_mfma_f32_16x16x32_bf16 v[112:115], v[178:181], v[186:189], 0
	v_mfma_f32_16x16x32_bf16 v[100:103], v[170:173], v[194:197], 0
	v_mfma_f32_16x16x32_bf16 v[96:99], v[178:181], v[194:197], 0
	v_mfma_f32_16x16x32_bf16 v[84:87], v[170:173], v[202:205], 0
	v_mfma_f32_16x16x32_bf16 v[80:83], v[178:181], v[202:205], 0
	v_mfma_f32_16x16x32_bf16 v[68:71], v[170:173], v[210:213], 0
	v_mfma_f32_16x16x32_bf16 v[64:67], v[178:181], v[210:213], 0
	v_mfma_f32_16x16x32_bf16 v[116:119], v[174:177], v[190:193], v[116:119]
	v_mfma_f32_16x16x32_bf16 v[112:115], v[182:185], v[190:193], v[112:115]
	v_mfma_f32_16x16x32_bf16 v[100:103], v[174:177], v[198:201], v[100:103]
	v_mfma_f32_16x16x32_bf16 v[96:99], v[182:185], v[198:201], v[96:99]
	v_mfma_f32_16x16x32_bf16 v[84:87], v[174:177], v[206:209], v[84:87]
	v_mfma_f32_16x16x32_bf16 v[80:83], v[182:185], v[206:209], v[80:83]
	v_mfma_f32_16x16x32_bf16 v[68:71], v[174:177], v[214:217], v[68:71]
	v_mfma_f32_16x16x32_bf16 v[64:67], v[182:185], v[214:217], v[64:67]
	s_setprio 0
	s_barrier
	s_add_i32 s26, s63, s56
	s_mov_b32 m0, s26
	ds_read_b128 v[186:189], v155 offset:16384
	ds_read_b128 v[190:193], v155 offset:17408
	ds_read_b128 v[194:197], v155 offset:18432
	ds_read_b128 v[198:201], v155 offset:19456
	ds_read_b128 v[202:205], v155 offset:20480
	ds_read_b128 v[206:209], v155 offset:21504
	ds_read_b128 v[210:213], v155 offset:22528
	ds_read_b128 v[214:217], v155 offset:23552
	global_load_lds_dwordx4 v130, s[52:53]
	s_add_i32 m0, s26, 0x2000
	s_add_u32 s26, s52, 0x80000
	s_addc_u32 s27, s53, 0
	s_add_i32 s33, s64, s56
	global_load_lds_dwordx4 v134, s[52:53]
	s_mov_b32 m0, s33
	s_nop 0
	global_load_lds_dwordx4 v130, s[26:27]
	s_add_i32 m0, s33, 0x2000
	s_nop 0
	global_load_lds_dwordx4 v134, s[26:27]
	s_mov_b32 m0, s49
	s_nop 0
	global_load_lds_dwordx4 v128, s[54:55]
	s_mov_b32 m0, s57
	s_nop 0
	global_load_lds_dwordx4 v132, s[54:55]
	s_waitcnt vmcnt(8)
	s_waitcnt lgkmcnt(0)
	s_barrier
; #define PG8_STAGE(bufoff, gbase, voff) do { _Pragma("unroll") for (int _i = 0; _i < 2; ++_i) \
;         __builtin_amdgcn_global_load_lds((const unsigned*)((const char*)(gbase) + (voff)[_i]), (PG8_LAS unsigned*)(lds + (bufoff) + ldsw + _i * 8192), 16, 0, 0); } while (0)
; #define PG8_LDA(dst, b, h) do { _Pragma("unroll") for (int m = 0; m < 4; ++m) _Pragma("unroll") for (int k = 0; k < 2; ++k) dst[m][k] = *(const PG8_LAS bf16x8*)(lds + PG8_SA(b, h) + aoff + m * 2048 + k * 1024); } while (0)
; #define PG8_LDB(dst, b, h) do { _Pragma("unroll") for (int n = 0; n < 2; ++n) _Pragma("unroll") for (int k = 0; k < 2; ++k) dst[n][k] = *(const PG8_LAS bf16x8*)(lds + PG8_SB(b, h) + boff + n * 2048 + k * 1024); } while (0)
; #define PG8_MMA(ai, bj, At, Bt) do { __builtin_amdgcn_s_setprio(1); _Pragma("unroll") for (int m = 0; m < 4; ++m) _Pragma("unroll") for (int n = 0; n < 2; ++n) _Pragma("unroll") for (int k = 0; k < 2; ++k) \
;         acc[ai][bj][m][n] = __builtin_amdgcn_mfma_f32_16x16x32_bf16(Bt[n][k], At[m][k], acc[ai][bj][m][n], 0, 0, 0); __builtin_amdgcn_s_setprio(0); } while (0)
; #define PG8_WAIT_V(n) asm volatile("s_waitcnt vmcnt(" #n ")" ::: "memory")
; #define PG8_WAIT_L(n) asm volatile("s_waitcnt lgkmcnt(" #n ")" ::: "memory")
; #define PG8_BAR __builtin_amdgcn_s_barrier()
; #define PG8_SCHED __builtin_amdgcn_sched_barrier(0)
; template <class Epi, class Sched, bool ALIGN_EPI = false, bool SP2 = false>
; __device__ __forceinline__ void gemm_phase(PG8_LAS unsigned char* lds, const Gemm g, const Sched& S, const Epi& E, int tid_in) {
;     ...
;             PG8_WAIT_V(8); PG8_WAIT_L(0); PG8_BAR; PG8_MMA(1, 0, At, B0); PG8_MMA(1, 1, At, B1); PG8_BAR; PG8_SCHED;
;             PG8_LDB(B0, 1, 0); PG8_LDB(B1, 1, 1); PG8_SCHED; PG8_LDA(At, 1, 0); PG8_STAGE(PG8_SA(0, 1), a2 + hstep, voffA);
;             PG8_WAIT_V(8); PG8_WAIT_L(0); PG8_BAR; PG8_MMA(0, 0, At, B0); PG8_MMA(0, 1, At, B1); PG8_BAR; PG8_SCHED;
;             PG8_LDA(At, 1, 1); PG8_STAGE(PG8_SB(1, 0), b3, voffB); PG8_STAGE(PG8_SB(1, 1), b3 + hstepB, voffB); PG8_STAGE(PG8_SA(1, 0), a3, voffA);
	s_setprio 1
	s_waitcnt lgkmcnt(0)
	v_mfma_f32_16x16x32_bf16 v[60:63], v[146:149], v[186:189], 0
	v_mfma_f32_16x16x32_bf16 v[56:59], v[162:165], v[186:189], 0
	v_mfma_f32_16x16x32_bf16 v[44:47], v[146:149], v[194:197], 0
	v_mfma_f32_16x16x32_bf16 v[40:43], v[162:165], v[194:197], 0
	v_mfma_f32_16x16x32_bf16 v[28:31], v[146:149], v[202:205], 0
	v_mfma_f32_16x16x32_bf16 v[24:27], v[162:165], v[202:205], 0
	v_mfma_f32_16x16x32_bf16 v[12:15], v[146:149], v[210:213], 0
	v_mfma_f32_16x16x32_bf16 v[8:11], v[162:165], v[210:213], 0
	v_mfma_f32_16x16x32_bf16 v[60:63], v[158:161], v[190:193], v[60:63]
	v_mfma_f32_16x16x32_bf16 v[56:59], v[166:169], v[190:193], v[56:59]
	v_mfma_f32_16x16x32_bf16 v[44:47], v[158:161], v[198:201], v[44:47]
	v_mfma_f32_16x16x32_bf16 v[40:43], v[166:169], v[198:201], v[40:43]
	v_mfma_f32_16x16x32_bf16 v[28:31], v[158:161], v[206:209], v[28:31]
	v_mfma_f32_16x16x32_bf16 v[24:27], v[166:169], v[206:209], v[24:27]
	v_mfma_f32_16x16x32_bf16 v[12:15], v[158:161], v[214:217], v[12:15]
	v_mfma_f32_16x16x32_bf16 v[8:11], v[166:169], v[214:217], v[8:11]
	s_setprio 0
	s_setprio 1
	v_mfma_f32_16x16x32_bf16 v[52:55], v[170:173], v[186:189], 0
	v_mfma_f32_16x16x32_bf16 v[48:51], v[178:181], v[186:189], 0
	v_mfma_f32_16x16x32_bf16 v[36:39], v[170:173], v[194:197], 0
	v_mfma_f32_16x16x32_bf16 v[32:35], v[178:181], v[194:197], 0
	v_mfma_f32_16x16x32_bf16 v[20:23], v[170:173], v[202:205], 0
	v_mfma_f32_16x16x32_bf16 v[16:19], v[178:181], v[202:205], 0
	v_mfma_f32_16x16x32_bf16 v[4:7], v[170:173], v[210:213], 0
	v_mfma_f32_16x16x32_bf16 v[0:3], v[178:181], v[210:213], 0
	v_mfma_f32_16x16x32_bf16 v[52:55], v[174:177], v[190:193], v[52:55]
	v_mfma_f32_16x16x32_bf16 v[48:51], v[182:185], v[190:193], v[48:51]
	v_mfma_f32_16x16x32_bf16 v[36:39], v[174:177], v[198:201], v[36:39]
	v_mfma_f32_16x16x32_bf16 v[32:35], v[182:185], v[198:201], v[32:35]
	v_mfma_f32_16x16x32_bf16 v[20:23], v[174:177], v[206:209], v[20:23]
	v_mfma_f32_16x16x32_bf16 v[16:19], v[182:185], v[206:209], v[16:19]
	v_mfma_f32_16x16x32_bf16 v[4:7], v[174:177], v[214:217], v[4:7]
	v_mfma_f32_16x16x32_bf16 v[0:3], v[182:185], v[214:217], v[0:3]
	s_setprio 0
	s_barrier
	s_add_i32 s33, 0, 0x18000
	s_add_i32 s50, 0, 0x1c000
	v_add_u32_e32 v166, s33, v137
	v_add_u32_e32 v182, s50, v137
	ds_read_b128 v[146:149], v166
	ds_read_b128 v[158:161], v166 offset:1024
	ds_read_b128 v[162:165], v166 offset:2048
	ds_read_b128 v[166:169], v166 offset:3072
	ds_read_b128 v[170:173], v182
	ds_read_b128 v[174:177], v182 offset:1024
	ds_read_b128 v[178:181], v182 offset:2048
	ds_read_b128 v[182:185], v182 offset:3072
	s_add_u32 s26, s54, 0x204000
	s_addc_u32 s27, s55, 0
	s_mov_b32 m0, s58
	ds_read_b128 v[186:189], v155 offset:32768
	ds_read_b128 v[190:193], v155 offset:33792
	ds_read_b128 v[194:197], v155 offset:34816
	ds_read_b128 v[198:201], v155 offset:35840
	ds_read_b128 v[202:205], v155 offset:36864
	ds_read_b128 v[206:209], v155 offset:37888
	ds_read_b128 v[210:213], v155 offset:38912
	ds_read_b128 v[214:217], v155 offset:39936
	global_load_lds_dwordx4 v128, s[26:27]
	s_mov_b32 m0, s59
	s_nop 0
	global_load_lds_dwordx4 v132, s[26:27]
	s_waitcnt vmcnt(8)
	s_waitcnt lgkmcnt(0)
	s_barrier
	s_setprio 1
	s_waitcnt lgkmcnt(0)
	v_mfma_f32_16x16x32_bf16 v[124:127], v[146:149], v[186:189], v[124:127]
	v_mfma_f32_16x16x32_bf16 v[120:123], v[162:165], v[186:189], v[120:123]
	v_mfma_f32_16x16x32_bf16 v[108:111], v[146:149], v[194:197], v[108:111]
	v_mfma_f32_16x16x32_bf16 v[104:107], v[162:165], v[194:197], v[104:107]
	v_mfma_f32_16x16x32_bf16 v[92:95], v[146:149], v[202:205], v[92:95]
	v_mfma_f32_16x16x32_bf16 v[88:91], v[162:165], v[202:205], v[88:91]
	v_mfma_f32_16x16x32_bf16 v[76:79], v[146:149], v[210:213], v[76:79]
	v_mfma_f32_16x16x32_bf16 v[72:75], v[162:165], v[210:213], v[72:75]
	v_mfma_f32_16x16x32_bf16 v[124:127], v[158:161], v[190:193], v[124:127]
	v_mfma_f32_16x16x32_bf16 v[120:123], v[166:169], v[190:193], v[120:123]
	v_mfma_f32_16x16x32_bf16 v[108:111], v[158:161], v[198:201], v[108:111]
	v_mfma_f32_16x16x32_bf16 v[104:107], v[166:169], v[198:201], v[104:107]
	v_mfma_f32_16x16x32_bf16 v[92:95], v[158:161], v[206:209], v[92:95]
	v_mfma_f32_16x16x32_bf16 v[88:91], v[166:169], v[206:209], v[88:91]
	v_mfma_f32_16x16x32_bf16 v[76:79], v[158:161], v[214:217], v[76:79]
	v_mfma_f32_16x16x32_bf16 v[72:75], v[166:169], v[214:217], v[72:75]
	s_setprio 0
	s_setprio 1
	v_mfma_f32_16x16x32_bf16 v[116:119], v[170:173], v[186:189], v[116:119]
	v_mfma_f32_16x16x32_bf16 v[112:115], v[178:181], v[186:189], v[112:115]
	v_mfma_f32_16x16x32_bf16 v[100:103], v[170:173], v[194:197], v[100:103]
	v_mfma_f32_16x16x32_bf16 v[96:99], v[178:181], v[194:197], v[96:99]
	v_mfma_f32_16x16x32_bf16 v[84:87], v[170:173], v[202:205], v[84:87]
	v_mfma_f32_16x16x32_bf16 v[80:83], v[178:181], v[202:205], v[80:83]
	v_mfma_f32_16x16x32_bf16 v[68:71], v[170:173], v[210:213], v[68:71]
	v_mfma_f32_16x16x32_bf16 v[64:67], v[178:181], v[210:213], v[64:67]
	v_mfma_f32_16x16x32_bf16 v[116:119], v[174:177], v[190:193], v[116:119]
	v_mfma_f32_16x16x32_bf16 v[112:115], v[182:185], v[190:193], v[112:115]
	v_mfma_f32_16x16x32_bf16 v[100:103], v[174:177], v[198:201], v[100:103]
	v_mfma_f32_16x16x32_bf16 v[96:99], v[182:185], v[198:201], v[96:99]
	v_mfma_f32_16x16x32_bf16 v[84:87], v[174:177], v[206:209], v[84:87]
	v_mfma_f32_16x16x32_bf16 v[80:83], v[182:185], v[206:209], v[80:83]
	v_mfma_f32_16x16x32_bf16 v[68:71], v[174:177], v[214:217], v[68:71]
	v_mfma_f32_16x16x32_bf16 v[64:67], v[182:185], v[214:217], v[64:67]
	s_setprio 0
	s_barrier
; #define PG8_STAGE(bufoff, gbase, voff) do { _Pragma("unroll") for (int _i = 0; _i < 2; ++_i) \
;         __builtin_amdgcn_global_load_lds((const unsigned*)((const char*)(gbase) + (voff)[_i]), (PG8_LAS unsigned*)(lds + (bufoff) + ldsw + _i * 8192), 16, 0, 0); } while (0)
; #define PG8_LDA(dst, b, h) do { _Pragma("unroll") for (int m = 0; m < 4; ++m) _Pragma("unroll") for (int k = 0; k < 2; ++k) dst[m][k] = *(const PG8_LAS bf16x8*)(lds + PG8_SA(b, h) + aoff + m * 2048 + k * 1024); } while (0)
; #define PG8_MMA(ai, bj, At, Bt) do { __builtin_amdgcn_s_setprio(1); _Pragma("unroll") for (int m = 0; m < 4; ++m) _Pragma("unroll") for (int n = 0; n < 2; ++n) _Pragma("unroll") for (int k = 0; k < 2; ++k) \
;         acc[ai][bj][m][n] = __builtin_amdgcn_mfma_f32_16x16x32_bf16(Bt[n][k], At[m][k], acc[ai][bj][m][n], 0, 0, 0); __builtin_amdgcn_s_setprio(0); } while (0)
; #define PG8_WAIT_V(n) asm volatile("s_waitcnt vmcnt(" #n ")" ::: "memory")
; #define PG8_WAIT_L(n) asm volatile("s_waitcnt lgkmcnt(" #n ")" ::: "memory")
; #define PG8_BAR __builtin_amdgcn_s_barrier()
; #define PG8_SCHED __builtin_amdgcn_sched_barrier(0)
; template <class Epi, class Sched, bool ALIGN_EPI = false, bool SP2 = false>
; __device__ __forceinline__ void gemm_phase(PG8_LAS unsigned char* lds, const Gemm g, const Sched& S, const Epi& E, int tid_in) {
;     ...
;         for (int t = 0; t < nt; t += 2) {
;     ...
;             PG8_WAIT_V(8); PG8_WAIT_L(0); PG8_BAR; PG8_MMA(0, 0, At, B0); PG8_MMA(0, 1, At, B1); PG8_BAR; PG8_SCHED;
;             PG8_LDA(At, 1, 1); PG8_STAGE(PG8_SB(1, 0), b3, voffB); PG8_STAGE(PG8_SB(1, 1), b3 + hstepB, voffB); PG8_STAGE(PG8_SA(1, 0), a3, voffA);
;             PG8_WAIT_V(8); PG8_WAIT_L(0); PG8_BAR; PG8_MMA(1, 0, At, B0); PG8_MMA(1, 1, At, B1); PG8_BAR; PG8_SCHED;
	s_add_i32 s26, s33, s56
	s_add_i32 m0, s26, 0xffffff80
	ds_read_b128 v[186:189], v155 offset:49152
	ds_read_b128 v[190:193], v155 offset:50176
	ds_read_b128 v[194:197], v155 offset:51200
	ds_read_b128 v[198:201], v155 offset:52224
	ds_read_b128 v[202:205], v155 offset:53248
	ds_read_b128 v[206:209], v155 offset:54272
	ds_read_b128 v[210:213], v155 offset:55296
	ds_read_b128 v[214:217], v155 offset:56320
	global_load_lds_dwordx4 v130, s[52:53] offset:128
	s_add_i32 m0, s26, 0x1f80
	s_add_u32 s26, s52, 0x80080
	s_addc_u32 s27, s53, 0
	s_add_i32 s33, s50, s56
	global_load_lds_dwordx4 v134, s[52:53] offset:128
	s_mov_b32 m0, s33
	s_nop 0
	global_load_lds_dwordx4 v130, s[26:27]
	s_add_i32 m0, s33, 0x2000
	s_nop 0
	global_load_lds_dwordx4 v134, s[26:27]
	s_add_i32 m0, s61, 0xffffff80
	s_nop 0
	global_load_lds_dwordx4 v128, s[54:55] offset:128
	s_add_i32 m0, s62, 0xffffff80
	s_nop 0
	global_load_lds_dwordx4 v132, s[54:55] offset:128
	s_waitcnt vmcnt(8)
	s_waitcnt lgkmcnt(0)
	s_barrier
	s_setprio 1
	s_waitcnt lgkmcnt(0)
	v_mfma_f32_16x16x32_bf16 v[60:63], v[146:149], v[186:189], v[60:63]
	v_mfma_f32_16x16x32_bf16 v[56:59], v[162:165], v[186:189], v[56:59]
	v_mfma_f32_16x16x32_bf16 v[44:47], v[146:149], v[194:197], v[44:47]
	v_mfma_f32_16x16x32_bf16 v[40:43], v[162:165], v[194:197], v[40:43]
	v_mfma_f32_16x16x32_bf16 v[28:31], v[146:149], v[202:205], v[28:31]
	v_mfma_f32_16x16x32_bf16 v[24:27], v[162:165], v[202:205], v[24:27]
	v_mfma_f32_16x16x32_bf16 v[12:15], v[146:149], v[210:213], v[12:15]
	v_mfma_f32_16x16x32_bf16 v[8:11], v[162:165], v[210:213], v[8:11]
	v_mfma_f32_16x16x32_bf16 v[60:63], v[158:161], v[190:193], v[60:63]
	v_mfma_f32_16x16x32_bf16 v[56:59], v[166:169], v[190:193], v[56:59]
	v_mfma_f32_16x16x32_bf16 v[44:47], v[158:161], v[198:201], v[44:47]
	v_mfma_f32_16x16x32_bf16 v[40:43], v[166:169], v[198:201], v[40:43]
	v_mfma_f32_16x16x32_bf16 v[28:31], v[158:161], v[206:209], v[28:31]
	v_mfma_f32_16x16x32_bf16 v[24:27], v[166:169], v[206:209], v[24:27]
	v_mfma_f32_16x16x32_bf16 v[12:15], v[158:161], v[214:217], v[12:15]
	v_mfma_f32_16x16x32_bf16 v[8:11], v[166:169], v[214:217], v[8:11]
	s_setprio 0
	s_setprio 1
	v_mfma_f32_16x16x32_bf16 v[52:55], v[170:173], v[186:189], v[52:55]
	v_mfma_f32_16x16x32_bf16 v[48:51], v[178:181], v[186:189], v[48:51]
	v_mfma_f32_16x16x32_bf16 v[36:39], v[170:173], v[194:197], v[36:39]
	v_mfma_f32_16x16x32_bf16 v[32:35], v[178:181], v[194:197], v[32:35]
	v_mfma_f32_16x16x32_bf16 v[20:23], v[170:173], v[202:205], v[20:23]
	v_mfma_f32_16x16x32_bf16 v[16:19], v[178:181], v[202:205], v[16:19]
	v_mfma_f32_16x16x32_bf16 v[4:7], v[170:173], v[210:213], v[4:7]
	v_mfma_f32_16x16x32_bf16 v[0:3], v[178:181], v[210:213], v[0:3]
	v_mfma_f32_16x16x32_bf16 v[52:55], v[174:177], v[190:193], v[52:55]
	v_mfma_f32_16x16x32_bf16 v[48:51], v[182:185], v[190:193], v[48:51]
	v_mfma_f32_16x16x32_bf16 v[36:39], v[174:177], v[198:201], v[36:39]
	v_mfma_f32_16x16x32_bf16 v[32:35], v[182:185], v[198:201], v[32:35]
	v_mfma_f32_16x16x32_bf16 v[20:23], v[174:177], v[206:209], v[20:23]
	v_mfma_f32_16x16x32_bf16 v[16:19], v[182:185], v[206:209], v[16:19]
	v_mfma_f32_16x16x32_bf16 v[4:7], v[174:177], v[214:217], v[4:7]
	v_mfma_f32_16x16x32_bf16 v[0:3], v[182:185], v[214:217], v[0:3]
	s_setprio 0
	s_barrier
	s_add_i32 s70, s70, 2
	s_add_u32 s68, s68, 0x100
	s_addc_u32 s69, s69, 0
	s_cmpk_gt_u32 s70, 0x7d
	s_mov_b64 s[50:51], s[10:11]
